# lgkmcnt(0) wait moved in front of the barrier in the light load segments only (phases 2,3,6,7), so those MFMA segments start with no wait instruction
# speedup vs baseline: 1.0054x; 1.0054x over previous
.Lrot_enter_10:
	s_add_u32 s7, s46, 0xffea0080
	s_addc_u32 s78, s47, -1
	s_add_i32 s87, 0, 0x10000
	v_add_u32_e32 v132, s87, v135
	ds_read_b128 v[138:141], v132
	ds_read_b128 v[142:145], v132 offset:1024
	ds_read_b128 v[148:151], v132 offset:2048
	ds_read_b128 v[152:155], v132 offset:3072
	s_cmpk_eq_i32 s6, 0x54
	s_cselect_b32 s79, s43, s78
	s_cselect_b32 s78, s42, s7
	s_cselect_b32 s89, s45, s9
	s_cselect_b32 s88, s44, s8
	v_lshl_add_u64 v[132:133], s[46:47], 0, v[130:131]
	s_add_i32 m0, s54, 0xc000
	ds_read_b128 v[156:159], v136
	ds_read_b128 v[160:163], v136 offset:1024
	ds_read_b128 v[164:167], v136 offset:2048
	ds_read_b128 v[168:171], v136 offset:3072
	ds_read_b128 v[172:175], v136 offset:4096
	ds_read_b128 v[176:179], v136 offset:5120
	ds_read_b128 v[180:183], v136 offset:6144
	ds_read_b128 v[184:187], v136 offset:7168
	global_load_lds_dwordx4 v[132:133], off
	v_lshl_add_u64 v[132:133], v[132:133], 0, s[26:27]
	s_add_i32 m0, s54, 0xe000
	s_nop 0
	global_load_lds_dwordx4 v[132:133], off
	s_waitcnt lgkmcnt(8)
	s_barrier
	s_waitcnt lgkmcnt(0)
	v_mfma_f32_16x16x32_bf16 v[126:129], v[138:141], v[156:159], v[126:129]
	v_mfma_f32_16x16x32_bf16 v[122:125], v[148:151], v[156:159], v[122:125]
	v_mfma_f32_16x16x32_bf16 v[118:121], v[138:141], v[164:167], v[118:121]
	v_mfma_f32_16x16x32_bf16 v[110:113], v[148:151], v[164:167], v[110:113]
	v_mfma_f32_16x16x32_bf16 v[102:105], v[138:141], v[172:175], v[102:105]
	v_mfma_f32_16x16x32_bf16 v[94:97], v[148:151], v[172:175], v[94:97]
	v_mfma_f32_16x16x32_bf16 v[86:89], v[138:141], v[180:183], v[86:89]
	v_mfma_f32_16x16x32_bf16 v[78:81], v[148:151], v[180:183], v[78:81]
	v_mfma_f32_16x16x32_bf16 v[126:129], v[142:145], v[160:163], v[126:129]
	v_mfma_f32_16x16x32_bf16 v[122:125], v[152:155], v[160:163], v[122:125]
	v_mfma_f32_16x16x32_bf16 v[118:121], v[142:145], v[168:171], v[118:121]
	v_mfma_f32_16x16x32_bf16 v[110:113], v[152:155], v[168:171], v[110:113]
	v_mfma_f32_16x16x32_bf16 v[102:105], v[142:145], v[176:179], v[102:105]
	v_mfma_f32_16x16x32_bf16 v[94:97], v[152:155], v[176:179], v[94:97]
	v_mfma_f32_16x16x32_bf16 v[86:89], v[142:145], v[184:187], v[86:89]
	v_mfma_f32_16x16x32_bf16 v[78:81], v[152:155], v[184:187], v[78:81]
	s_barrier
	s_add_i32 s7, 0, 0x14000
	v_add_u32_e32 v132, s7, v135
	s_add_i32 s87, s87, s53
	ds_read_b128 v[188:191], v132
	ds_read_b128 v[192:195], v132 offset:1024
	ds_read_b128 v[196:199], v132 offset:2048
	ds_read_b128 v[200:203], v132 offset:3072
	v_lshl_add_u64 v[132:133], s[88:89], 0, v[0:1]
	s_mov_b32 m0, s87
	v_lshl_add_u64 v[204:205], v[132:133], 0, s[26:27]
	global_load_lds_dwordx4 v[132:133], off
	s_add_i32 m0, s87, 0x2000
	s_nop 0
	global_load_lds_dwordx4 v[204:205], off
	s_waitcnt lgkmcnt(0)
	s_barrier
	v_mfma_f32_16x16x32_bf16 v[114:117], v[188:191], v[156:159], v[114:117]
	v_mfma_f32_16x16x32_bf16 v[106:109], v[196:199], v[156:159], v[106:109]
	v_mfma_f32_16x16x32_bf16 v[98:101], v[188:191], v[164:167], v[98:101]
	v_mfma_f32_16x16x32_bf16 v[90:93], v[196:199], v[164:167], v[90:93]
	v_mfma_f32_16x16x32_bf16 v[82:85], v[188:191], v[172:175], v[82:85]
	v_mfma_f32_16x16x32_bf16 v[74:77], v[196:199], v[172:175], v[74:77]
	v_mfma_f32_16x16x32_bf16 v[70:73], v[188:191], v[180:183], v[70:73]
	v_mfma_f32_16x16x32_bf16 v[66:69], v[196:199], v[180:183], v[66:69]
	v_mfma_f32_16x16x32_bf16 v[114:117], v[192:195], v[160:163], v[114:117]
	v_mfma_f32_16x16x32_bf16 v[106:109], v[200:203], v[160:163], v[106:109]
	v_mfma_f32_16x16x32_bf16 v[98:101], v[192:195], v[168:171], v[98:101]
	v_mfma_f32_16x16x32_bf16 v[90:93], v[200:203], v[168:171], v[90:93]
	v_mfma_f32_16x16x32_bf16 v[82:85], v[192:195], v[176:179], v[82:85]
	v_mfma_f32_16x16x32_bf16 v[74:77], v[200:203], v[176:179], v[74:77]
	v_mfma_f32_16x16x32_bf16 v[70:73], v[192:195], v[184:187], v[70:73]
	v_mfma_f32_16x16x32_bf16 v[66:69], v[200:203], v[184:187], v[66:69]
	s_barrier
	s_mov_b32 m0, s54
	v_lshl_add_u64 v[204:205], s[78:79], 0, v[0:1]
	ds_read_b128 v[156:159], v136 offset:16384
	ds_read_b128 v[160:163], v136 offset:17408
	ds_read_b128 v[164:167], v136 offset:18432
	ds_read_b128 v[168:171], v136 offset:19456
	ds_read_b128 v[172:175], v136 offset:20480
	ds_read_b128 v[176:179], v136 offset:21504
	ds_read_b128 v[180:183], v136 offset:22528
	ds_read_b128 v[184:187], v136 offset:23552
	global_load_lds_dwordx4 v[204:205], off
	v_lshl_add_u64 v[206:207], v[204:205], 0, s[26:27]
	s_mov_b32 m0, s55
	s_nop 0
	global_load_lds_dwordx4 v[206:207], off
	s_waitcnt lgkmcnt(0)
	s_barrier
	v_mfma_f32_16x16x32_bf16 v[62:65], v[138:141], v[156:159], v[62:65]
	v_mfma_f32_16x16x32_bf16 v[58:61], v[148:151], v[156:159], v[58:61]
	v_mfma_f32_16x16x32_bf16 v[54:57], v[138:141], v[164:167], v[54:57]
	v_mfma_f32_16x16x32_bf16 v[46:49], v[148:151], v[164:167], v[46:49]
	v_mfma_f32_16x16x32_bf16 v[38:41], v[138:141], v[172:175], v[38:41]
	v_mfma_f32_16x16x32_bf16 v[30:33], v[148:151], v[172:175], v[30:33]
	v_mfma_f32_16x16x32_bf16 v[22:25], v[138:141], v[180:183], v[22:25]
	v_mfma_f32_16x16x32_bf16 v[14:17], v[148:151], v[180:183], v[14:17]
	v_mfma_f32_16x16x32_bf16 v[62:65], v[142:145], v[160:163], v[62:65]
	v_mfma_f32_16x16x32_bf16 v[58:61], v[152:155], v[160:163], v[58:61]
	v_mfma_f32_16x16x32_bf16 v[54:57], v[142:145], v[168:171], v[54:57]
	v_mfma_f32_16x16x32_bf16 v[46:49], v[152:155], v[168:171], v[46:49]
	v_mfma_f32_16x16x32_bf16 v[38:41], v[142:145], v[176:179], v[38:41]
	v_mfma_f32_16x16x32_bf16 v[30:33], v[152:155], v[176:179], v[30:33]
	v_mfma_f32_16x16x32_bf16 v[22:25], v[142:145], v[184:187], v[22:25]
	v_mfma_f32_16x16x32_bf16 v[14:17], v[152:155], v[184:187], v[14:17]
	s_barrier
	s_add_i32 s7, s7, s53
	v_lshl_add_u64 v[138:139], v[132:133], 0, s[28:29]
	s_mov_b32 m0, s7
	s_nop 0
	global_load_lds_dwordx4 v[138:139], off
	v_lshl_add_u64 v[138:139], v[132:133], 0, s[30:31]
	s_add_i32 m0, s7, 0x2000
	s_nop 0
	global_load_lds_dwordx4 v[138:139], off
	v_lshl_add_u64 v[230:231], v[204:205], 0, s[28:29]
	s_mov_b32 m0, s56
	s_nop 0
	global_load_lds_dwordx4 v[230:231], off
	v_lshl_add_u64 v[230:231], v[204:205], 0, s[30:31]
	s_mov_b32 m0, s57
	s_nop 0
	global_load_lds_dwordx4 v[230:231], off
	s_waitcnt vmcnt(8)
	s_barrier
	v_mfma_f32_16x16x32_bf16 v[50:53], v[188:191], v[156:159], v[50:53]
	v_mfma_f32_16x16x32_bf16 v[42:45], v[196:199], v[156:159], v[42:45]
	v_mfma_f32_16x16x32_bf16 v[34:37], v[188:191], v[164:167], v[34:37]
	v_mfma_f32_16x16x32_bf16 v[26:29], v[196:199], v[164:167], v[26:29]
	v_mfma_f32_16x16x32_bf16 v[18:21], v[188:191], v[172:175], v[18:21]
	v_mfma_f32_16x16x32_bf16 v[10:13], v[196:199], v[172:175], v[10:13]
	v_mfma_f32_16x16x32_bf16 v[6:9], v[188:191], v[180:183], v[6:9]
	v_mfma_f32_16x16x32_bf16 v[2:5], v[196:199], v[180:183], v[2:5]
	v_mfma_f32_16x16x32_bf16 v[50:53], v[192:195], v[160:163], v[50:53]
	v_mfma_f32_16x16x32_bf16 v[42:45], v[200:203], v[160:163], v[42:45]
	v_mfma_f32_16x16x32_bf16 v[34:37], v[192:195], v[168:171], v[34:37]
	v_mfma_f32_16x16x32_bf16 v[26:29], v[200:203], v[168:171], v[26:29]
	v_mfma_f32_16x16x32_bf16 v[18:21], v[192:195], v[176:179], v[18:21]
	v_mfma_f32_16x16x32_bf16 v[10:13], v[200:203], v[176:179], v[10:13]
	v_mfma_f32_16x16x32_bf16 v[6:9], v[192:195], v[184:187], v[6:9]
	v_mfma_f32_16x16x32_bf16 v[2:5], v[200:203], v[184:187], v[2:5]
	s_barrier
	s_add_i32 s7, 0, 0x18000
	v_add_u32_e32 v137, s7, v135
	ds_read_b128 v[138:141], v137
	ds_read_b128 v[142:145], v137 offset:1024
	ds_read_b128 v[148:151], v137 offset:2048
	ds_read_b128 v[152:155], v137 offset:3072
	ds_read_b128 v[156:159], v136 offset:32768
	ds_read_b128 v[160:163], v136 offset:33792
	ds_read_b128 v[164:167], v136 offset:34816
	ds_read_b128 v[168:171], v136 offset:35840
	ds_read_b128 v[172:175], v136 offset:36864
	ds_read_b128 v[176:179], v136 offset:37888
	ds_read_b128 v[180:183], v136 offset:38912
	ds_read_b128 v[184:187], v136 offset:39936
	s_waitcnt lgkmcnt(8)
	s_barrier
	s_waitcnt lgkmcnt(0)
	v_mfma_f32_16x16x32_bf16 v[126:129], v[138:141], v[156:159], v[126:129]
	v_mfma_f32_16x16x32_bf16 v[122:125], v[148:151], v[156:159], v[122:125]
	v_mfma_f32_16x16x32_bf16 v[118:121], v[138:141], v[164:167], v[118:121]
	v_mfma_f32_16x16x32_bf16 v[110:113], v[148:151], v[164:167], v[110:113]
	v_mfma_f32_16x16x32_bf16 v[102:105], v[138:141], v[172:175], v[102:105]
	v_mfma_f32_16x16x32_bf16 v[94:97], v[148:151], v[172:175], v[94:97]
	v_mfma_f32_16x16x32_bf16 v[86:89], v[138:141], v[180:183], v[86:89]
	v_mfma_f32_16x16x32_bf16 v[78:81], v[148:151], v[180:183], v[78:81]
	v_mfma_f32_16x16x32_bf16 v[126:129], v[142:145], v[160:163], v[126:129]
	v_mfma_f32_16x16x32_bf16 v[122:125], v[152:155], v[160:163], v[122:125]
	v_mfma_f32_16x16x32_bf16 v[118:121], v[142:145], v[168:171], v[118:121]
	v_mfma_f32_16x16x32_bf16 v[110:113], v[152:155], v[168:171], v[110:113]
	v_mfma_f32_16x16x32_bf16 v[102:105], v[142:145], v[176:179], v[102:105]
	v_mfma_f32_16x16x32_bf16 v[94:97], v[152:155], v[176:179], v[94:97]
	v_mfma_f32_16x16x32_bf16 v[86:89], v[142:145], v[184:187], v[86:89]
	v_mfma_f32_16x16x32_bf16 v[78:81], v[152:155], v[184:187], v[78:81]
	s_barrier
	s_add_i32 s78, 0, 0x1c000
	s_add_i32 s7, s7, s53
	v_add_u32_e32 v137, s78, v135
	v_lshl_add_u64 v[206:207], v[132:133], 0, s[34:35]
	s_mov_b32 m0, s7
	ds_read_b128 v[188:191], v137
	ds_read_b128 v[192:195], v137 offset:1024
	ds_read_b128 v[196:199], v137 offset:2048
	ds_read_b128 v[200:203], v137 offset:3072
	global_load_lds_dwordx4 v[206:207], off
	v_lshl_add_u64 v[206:207], v[132:133], 0, s[36:37]
	s_add_i32 m0, s7, 0x2000
	s_nop 0
	global_load_lds_dwordx4 v[206:207], off
	s_waitcnt lgkmcnt(0)
	s_barrier
	v_mfma_f32_16x16x32_bf16 v[114:117], v[188:191], v[156:159], v[114:117]
	v_mfma_f32_16x16x32_bf16 v[106:109], v[196:199], v[156:159], v[106:109]
	v_mfma_f32_16x16x32_bf16 v[98:101], v[188:191], v[164:167], v[98:101]
	v_mfma_f32_16x16x32_bf16 v[90:93], v[196:199], v[164:167], v[90:93]
	v_mfma_f32_16x16x32_bf16 v[82:85], v[188:191], v[172:175], v[82:85]
	v_mfma_f32_16x16x32_bf16 v[74:77], v[196:199], v[172:175], v[74:77]
	v_mfma_f32_16x16x32_bf16 v[70:73], v[188:191], v[180:183], v[70:73]
	v_mfma_f32_16x16x32_bf16 v[66:69], v[196:199], v[180:183], v[66:69]
	v_mfma_f32_16x16x32_bf16 v[114:117], v[192:195], v[160:163], v[114:117]
	v_mfma_f32_16x16x32_bf16 v[106:109], v[200:203], v[160:163], v[106:109]
	v_mfma_f32_16x16x32_bf16 v[98:101], v[192:195], v[168:171], v[98:101]
	v_mfma_f32_16x16x32_bf16 v[90:93], v[200:203], v[168:171], v[90:93]
	v_mfma_f32_16x16x32_bf16 v[82:85], v[192:195], v[176:179], v[82:85]
	v_mfma_f32_16x16x32_bf16 v[74:77], v[200:203], v[176:179], v[74:77]
	v_mfma_f32_16x16x32_bf16 v[70:73], v[192:195], v[184:187], v[70:73]
	v_mfma_f32_16x16x32_bf16 v[66:69], v[200:203], v[184:187], v[66:69]
	s_barrier
	s_mov_b32 m0, s62
	v_lshl_add_u64 v[206:207], v[204:205], 0, s[34:35]
	ds_read_b128 v[156:159], v136 offset:49152
	ds_read_b128 v[160:163], v136 offset:50176
	ds_read_b128 v[164:167], v136 offset:51200
	ds_read_b128 v[168:171], v136 offset:52224
	ds_read_b128 v[172:175], v136 offset:53248
	ds_read_b128 v[176:179], v136 offset:54272
	ds_read_b128 v[180:183], v136 offset:55296
	ds_read_b128 v[184:187], v136 offset:56320
	global_load_lds_dwordx4 v[206:207], off
	v_lshl_add_u64 v[204:205], v[204:205], 0, s[36:37]
	s_mov_b32 m0, s63
	s_nop 0
	global_load_lds_dwordx4 v[204:205], off
	s_waitcnt lgkmcnt(0)
	s_barrier
	v_mfma_f32_16x16x32_bf16 v[62:65], v[138:141], v[156:159], v[62:65]
	v_mfma_f32_16x16x32_bf16 v[58:61], v[148:151], v[156:159], v[58:61]
	v_mfma_f32_16x16x32_bf16 v[54:57], v[138:141], v[164:167], v[54:57]
	v_mfma_f32_16x16x32_bf16 v[46:49], v[148:151], v[164:167], v[46:49]
	v_mfma_f32_16x16x32_bf16 v[38:41], v[138:141], v[172:175], v[38:41]
	v_mfma_f32_16x16x32_bf16 v[30:33], v[148:151], v[172:175], v[30:33]
	v_mfma_f32_16x16x32_bf16 v[22:25], v[138:141], v[180:183], v[22:25]
	v_mfma_f32_16x16x32_bf16 v[14:17], v[148:151], v[180:183], v[14:17]
	v_mfma_f32_16x16x32_bf16 v[62:65], v[142:145], v[160:163], v[62:65]
	v_mfma_f32_16x16x32_bf16 v[58:61], v[152:155], v[160:163], v[58:61]
	v_mfma_f32_16x16x32_bf16 v[54:57], v[142:145], v[168:171], v[54:57]
	v_mfma_f32_16x16x32_bf16 v[46:49], v[152:155], v[168:171], v[46:49]
	v_mfma_f32_16x16x32_bf16 v[38:41], v[142:145], v[176:179], v[38:41]
	v_mfma_f32_16x16x32_bf16 v[30:33], v[152:155], v[176:179], v[30:33]
	v_mfma_f32_16x16x32_bf16 v[22:25], v[142:145], v[184:187], v[22:25]
	v_mfma_f32_16x16x32_bf16 v[14:17], v[152:155], v[184:187], v[14:17]
	s_barrier
	s_add_i32 s7, s78, s53
	v_lshl_add_u64 v[138:139], v[132:133], 0, s[18:19]
	s_mov_b32 m0, s7
	v_lshl_add_u64 v[132:133], v[132:133], 0, s[14:15]
	global_load_lds_dwordx4 v[138:139], off
	s_add_i32 m0, s7, 0x2000
	s_nop 0
	global_load_lds_dwordx4 v[132:133], off
	s_waitcnt vmcnt(6)
	s_add_i32 s6, s6, 2
	s_add_u32 s8, s8, 0x100
	s_addc_u32 s9, s9, 0
	s_add_u32 s46, s46, 0x100
	s_addc_u32 s47, s47, 0
	s_cmpk_gt_u32 s6, 0x55
	s_cbranch_scc0 .LBB0_37
	s_barrier
	v_mfma_f32_16x16x32_bf16 v[50:53], v[188:191], v[156:159], v[50:53]
	v_mfma_f32_16x16x32_bf16 v[42:45], v[196:199], v[156:159], v[42:45]
	v_mfma_f32_16x16x32_bf16 v[34:37], v[188:191], v[164:167], v[34:37]
	v_mfma_f32_16x16x32_bf16 v[26:29], v[196:199], v[164:167], v[26:29]
	v_mfma_f32_16x16x32_bf16 v[18:21], v[188:191], v[172:175], v[18:21]
	v_mfma_f32_16x16x32_bf16 v[10:13], v[196:199], v[172:175], v[10:13]
	v_mfma_f32_16x16x32_bf16 v[6:9], v[188:191], v[180:183], v[6:9]
	v_mfma_f32_16x16x32_bf16 v[2:5], v[196:199], v[180:183], v[2:5]
	v_mfma_f32_16x16x32_bf16 v[50:53], v[192:195], v[160:163], v[50:53]
	v_mfma_f32_16x16x32_bf16 v[42:45], v[200:203], v[160:163], v[42:45]
	v_mfma_f32_16x16x32_bf16 v[34:37], v[192:195], v[168:171], v[34:37]
	v_mfma_f32_16x16x32_bf16 v[26:29], v[200:203], v[168:171], v[26:29]
	v_mfma_f32_16x16x32_bf16 v[18:21], v[192:195], v[176:179], v[18:21]
	v_mfma_f32_16x16x32_bf16 v[10:13], v[200:203], v[176:179], v[10:13]
	v_mfma_f32_16x16x32_bf16 v[6:9], v[192:195], v[184:187], v[6:9]
	v_mfma_f32_16x16x32_bf16 v[2:5], v[200:203], v[184:187], v[2:5]
	s_barrier
	v_mov_b32_e32 v137, v134
	s_lshl_b32 s6, s86, 8
	v_ashrrev_i32_e32 v132, 2, v137
	s_or_b32 s6, s6, s59
	v_and_b32_e32 v132, -4, v132
	v_add_u32_e32 v132, s6, v132
	s_lshl_b32 s6, s85, 8
	s_add_i32 s6, s6, s58
	v_and_or_b32 v188, v137, 15, s6
	v_ashrrev_i32_e32 v189, 31, v188
	v_ashrrev_i32_e32 v133, 31, v132
	v_lshlrev_b64 v[206:207], 13, v[188:189]
	v_or_b32_e32 v156, 16, v188
	v_or_b32_e32 v172, 32, v188
	v_or_b32_e32 v188, 48, v188
	v_lshlrev_b64 v[132:133], 2, v[132:133]
	v_ashrrev_i32_e32 v157, 31, v156
	v_ashrrev_i32_e32 v173, 31, v172
	v_ashrrev_i32_e32 v189, 31, v188
	v_lshl_add_u64 v[204:205], s[4:5], 0, v[132:133]
	v_lshlrev_b64 v[208:209], 13, v[156:157]
	v_lshlrev_b64 v[210:211], 13, v[172:173]
	v_lshlrev_b64 v[212:213], 13, v[188:189]
	v_lshl_add_u64 v[152:153], v[204:205], 0, v[206:207]
	v_lshl_add_u64 v[168:169], v[204:205], 0, v[208:209]
	v_lshl_add_u64 v[184:185], v[204:205], 0, v[210:211]
	v_lshl_add_u64 v[200:201], v[204:205], 0, v[212:213]
	global_load_dwordx4 v[138:141], v[152:153], off
	global_load_dwordx4 v[142:145], v[152:153], off offset:64
	global_load_dwordx4 v[148:151], v[152:153], off offset:512
	s_nop 0
	global_load_dwordx4 v[152:155], v[152:153], off offset:576
	s_nop 0
	global_load_dwordx4 v[156:159], v[168:169], off
	global_load_dwordx4 v[160:163], v[168:169], off offset:64
	global_load_dwordx4 v[164:167], v[168:169], off offset:512
	s_nop 0
	global_load_dwordx4 v[168:171], v[168:169], off offset:576
	s_nop 0
	global_load_dwordx4 v[172:175], v[184:185], off
	global_load_dwordx4 v[176:179], v[184:185], off offset:64
	global_load_dwordx4 v[180:183], v[184:185], off offset:512
	s_nop 0
	global_load_dwordx4 v[184:187], v[184:185], off offset:576
	s_nop 0
	global_load_dwordx4 v[188:191], v[200:201], off
	global_load_dwordx4 v[192:195], v[200:201], off offset:64
	global_load_dwordx4 v[196:199], v[200:201], off offset:512
	s_nop 0
	global_load_dwordx4 v[200:203], v[200:201], off offset:576
	s_waitcnt vmcnt(0) lgkmcnt(0)
	v_pk_fma_f32 v[126:127], v[126:127], 0.5, v[138:139] op_sel_hi:[1,0,1]
	v_lshl_add_u64 v[138:139], s[4:5], 0, v[206:207]
	v_lshl_add_u64 v[138:139], v[138:139], 0, v[132:133]
	v_pk_fma_f32 v[116:117], v[116:117], 0.5, v[150:151] op_sel_hi:[1,0,1]
	v_pk_fma_f32 v[114:115], v[114:115], 0.5, v[148:149] op_sel_hi:[1,0,1]
	global_store_dwordx4 v[138:139], v[114:117], off offset:512
	v_pk_fma_f32 v[100:101], v[100:101], 0.5, v[166:167] op_sel_hi:[1,0,1]
	v_pk_fma_f32 v[98:99], v[98:99], 0.5, v[164:165] op_sel_hi:[1,0,1]
	v_lshl_add_u64 v[114:115], s[4:5], 0, v[208:209]
	v_lshl_add_u64 v[114:115], v[114:115], 0, v[132:133]
	global_store_dwordx4 v[114:115], v[98:101], off offset:512
	v_pk_fma_f32 v[84:85], v[84:85], 0.5, v[182:183] op_sel_hi:[1,0,1]
	v_pk_fma_f32 v[82:83], v[82:83], 0.5, v[180:181] op_sel_hi:[1,0,1]
	v_lshl_add_u64 v[98:99], s[4:5], 0, v[210:211]
	v_lshl_add_u64 v[98:99], v[98:99], 0, v[132:133]
	v_pk_fma_f32 v[108:109], v[108:109], 0.5, v[154:155] op_sel_hi:[1,0,1]
	v_pk_fma_f32 v[106:107], v[106:107], 0.5, v[152:153] op_sel_hi:[1,0,1]
	v_pk_fma_f32 v[92:93], v[92:93], 0.5, v[170:171] op_sel_hi:[1,0,1]
	v_pk_fma_f32 v[90:91], v[90:91], 0.5, v[168:169] op_sel_hi:[1,0,1]
	global_store_dwordx4 v[98:99], v[82:85], off offset:512
	v_pk_fma_f32 v[76:77], v[76:77], 0.5, v[186:187] op_sel_hi:[1,0,1]
	v_pk_fma_f32 v[74:75], v[74:75], 0.5, v[184:185] op_sel_hi:[1,0,1]
	v_lshl_add_u64 v[82:83], s[4:5], 0, v[212:213]
	global_store_dwordx4 v[138:139], v[106:109], off offset:576
	global_store_dwordx4 v[114:115], v[90:93], off offset:576
	global_store_dwordx4 v[98:99], v[74:77], off offset:576
	v_pk_fma_f32 v[108:109], v[120:121], 0.5, v[158:159] op_sel_hi:[1,0,1]
	v_pk_fma_f32 v[106:107], v[118:119], 0.5, v[156:157] op_sel_hi:[1,0,1]
	v_pk_fma_f32 v[92:93], v[104:105], 0.5, v[174:175] op_sel_hi:[1,0,1]
	v_pk_fma_f32 v[90:91], v[102:103], 0.5, v[172:173] op_sel_hi:[1,0,1]
	v_pk_fma_f32 v[76:77], v[88:89], 0.5, v[190:191] op_sel_hi:[1,0,1]
	v_pk_fma_f32 v[74:75], v[86:87], 0.5, v[188:189] op_sel_hi:[1,0,1]
	v_lshl_add_u64 v[82:83], v[82:83], 0, v[132:133]
	v_pk_fma_f32 v[128:129], v[128:129], 0.5, v[140:141] op_sel_hi:[1,0,1]
	v_pk_fma_f32 v[124:125], v[124:125], 0.5, v[144:145] op_sel_hi:[1,0,1]
	v_pk_fma_f32 v[122:123], v[122:123], 0.5, v[142:143] op_sel_hi:[1,0,1]
	global_store_dwordx4 v[114:115], v[106:109], off
	global_store_dwordx4 v[98:99], v[90:93], off
	global_store_dwordx4 v[82:83], v[74:77], off
	v_pk_fma_f32 v[108:109], v[112:113], 0.5, v[162:163] op_sel_hi:[1,0,1]
	v_pk_fma_f32 v[106:107], v[110:111], 0.5, v[160:161] op_sel_hi:[1,0,1]
	v_pk_fma_f32 v[92:93], v[96:97], 0.5, v[178:179] op_sel_hi:[1,0,1]
	v_pk_fma_f32 v[90:91], v[94:95], 0.5, v[176:177] op_sel_hi:[1,0,1]
	v_pk_fma_f32 v[76:77], v[80:81], 0.5, v[194:195] op_sel_hi:[1,0,1]
	v_pk_fma_f32 v[74:75], v[78:79], 0.5, v[192:193] op_sel_hi:[1,0,1]
	v_pk_fma_f32 v[72:73], v[72:73], 0.5, v[198:199] op_sel_hi:[1,0,1]
	v_pk_fma_f32 v[70:71], v[70:71], 0.5, v[196:197] op_sel_hi:[1,0,1]
	v_pk_fma_f32 v[68:69], v[68:69], 0.5, v[202:203] op_sel_hi:[1,0,1]
	v_pk_fma_f32 v[66:67], v[66:67], 0.5, v[200:201] op_sel_hi:[1,0,1]
	global_store_dwordx4 v[138:139], v[126:129], off
	global_store_dwordx4 v[138:139], v[122:125], off offset:64
	global_store_dwordx4 v[114:115], v[106:109], off offset:64
	global_store_dwordx4 v[98:99], v[90:93], off offset:64
	global_store_dwordx4 v[82:83], v[74:77], off offset:64
	global_store_dwordx4 v[82:83], v[70:73], off offset:512
	global_store_dwordx4 v[82:83], v[66:69], off offset:576
	s_mov_b64 s[6:7], 0x120000
	v_lshl_add_u64 v[140:141], v[206:207], 0, s[6:7]
	s_mov_b64 s[6:7], 0x140000
	v_lshl_add_u64 v[138:139], v[206:207], 0, s[0:1]
	v_lshl_add_u64 v[142:143], v[206:207], 0, s[6:7]
	v_lshl_add_u64 v[144:145], v[206:207], 0, s[28:29]
	v_lshl_add_u64 v[78:79], v[204:205], 0, v[138:139]
	v_lshl_add_u64 v[94:95], v[204:205], 0, v[140:141]
	v_lshl_add_u64 v[110:111], v[204:205], 0, v[142:143]
	v_lshl_add_u64 v[126:127], v[204:205], 0, v[144:145]
	global_load_dwordx4 v[66:69], v[78:79], off
	global_load_dwordx4 v[70:73], v[78:79], off offset:64
	global_load_dwordx4 v[74:77], v[78:79], off offset:512
	s_nop 0
	global_load_dwordx4 v[78:81], v[78:79], off offset:576
	s_nop 0
	global_load_dwordx4 v[82:85], v[94:95], off
	global_load_dwordx4 v[86:89], v[94:95], off offset:64
	global_load_dwordx4 v[90:93], v[94:95], off offset:512
	s_nop 0
	global_load_dwordx4 v[94:97], v[94:95], off offset:576
	s_nop 0
	global_load_dwordx4 v[98:101], v[110:111], off
	global_load_dwordx4 v[102:105], v[110:111], off offset:64
	global_load_dwordx4 v[106:109], v[110:111], off offset:512
	s_nop 0
	global_load_dwordx4 v[110:113], v[110:111], off offset:576
	s_nop 0
	global_load_dwordx4 v[114:117], v[126:127], off
	global_load_dwordx4 v[118:121], v[126:127], off offset:64
	global_load_dwordx4 v[122:125], v[126:127], off offset:512
	s_nop 0
	global_load_dwordx4 v[126:129], v[126:127], off offset:576
	s_waitcnt vmcnt(0) lgkmcnt(0)
	v_pk_fma_f32 v[62:63], v[62:63], 0.5, v[66:67] op_sel_hi:[1,0,1]
	v_lshl_add_u64 v[66:67], s[4:5], 0, v[138:139]
	v_lshl_add_u64 v[66:67], v[66:67], 0, v[132:133]
	v_pk_fma_f32 v[52:53], v[52:53], 0.5, v[76:77] op_sel_hi:[1,0,1]
	v_pk_fma_f32 v[50:51], v[50:51], 0.5, v[74:75] op_sel_hi:[1,0,1]
	global_store_dwordx4 v[66:67], v[50:53], off offset:512
	v_pk_fma_f32 v[36:37], v[36:37], 0.5, v[92:93] op_sel_hi:[1,0,1]
	v_pk_fma_f32 v[34:35], v[34:35], 0.5, v[90:91] op_sel_hi:[1,0,1]
	v_lshl_add_u64 v[50:51], s[4:5], 0, v[140:141]
	v_lshl_add_u64 v[50:51], v[50:51], 0, v[132:133]
	global_store_dwordx4 v[50:51], v[34:37], off offset:512
	v_pk_fma_f32 v[20:21], v[20:21], 0.5, v[108:109] op_sel_hi:[1,0,1]
	v_pk_fma_f32 v[18:19], v[18:19], 0.5, v[106:107] op_sel_hi:[1,0,1]
	v_lshl_add_u64 v[34:35], s[4:5], 0, v[142:143]
	v_lshl_add_u64 v[34:35], v[34:35], 0, v[132:133]
	v_pk_fma_f32 v[44:45], v[44:45], 0.5, v[80:81] op_sel_hi:[1,0,1]
	v_pk_fma_f32 v[42:43], v[42:43], 0.5, v[78:79] op_sel_hi:[1,0,1]
	v_pk_fma_f32 v[28:29], v[28:29], 0.5, v[96:97] op_sel_hi:[1,0,1]
	v_pk_fma_f32 v[26:27], v[26:27], 0.5, v[94:95] op_sel_hi:[1,0,1]
	global_store_dwordx4 v[34:35], v[18:21], off offset:512
	v_pk_fma_f32 v[12:13], v[12:13], 0.5, v[112:113] op_sel_hi:[1,0,1]
	v_pk_fma_f32 v[10:11], v[10:11], 0.5, v[110:111] op_sel_hi:[1,0,1]
	v_lshl_add_u64 v[18:19], s[4:5], 0, v[144:145]
	global_store_dwordx4 v[66:67], v[42:45], off offset:576
	global_store_dwordx4 v[50:51], v[26:29], off offset:576
	global_store_dwordx4 v[34:35], v[10:13], off offset:576
	v_pk_fma_f32 v[44:45], v[56:57], 0.5, v[84:85] op_sel_hi:[1,0,1]
	v_pk_fma_f32 v[42:43], v[54:55], 0.5, v[82:83] op_sel_hi:[1,0,1]
	v_pk_fma_f32 v[28:29], v[40:41], 0.5, v[100:101] op_sel_hi:[1,0,1]
	v_pk_fma_f32 v[26:27], v[38:39], 0.5, v[98:99] op_sel_hi:[1,0,1]
	v_pk_fma_f32 v[12:13], v[24:25], 0.5, v[116:117] op_sel_hi:[1,0,1]
	v_pk_fma_f32 v[10:11], v[22:23], 0.5, v[114:115] op_sel_hi:[1,0,1]
	v_lshl_add_u64 v[18:19], v[18:19], 0, v[132:133]
	v_pk_fma_f32 v[64:65], v[64:65], 0.5, v[68:69] op_sel_hi:[1,0,1]
	v_pk_fma_f32 v[60:61], v[60:61], 0.5, v[72:73] op_sel_hi:[1,0,1]
	v_pk_fma_f32 v[58:59], v[58:59], 0.5, v[70:71] op_sel_hi:[1,0,1]
	global_store_dwordx4 v[50:51], v[42:45], off
	global_store_dwordx4 v[34:35], v[26:29], off
	global_store_dwordx4 v[18:19], v[10:13], off
	v_pk_fma_f32 v[44:45], v[48:49], 0.5, v[88:89] op_sel_hi:[1,0,1]
	v_pk_fma_f32 v[42:43], v[46:47], 0.5, v[86:87] op_sel_hi:[1,0,1]
	v_pk_fma_f32 v[28:29], v[32:33], 0.5, v[104:105] op_sel_hi:[1,0,1]
	v_pk_fma_f32 v[26:27], v[30:31], 0.5, v[102:103] op_sel_hi:[1,0,1]
	v_pk_fma_f32 v[12:13], v[16:17], 0.5, v[120:121] op_sel_hi:[1,0,1]
	v_pk_fma_f32 v[10:11], v[14:15], 0.5, v[118:119] op_sel_hi:[1,0,1]
	v_pk_fma_f32 v[8:9], v[8:9], 0.5, v[124:125] op_sel_hi:[1,0,1]
	v_pk_fma_f32 v[6:7], v[6:7], 0.5, v[122:123] op_sel_hi:[1,0,1]
	v_pk_fma_f32 v[4:5], v[4:5], 0.5, v[128:129] op_sel_hi:[1,0,1]
	v_pk_fma_f32 v[2:3], v[2:3], 0.5, v[126:127] op_sel_hi:[1,0,1]
	global_store_dwordx4 v[66:67], v[62:65], off
	global_store_dwordx4 v[66:67], v[58:61], off offset:64
	global_store_dwordx4 v[50:51], v[42:45], off offset:64
	global_store_dwordx4 v[34:35], v[26:29], off offset:64
	global_store_dwordx4 v[18:19], v[10:13], off offset:64
	global_store_dwordx4 v[18:19], v[6:9], off offset:512
	global_store_dwordx4 v[18:19], v[2:5], off offset:576
	s_and_b64 vcc, exec, s[40:41]
	s_mov_b32 s85, s10
	s_mov_b32 s86, s11
	s_mov_b64 s[8:9], s[44:45]
	s_mov_b64 s[6:7], s[42:43]
	s_movk_i32 s89, 0x37ff
	s_mov_b32 s88, 0x16000
	s_cbranch_vccz .LBB0_30
	s_waitcnt vmcnt(0)
	s_cmpk_gt_u32 s48, 0xff
	s_cbranch_scc1 .LBB0_41
	s_barrier

.Lrot_enter_9:
	s_add_u32 s8, s6, 0x100
	s_addc_u32 s9, s7, 0
	s_add_i32 s90, 0, 0x10000
	v_add_u32_e32 v134, s90, v137
	ds_read_b128 v[140:143], v134
	ds_read_b128 v[148:151], v134 offset:1024
	ds_read_b128 v[152:155], v134 offset:2048
	ds_read_b128 v[156:159], v134 offset:3072
	s_cmp_eq_u32 s87, 28
	s_cselect_b32 s79, s43, s9
	s_cselect_b32 s78, s42, s8
	s_cselect_b32 s89, s47, s86
	s_cselect_b32 s88, s46, s41
	v_lshl_add_u64 v[134:135], s[6:7], 0, v[132:133]
	v_lshl_add_u64 v[144:145], v[134:135], 0, s[16:17]
	s_add_i32 m0, s49, 0xc000
	ds_read_b128 v[160:163], v138
	ds_read_b128 v[164:167], v138 offset:1024
	ds_read_b128 v[168:171], v138 offset:2048
	ds_read_b128 v[172:175], v138 offset:3072
	ds_read_b128 v[176:179], v138 offset:4096
	ds_read_b128 v[180:183], v138 offset:5120
	ds_read_b128 v[184:187], v138 offset:6144
	ds_read_b128 v[188:191], v138 offset:7168
	global_load_lds_dwordx4 v[144:145], off
	v_lshl_add_u64 v[134:135], v[134:135], 0, s[80:81]
	s_add_i32 m0, s49, 0xe000
	s_nop 0
	global_load_lds_dwordx4 v[134:135], off
	s_waitcnt lgkmcnt(8)
	s_barrier
	s_waitcnt lgkmcnt(0)
	v_mfma_f32_16x16x32_bf16 v[126:129], v[140:143], v[160:163], v[126:129]
	v_mfma_f32_16x16x32_bf16 v[118:121], v[152:155], v[160:163], v[118:121]
	v_mfma_f32_16x16x32_bf16 v[110:113], v[140:143], v[168:171], v[110:113]
	v_mfma_f32_16x16x32_bf16 v[102:105], v[152:155], v[168:171], v[102:105]
	v_mfma_f32_16x16x32_bf16 v[94:97], v[140:143], v[176:179], v[94:97]
	v_mfma_f32_16x16x32_bf16 v[86:89], v[152:155], v[176:179], v[86:89]
	v_mfma_f32_16x16x32_bf16 v[78:81], v[140:143], v[184:187], v[78:81]
	v_mfma_f32_16x16x32_bf16 v[70:73], v[152:155], v[184:187], v[70:73]
	v_mfma_f32_16x16x32_bf16 v[126:129], v[148:151], v[164:167], v[126:129]
	v_mfma_f32_16x16x32_bf16 v[118:121], v[156:159], v[164:167], v[118:121]
	v_mfma_f32_16x16x32_bf16 v[110:113], v[148:151], v[172:175], v[110:113]
	v_mfma_f32_16x16x32_bf16 v[102:105], v[156:159], v[172:175], v[102:105]
	v_mfma_f32_16x16x32_bf16 v[94:97], v[148:151], v[180:183], v[94:97]
	v_mfma_f32_16x16x32_bf16 v[86:89], v[156:159], v[180:183], v[86:89]
	v_mfma_f32_16x16x32_bf16 v[78:81], v[148:151], v[188:191], v[78:81]
	v_mfma_f32_16x16x32_bf16 v[70:73], v[156:159], v[188:191], v[70:73]
	s_barrier
	s_add_i32 s6, 0, 0x14000
	v_add_u32_e32 v134, s6, v137
	s_add_i32 s7, s90, s54
	ds_read_b128 v[192:195], v134
	ds_read_b128 v[196:199], v134 offset:1024
	ds_read_b128 v[200:203], v134 offset:2048
	ds_read_b128 v[204:207], v134 offset:3072
	v_lshl_add_u64 v[134:135], s[88:89], 0, v[0:1]
	s_mov_b32 m0, s7
	v_lshl_add_u64 v[144:145], v[134:135], 0, s[60:61]
	global_load_lds_dwordx4 v[134:135], off
	s_add_i32 m0, s7, 0x2000
	s_nop 0
	global_load_lds_dwordx4 v[144:145], off
	s_waitcnt lgkmcnt(0)
	s_barrier
	v_mfma_f32_16x16x32_bf16 v[122:125], v[192:195], v[160:163], v[122:125]
	v_mfma_f32_16x16x32_bf16 v[114:117], v[200:203], v[160:163], v[114:117]
	v_mfma_f32_16x16x32_bf16 v[106:109], v[192:195], v[168:171], v[106:109]
	v_mfma_f32_16x16x32_bf16 v[98:101], v[200:203], v[168:171], v[98:101]
	v_mfma_f32_16x16x32_bf16 v[90:93], v[192:195], v[176:179], v[90:93]
	v_mfma_f32_16x16x32_bf16 v[82:85], v[200:203], v[176:179], v[82:85]
	v_mfma_f32_16x16x32_bf16 v[74:77], v[192:195], v[184:187], v[74:77]
	v_mfma_f32_16x16x32_bf16 v[66:69], v[200:203], v[184:187], v[66:69]
	v_mfma_f32_16x16x32_bf16 v[122:125], v[196:199], v[164:167], v[122:125]
	v_mfma_f32_16x16x32_bf16 v[114:117], v[204:207], v[164:167], v[114:117]
	v_mfma_f32_16x16x32_bf16 v[106:109], v[196:199], v[172:175], v[106:109]
	v_mfma_f32_16x16x32_bf16 v[98:101], v[204:207], v[172:175], v[98:101]
	v_mfma_f32_16x16x32_bf16 v[90:93], v[196:199], v[180:183], v[90:93]
	v_mfma_f32_16x16x32_bf16 v[82:85], v[204:207], v[180:183], v[82:85]
	v_mfma_f32_16x16x32_bf16 v[74:77], v[196:199], v[188:191], v[74:77]
	v_mfma_f32_16x16x32_bf16 v[66:69], v[204:207], v[188:191], v[66:69]
	s_barrier
	s_mov_b32 m0, s49
	v_lshl_add_u64 v[144:145], s[78:79], 0, v[130:131]
	ds_read_b128 v[160:163], v138 offset:16384
	ds_read_b128 v[164:167], v138 offset:17408
	ds_read_b128 v[168:171], v138 offset:18432
	ds_read_b128 v[172:175], v138 offset:19456
	ds_read_b128 v[176:179], v138 offset:20480
	ds_read_b128 v[180:183], v138 offset:21504
	ds_read_b128 v[184:187], v138 offset:22528
	ds_read_b128 v[188:191], v138 offset:23552
	global_load_lds_dwordx4 v[144:145], off
	v_lshl_add_u64 v[208:209], v[144:145], 0, s[60:61]
	s_mov_b32 m0, s55
	s_nop 0
	global_load_lds_dwordx4 v[208:209], off
	s_waitcnt lgkmcnt(0)
	s_barrier
	v_mfma_f32_16x16x32_bf16 v[62:65], v[140:143], v[160:163], v[62:65]
	v_mfma_f32_16x16x32_bf16 v[54:57], v[152:155], v[160:163], v[54:57]
	v_mfma_f32_16x16x32_bf16 v[46:49], v[140:143], v[168:171], v[46:49]
	v_mfma_f32_16x16x32_bf16 v[38:41], v[152:155], v[168:171], v[38:41]
	v_mfma_f32_16x16x32_bf16 v[30:33], v[140:143], v[176:179], v[30:33]
	v_mfma_f32_16x16x32_bf16 v[22:25], v[152:155], v[176:179], v[22:25]
	v_mfma_f32_16x16x32_bf16 v[14:17], v[140:143], v[184:187], v[14:17]
	v_mfma_f32_16x16x32_bf16 v[6:9], v[152:155], v[184:187], v[6:9]
	v_mfma_f32_16x16x32_bf16 v[62:65], v[148:151], v[164:167], v[62:65]
	v_mfma_f32_16x16x32_bf16 v[54:57], v[156:159], v[164:167], v[54:57]
	v_mfma_f32_16x16x32_bf16 v[46:49], v[148:151], v[172:175], v[46:49]
	v_mfma_f32_16x16x32_bf16 v[38:41], v[156:159], v[172:175], v[38:41]
	v_mfma_f32_16x16x32_bf16 v[30:33], v[148:151], v[180:183], v[30:33]
	v_mfma_f32_16x16x32_bf16 v[22:25], v[156:159], v[180:183], v[22:25]
	v_mfma_f32_16x16x32_bf16 v[14:17], v[148:151], v[188:191], v[14:17]
	v_mfma_f32_16x16x32_bf16 v[6:9], v[156:159], v[188:191], v[6:9]
	s_barrier
	s_add_i32 s6, s6, s54
	v_lshl_add_u64 v[140:141], v[134:135], 0, s[20:21]
	s_mov_b32 m0, s6
	s_nop 0
	global_load_lds_dwordx4 v[140:141], off
	v_lshl_add_u64 v[140:141], v[134:135], 0, s[64:65]
	s_add_i32 m0, s6, 0x2000
	s_nop 0
	global_load_lds_dwordx4 v[140:141], off
	v_lshl_add_u64 v[230:231], v[144:145], 0, s[20:21]
	s_mov_b32 m0, s56
	s_nop 0
	global_load_lds_dwordx4 v[230:231], off
	v_lshl_add_u64 v[230:231], v[144:145], 0, s[64:65]
	s_mov_b32 m0, s57
	s_nop 0
	global_load_lds_dwordx4 v[230:231], off
	s_waitcnt vmcnt(8)
	s_barrier
	v_mfma_f32_16x16x32_bf16 v[58:61], v[192:195], v[160:163], v[58:61]
	v_mfma_f32_16x16x32_bf16 v[50:53], v[200:203], v[160:163], v[50:53]
	v_mfma_f32_16x16x32_bf16 v[42:45], v[192:195], v[168:171], v[42:45]
	v_mfma_f32_16x16x32_bf16 v[34:37], v[200:203], v[168:171], v[34:37]
	v_mfma_f32_16x16x32_bf16 v[26:29], v[192:195], v[176:179], v[26:29]
	v_mfma_f32_16x16x32_bf16 v[18:21], v[200:203], v[176:179], v[18:21]
	v_mfma_f32_16x16x32_bf16 v[10:13], v[192:195], v[184:187], v[10:13]
	v_mfma_f32_16x16x32_bf16 v[2:5], v[200:203], v[184:187], v[2:5]
	v_mfma_f32_16x16x32_bf16 v[58:61], v[196:199], v[164:167], v[58:61]
	v_mfma_f32_16x16x32_bf16 v[50:53], v[204:207], v[164:167], v[50:53]
	v_mfma_f32_16x16x32_bf16 v[42:45], v[196:199], v[172:175], v[42:45]
	v_mfma_f32_16x16x32_bf16 v[34:37], v[204:207], v[172:175], v[34:37]
	v_mfma_f32_16x16x32_bf16 v[26:29], v[196:199], v[180:183], v[26:29]
	v_mfma_f32_16x16x32_bf16 v[18:21], v[204:207], v[180:183], v[18:21]
	v_mfma_f32_16x16x32_bf16 v[10:13], v[196:199], v[188:191], v[10:13]
	v_mfma_f32_16x16x32_bf16 v[2:5], v[204:207], v[188:191], v[2:5]
	s_barrier
	s_add_i32 s6, 0, 0x18000
	v_add_u32_e32 v139, s6, v137
	ds_read_b128 v[140:143], v139
	ds_read_b128 v[148:151], v139 offset:1024
	ds_read_b128 v[152:155], v139 offset:2048
	ds_read_b128 v[156:159], v139 offset:3072
	ds_read_b128 v[160:163], v138 offset:32768
	ds_read_b128 v[164:167], v138 offset:33792
	ds_read_b128 v[168:171], v138 offset:34816
	ds_read_b128 v[172:175], v138 offset:35840
	ds_read_b128 v[176:179], v138 offset:36864
	ds_read_b128 v[180:183], v138 offset:37888
	ds_read_b128 v[184:187], v138 offset:38912
	ds_read_b128 v[188:191], v138 offset:39936
	s_waitcnt lgkmcnt(8)
	s_barrier
	s_waitcnt lgkmcnt(0)
	v_mfma_f32_16x16x32_bf16 v[126:129], v[140:143], v[160:163], v[126:129]
	v_mfma_f32_16x16x32_bf16 v[118:121], v[152:155], v[160:163], v[118:121]
	v_mfma_f32_16x16x32_bf16 v[110:113], v[140:143], v[168:171], v[110:113]
	v_mfma_f32_16x16x32_bf16 v[102:105], v[152:155], v[168:171], v[102:105]
	v_mfma_f32_16x16x32_bf16 v[94:97], v[140:143], v[176:179], v[94:97]
	v_mfma_f32_16x16x32_bf16 v[86:89], v[152:155], v[176:179], v[86:89]
	v_mfma_f32_16x16x32_bf16 v[78:81], v[140:143], v[184:187], v[78:81]
	v_mfma_f32_16x16x32_bf16 v[70:73], v[152:155], v[184:187], v[70:73]
	v_mfma_f32_16x16x32_bf16 v[126:129], v[148:151], v[164:167], v[126:129]
	v_mfma_f32_16x16x32_bf16 v[118:121], v[156:159], v[164:167], v[118:121]
	v_mfma_f32_16x16x32_bf16 v[110:113], v[148:151], v[172:175], v[110:113]
	v_mfma_f32_16x16x32_bf16 v[102:105], v[156:159], v[172:175], v[102:105]
	v_mfma_f32_16x16x32_bf16 v[94:97], v[148:151], v[180:183], v[94:97]
	v_mfma_f32_16x16x32_bf16 v[86:89], v[156:159], v[180:183], v[86:89]
	v_mfma_f32_16x16x32_bf16 v[78:81], v[148:151], v[188:191], v[78:81]
	v_mfma_f32_16x16x32_bf16 v[70:73], v[156:159], v[188:191], v[70:73]
	s_barrier
	s_add_i32 s7, 0, 0x1c000
	s_add_i32 s6, s6, s54
	v_add_u32_e32 v139, s7, v137
	v_lshl_add_u64 v[208:209], v[134:135], 0, s[34:35]
	s_mov_b32 m0, s6
	ds_read_b128 v[192:195], v139
	ds_read_b128 v[196:199], v139 offset:1024
	ds_read_b128 v[200:203], v139 offset:2048
	ds_read_b128 v[204:207], v139 offset:3072
	global_load_lds_dwordx4 v[208:209], off
	v_lshl_add_u64 v[208:209], v[134:135], 0, s[66:67]
	s_add_i32 m0, s6, 0x2000
	s_nop 0
	global_load_lds_dwordx4 v[208:209], off
	s_waitcnt lgkmcnt(0)
	s_barrier
	v_mfma_f32_16x16x32_bf16 v[122:125], v[192:195], v[160:163], v[122:125]
	v_mfma_f32_16x16x32_bf16 v[114:117], v[200:203], v[160:163], v[114:117]
	v_mfma_f32_16x16x32_bf16 v[106:109], v[192:195], v[168:171], v[106:109]
	v_mfma_f32_16x16x32_bf16 v[98:101], v[200:203], v[168:171], v[98:101]
	v_mfma_f32_16x16x32_bf16 v[90:93], v[192:195], v[176:179], v[90:93]
	v_mfma_f32_16x16x32_bf16 v[82:85], v[200:203], v[176:179], v[82:85]
	v_mfma_f32_16x16x32_bf16 v[74:77], v[192:195], v[184:187], v[74:77]
	v_mfma_f32_16x16x32_bf16 v[66:69], v[200:203], v[184:187], v[66:69]
	v_mfma_f32_16x16x32_bf16 v[122:125], v[196:199], v[164:167], v[122:125]
	v_mfma_f32_16x16x32_bf16 v[114:117], v[204:207], v[164:167], v[114:117]
	v_mfma_f32_16x16x32_bf16 v[106:109], v[196:199], v[172:175], v[106:109]
	v_mfma_f32_16x16x32_bf16 v[98:101], v[204:207], v[172:175], v[98:101]
	v_mfma_f32_16x16x32_bf16 v[90:93], v[196:199], v[180:183], v[90:93]
	v_mfma_f32_16x16x32_bf16 v[82:85], v[204:207], v[180:183], v[82:85]
	v_mfma_f32_16x16x32_bf16 v[74:77], v[196:199], v[188:191], v[74:77]
	v_mfma_f32_16x16x32_bf16 v[66:69], v[204:207], v[188:191], v[66:69]
	s_barrier
	s_mov_b32 m0, s59
	v_lshl_add_u64 v[208:209], v[144:145], 0, s[34:35]
	ds_read_b128 v[160:163], v138 offset:49152
	ds_read_b128 v[164:167], v138 offset:50176
	ds_read_b128 v[168:171], v138 offset:51200
	ds_read_b128 v[172:175], v138 offset:52224
	ds_read_b128 v[176:179], v138 offset:53248
	ds_read_b128 v[180:183], v138 offset:54272
	ds_read_b128 v[184:187], v138 offset:55296
	ds_read_b128 v[188:191], v138 offset:56320
	global_load_lds_dwordx4 v[208:209], off
	v_lshl_add_u64 v[144:145], v[144:145], 0, s[66:67]
	s_mov_b32 m0, s62
	s_nop 0
	global_load_lds_dwordx4 v[144:145], off
	s_waitcnt lgkmcnt(0)
	s_barrier
	v_mfma_f32_16x16x32_bf16 v[62:65], v[140:143], v[160:163], v[62:65]
	v_mfma_f32_16x16x32_bf16 v[54:57], v[152:155], v[160:163], v[54:57]
	v_mfma_f32_16x16x32_bf16 v[46:49], v[140:143], v[168:171], v[46:49]
	v_mfma_f32_16x16x32_bf16 v[38:41], v[152:155], v[168:171], v[38:41]
	v_mfma_f32_16x16x32_bf16 v[30:33], v[140:143], v[176:179], v[30:33]
	v_mfma_f32_16x16x32_bf16 v[22:25], v[152:155], v[176:179], v[22:25]
	v_mfma_f32_16x16x32_bf16 v[14:17], v[140:143], v[184:187], v[14:17]
	v_mfma_f32_16x16x32_bf16 v[6:9], v[152:155], v[184:187], v[6:9]
	v_mfma_f32_16x16x32_bf16 v[62:65], v[148:151], v[164:167], v[62:65]
	v_mfma_f32_16x16x32_bf16 v[54:57], v[156:159], v[164:167], v[54:57]
	v_mfma_f32_16x16x32_bf16 v[46:49], v[148:151], v[172:175], v[46:49]
	v_mfma_f32_16x16x32_bf16 v[38:41], v[156:159], v[172:175], v[38:41]
	v_mfma_f32_16x16x32_bf16 v[30:33], v[148:151], v[180:183], v[30:33]
	v_mfma_f32_16x16x32_bf16 v[22:25], v[156:159], v[180:183], v[22:25]
	v_mfma_f32_16x16x32_bf16 v[14:17], v[148:151], v[188:191], v[14:17]
	v_mfma_f32_16x16x32_bf16 v[6:9], v[156:159], v[188:191], v[6:9]
	s_barrier
	s_add_i32 s6, s7, s54
	v_lshl_add_u64 v[140:141], v[134:135], 0, s[16:17]
	s_mov_b32 m0, s6
	v_lshl_add_u64 v[134:135], v[134:135], 0, s[80:81]
	global_load_lds_dwordx4 v[140:141], off
	s_add_i32 m0, s6, 0x2000
	s_nop 0
	global_load_lds_dwordx4 v[134:135], off
	s_waitcnt vmcnt(6)
	s_add_i32 s87, s87, 2
	s_add_u32 s41, s41, 0x100
	s_addc_u32 s86, s86, 0
	s_cmp_gt_u32 s87, 29
	s_mov_b64 s[6:7], s[8:9]
	s_cbranch_scc0 .LBB0_51
	s_barrier
	v_mfma_f32_16x16x32_bf16 v[58:61], v[192:195], v[160:163], v[58:61]
	v_mfma_f32_16x16x32_bf16 v[50:53], v[200:203], v[160:163], v[50:53]
	v_mfma_f32_16x16x32_bf16 v[42:45], v[192:195], v[168:171], v[42:45]
	v_mfma_f32_16x16x32_bf16 v[34:37], v[200:203], v[168:171], v[34:37]
	v_mfma_f32_16x16x32_bf16 v[26:29], v[192:195], v[176:179], v[26:29]
	v_mfma_f32_16x16x32_bf16 v[18:21], v[200:203], v[176:179], v[18:21]
	v_mfma_f32_16x16x32_bf16 v[10:13], v[192:195], v[184:187], v[10:13]
	v_mfma_f32_16x16x32_bf16 v[2:5], v[200:203], v[184:187], v[2:5]
	v_mfma_f32_16x16x32_bf16 v[58:61], v[196:199], v[164:167], v[58:61]
	v_mfma_f32_16x16x32_bf16 v[50:53], v[204:207], v[164:167], v[50:53]
	v_mfma_f32_16x16x32_bf16 v[42:45], v[196:199], v[172:175], v[42:45]
	v_mfma_f32_16x16x32_bf16 v[34:37], v[204:207], v[172:175], v[34:37]
	v_mfma_f32_16x16x32_bf16 v[26:29], v[196:199], v[180:183], v[26:29]
	v_mfma_f32_16x16x32_bf16 v[18:21], v[204:207], v[180:183], v[18:21]
	v_mfma_f32_16x16x32_bf16 v[10:13], v[196:199], v[188:191], v[10:13]
	v_mfma_f32_16x16x32_bf16 v[2:5], v[204:207], v[188:191], v[2:5]
	s_barrier
	v_mul_f32_e32 v144, 0xbfb8aa3b, v126
	v_exp_f32_e32 v144, v144
	v_mov_b32_e32 v134, v136
	s_lshl_b32 s6, s48, 8
	v_add_f32_e32 v144, 1.0, v144
	v_rcp_f32_e32 v144, v144
	s_add_i32 s6, s6, s10
	v_and_or_b32 v139, v134, 15, s6
	s_lshl_b32 s6, s85, 7
	v_mul_f32_e32 v126, v126, v144
	v_mul_f32_e32 v122, v126, v122
	v_mul_f32_e32 v126, 0xbfb8aa3b, v127
	v_exp_f32_e32 v126, v126
	v_ashrrev_i32_e32 v134, 1, v134
	s_or_b32 s6, s6, s58
	v_and_b32_e32 v134, -8, v134
	v_add_f32_e32 v126, 1.0, v126
	v_rcp_f32_e32 v126, v126
	v_add_u32_e32 v140, s6, v134
	v_ashrrev_i32_e32 v141, 31, v140
	v_mov_b64_e32 v[134:135], s[4:5]
	v_mul_f32_e32 v126, v127, v126
	v_mul_f32_e32 v123, v126, v123
	v_mul_f32_e32 v126, 0xbfb8aa3b, v128
	v_exp_f32_e32 v126, v126
	v_mad_i64_i32 v[142:143], s[6:7], v139, s74, v[134:135]
	s_and_b64 vcc, exec, s[44:45]
	v_add_f32_e32 v126, 1.0, v126
	v_rcp_f32_e32 v126, v126
	s_mov_b32 s48, s40
	s_mov_b32 s85, s84
	s_mov_b64 s[8:9], s[46:47]
	v_mul_f32_e32 v126, v128, v126
	v_mul_f32_e32 v124, v126, v124
	v_mul_f32_e32 v126, 0xbfb8aa3b, v129
	v_exp_f32_e32 v126, v126
	s_nop 0
	v_add_f32_e32 v126, 1.0, v126
	v_rcp_f32_e32 v126, v126
	s_nop 0
	v_mul_f32_e32 v126, v129, v126
	v_mul_f32_e32 v125, v126, v125
	v_mul_f32_e32 v126, 0xbfb8aa3b, v118
	v_exp_f32_e32 v126, v126
	s_nop 0
	v_add_f32_e32 v126, 1.0, v126
	v_rcp_f32_e32 v126, v126
	s_nop 0
	v_mul_f32_e32 v118, v118, v126
	v_mul_f32_e32 v118, v118, v114
	v_mul_f32_e32 v114, 0xbfb8aa3b, v119
	v_exp_f32_e32 v114, v114
	s_nop 0
	v_add_f32_e32 v114, 1.0, v114
	v_rcp_f32_e32 v114, v114
	s_nop 0
	v_mul_f32_e32 v114, v119, v114
	v_mul_f32_e32 v119, v114, v115
	v_mul_f32_e32 v114, 0xbfb8aa3b, v120
	v_exp_f32_e32 v114, v114
	s_nop 0
	v_add_f32_e32 v114, 1.0, v114
	v_rcp_f32_e32 v114, v114
	s_nop 0
	v_mul_f32_e32 v114, v120, v114
	v_mul_f32_e32 v126, v114, v116
	v_mul_f32_e32 v114, 0xbfb8aa3b, v121
	v_exp_f32_e32 v114, v114
	v_cvt_pk_bf16_f32 v116, v122, v123
	s_nop 0
	v_add_f32_e32 v114, 1.0, v114
	v_rcp_f32_e32 v114, v114
	s_nop 0
	v_mul_f32_e32 v114, v121, v114
	v_mul_f32_e32 v127, v114, v117
	v_lshlrev_b64 v[114:115], 1, v[140:141]
	v_lshl_add_u64 v[120:121], v[142:143], 0, v[114:115]
	v_cvt_pk_bf16_f32 v117, v124, v125
	v_cvt_pk_bf16_f32 v118, v118, v119
	v_cvt_pk_bf16_f32 v119, v126, v127
	global_store_dwordx4 v[120:121], v[116:119], off
	s_nop 1
	v_mul_f32_e32 v118, 0xbfb8aa3b, v110
	v_exp_f32_e32 v118, v118
	v_or_b32_e32 v116, 16, v139
	v_mad_i64_i32 v[116:117], s[6:7], v116, s74, v[134:135]
	v_add_f32_e32 v118, 1.0, v118
	v_rcp_f32_e32 v118, v118
	s_nop 0
	v_mul_f32_e32 v110, v110, v118
	v_mul_f32_e32 v106, v110, v106
	v_mul_f32_e32 v110, 0xbfb8aa3b, v111
	v_exp_f32_e32 v110, v110
	s_nop 0
	v_add_f32_e32 v110, 1.0, v110
	v_rcp_f32_e32 v110, v110
	s_nop 0
	v_mul_f32_e32 v110, v111, v110
	v_mul_f32_e32 v107, v110, v107
	v_mul_f32_e32 v110, 0xbfb8aa3b, v112
	v_exp_f32_e32 v110, v110
	s_nop 0
	v_add_f32_e32 v110, 1.0, v110
	v_rcp_f32_e32 v110, v110
	s_nop 0
	v_mul_f32_e32 v110, v112, v110
	v_mul_f32_e32 v108, v110, v108
	v_mul_f32_e32 v110, 0xbfb8aa3b, v113
	v_exp_f32_e32 v110, v110
	s_nop 0
	v_add_f32_e32 v110, 1.0, v110
	v_rcp_f32_e32 v110, v110
	s_nop 0
	v_mul_f32_e32 v110, v113, v110
	v_mul_f32_e32 v109, v110, v109
	v_mul_f32_e32 v110, 0xbfb8aa3b, v102
	v_exp_f32_e32 v110, v110
	s_nop 0
	v_add_f32_e32 v110, 1.0, v110
	v_rcp_f32_e32 v110, v110
	s_nop 0
	v_mul_f32_e32 v102, v102, v110
	v_mul_f32_e32 v110, v102, v98
	v_mul_f32_e32 v98, 0xbfb8aa3b, v103
	v_exp_f32_e32 v98, v98
	s_nop 0
	v_add_f32_e32 v98, 1.0, v98
	v_rcp_f32_e32 v98, v98
	s_nop 0
	v_mul_f32_e32 v98, v103, v98
	v_mul_f32_e32 v111, v98, v99
	v_mul_f32_e32 v98, 0xbfb8aa3b, v104
	v_exp_f32_e32 v98, v98
	v_lshl_add_u64 v[102:103], v[116:117], 0, v[114:115]
	v_add_f32_e32 v98, 1.0, v98
	v_rcp_f32_e32 v98, v98
	s_nop 0
	v_mul_f32_e32 v98, v104, v98
	v_mul_f32_e32 v104, v98, v100
	v_mul_f32_e32 v98, 0xbfb8aa3b, v105
	v_exp_f32_e32 v98, v98
	s_nop 0
	v_add_f32_e32 v98, 1.0, v98
	v_rcp_f32_e32 v98, v98
	s_nop 0
	v_mul_f32_e32 v98, v105, v98
	v_mul_f32_e32 v101, v98, v101
	v_cvt_pk_bf16_f32 v98, v106, v107
	v_cvt_pk_bf16_f32 v99, v108, v109
	v_cvt_pk_bf16_f32 v100, v110, v111
	v_cvt_pk_bf16_f32 v101, v104, v101
	global_store_dwordx4 v[102:103], v[98:101], off
	s_nop 1
	v_mul_f32_e32 v100, 0xbfb8aa3b, v94
	v_exp_f32_e32 v100, v100
	v_or_b32_e32 v98, 32, v139
	v_mad_i64_i32 v[98:99], s[6:7], v98, s74, v[134:135]
	v_add_f32_e32 v100, 1.0, v100
	v_rcp_f32_e32 v100, v100
	s_nop 0
	v_mul_f32_e32 v94, v94, v100
	v_mul_f32_e32 v90, v94, v90
	v_mul_f32_e32 v94, 0xbfb8aa3b, v95
	v_exp_f32_e32 v94, v94
	s_nop 0
	v_add_f32_e32 v94, 1.0, v94
	v_rcp_f32_e32 v94, v94
	s_nop 0
	v_mul_f32_e32 v94, v95, v94
	v_mul_f32_e32 v91, v94, v91
	v_mul_f32_e32 v94, 0xbfb8aa3b, v96
	v_exp_f32_e32 v94, v94
	s_nop 0
	v_add_f32_e32 v94, 1.0, v94
	v_rcp_f32_e32 v94, v94
	s_nop 0
	v_mul_f32_e32 v94, v96, v94
	v_mul_f32_e32 v92, v94, v92
	v_mul_f32_e32 v94, 0xbfb8aa3b, v97
	v_exp_f32_e32 v94, v94
	s_nop 0
	v_add_f32_e32 v94, 1.0, v94
	v_rcp_f32_e32 v94, v94
	s_nop 0
	v_mul_f32_e32 v94, v97, v94
	v_mul_f32_e32 v93, v94, v93
	v_mul_f32_e32 v94, 0xbfb8aa3b, v86
	v_exp_f32_e32 v94, v94
	s_nop 0
	v_add_f32_e32 v94, 1.0, v94
	v_rcp_f32_e32 v94, v94
	s_nop 0
	v_mul_f32_e32 v86, v86, v94
	v_mul_f32_e32 v94, v86, v82
	v_mul_f32_e32 v82, 0xbfb8aa3b, v87
	v_exp_f32_e32 v82, v82
	s_nop 0
	v_add_f32_e32 v82, 1.0, v82
	v_rcp_f32_e32 v82, v82
	s_nop 0
	v_mul_f32_e32 v82, v87, v82
	v_mul_f32_e32 v95, v82, v83
	v_mul_f32_e32 v82, 0xbfb8aa3b, v88
	v_exp_f32_e32 v82, v82
	v_lshl_add_u64 v[86:87], v[98:99], 0, v[114:115]
	v_add_f32_e32 v82, 1.0, v82
	v_rcp_f32_e32 v82, v82
	s_nop 0
	v_mul_f32_e32 v82, v88, v82
	v_mul_f32_e32 v88, v82, v84
	v_mul_f32_e32 v82, 0xbfb8aa3b, v89
	v_exp_f32_e32 v82, v82
	s_nop 0
	v_add_f32_e32 v82, 1.0, v82
	v_rcp_f32_e32 v82, v82
	s_nop 0
	v_mul_f32_e32 v82, v89, v82
	v_mul_f32_e32 v85, v82, v85
	v_cvt_pk_bf16_f32 v82, v90, v91
	v_cvt_pk_bf16_f32 v83, v92, v93
	v_cvt_pk_bf16_f32 v84, v94, v95
	v_cvt_pk_bf16_f32 v85, v88, v85
	global_store_dwordx4 v[86:87], v[82:85], off
	s_nop 1
	v_mul_f32_e32 v84, 0xbfb8aa3b, v78
	v_exp_f32_e32 v84, v84
	v_or_b32_e32 v82, 48, v139
	v_mad_i64_i32 v[82:83], s[6:7], v82, s74, v[134:135]
	v_add_f32_e32 v84, 1.0, v84
	v_rcp_f32_e32 v84, v84
	s_nop 0
	v_mul_f32_e32 v78, v78, v84
	v_mul_f32_e32 v74, v78, v74
	v_mul_f32_e32 v78, 0xbfb8aa3b, v79
	v_exp_f32_e32 v78, v78
	s_nop 0
	v_add_f32_e32 v78, 1.0, v78
	v_rcp_f32_e32 v78, v78
	s_nop 0
	v_mul_f32_e32 v78, v79, v78
	v_mul_f32_e32 v75, v78, v75
	v_mul_f32_e32 v78, 0xbfb8aa3b, v80
	v_exp_f32_e32 v78, v78
	s_nop 0
	v_add_f32_e32 v78, 1.0, v78
	v_rcp_f32_e32 v78, v78
	s_nop 0
	v_mul_f32_e32 v78, v80, v78
	v_mul_f32_e32 v76, v78, v76
	v_mul_f32_e32 v78, 0xbfb8aa3b, v81
	v_exp_f32_e32 v78, v78
	s_nop 0
	v_add_f32_e32 v78, 1.0, v78
	v_rcp_f32_e32 v78, v78
	s_nop 0
	v_mul_f32_e32 v78, v81, v78
	v_mul_f32_e32 v77, v78, v77
	v_mul_f32_e32 v78, 0xbfb8aa3b, v70
	v_exp_f32_e32 v78, v78
	s_nop 0
	v_add_f32_e32 v78, 1.0, v78
	v_rcp_f32_e32 v78, v78
	s_nop 0
	v_mul_f32_e32 v70, v70, v78
	v_mul_f32_e32 v78, v70, v66
	v_mul_f32_e32 v66, 0xbfb8aa3b, v71
	v_exp_f32_e32 v66, v66
	s_nop 0
	v_add_f32_e32 v66, 1.0, v66
	v_rcp_f32_e32 v66, v66
	s_nop 0
	v_mul_f32_e32 v66, v71, v66
	v_mul_f32_e32 v79, v66, v67
	v_mul_f32_e32 v66, 0xbfb8aa3b, v72
	v_exp_f32_e32 v66, v66
	v_lshl_add_u64 v[70:71], v[82:83], 0, v[114:115]
	v_add_f32_e32 v66, 1.0, v66
	v_rcp_f32_e32 v66, v66
	s_nop 0
	v_mul_f32_e32 v66, v72, v66
	v_mul_f32_e32 v72, v66, v68
	v_mul_f32_e32 v66, 0xbfb8aa3b, v73
	v_exp_f32_e32 v66, v66
	s_nop 0
	v_add_f32_e32 v66, 1.0, v66
	v_rcp_f32_e32 v66, v66
	s_nop 0
	v_mul_f32_e32 v66, v73, v66
	v_mul_f32_e32 v69, v66, v69
	v_cvt_pk_bf16_f32 v66, v74, v75
	v_cvt_pk_bf16_f32 v67, v76, v77
	v_cvt_pk_bf16_f32 v68, v78, v79
	v_cvt_pk_bf16_f32 v69, v72, v69
	global_store_dwordx4 v[70:71], v[66:69], off
	s_nop 1
	v_mul_f32_e32 v68, 0xbfb8aa3b, v62
	v_exp_f32_e32 v68, v68
	v_add_u32_e32 v66, 0x80, v139
	v_mad_i64_i32 v[66:67], s[6:7], v66, s74, v[134:135]
	v_add_f32_e32 v68, 1.0, v68
	v_rcp_f32_e32 v68, v68
	s_nop 0
	v_mul_f32_e32 v62, v62, v68
	v_mul_f32_e32 v58, v62, v58
	v_mul_f32_e32 v62, 0xbfb8aa3b, v63
	v_exp_f32_e32 v62, v62
	s_nop 0
	v_add_f32_e32 v62, 1.0, v62
	v_rcp_f32_e32 v62, v62
	s_nop 0
	v_mul_f32_e32 v62, v63, v62
	v_mul_f32_e32 v59, v62, v59
	v_mul_f32_e32 v62, 0xbfb8aa3b, v64
	v_exp_f32_e32 v62, v62
	s_nop 0
	v_add_f32_e32 v62, 1.0, v62
	v_rcp_f32_e32 v62, v62
	s_nop 0
	v_mul_f32_e32 v62, v64, v62
	v_mul_f32_e32 v60, v62, v60
	v_mul_f32_e32 v62, 0xbfb8aa3b, v65
	v_exp_f32_e32 v62, v62
	s_nop 0
	v_add_f32_e32 v62, 1.0, v62
	v_rcp_f32_e32 v62, v62
	s_nop 0
	v_mul_f32_e32 v62, v65, v62
	v_mul_f32_e32 v61, v62, v61
	v_mul_f32_e32 v62, 0xbfb8aa3b, v54
	v_exp_f32_e32 v62, v62
	s_nop 0
	v_add_f32_e32 v62, 1.0, v62
	v_rcp_f32_e32 v62, v62
	s_nop 0
	v_mul_f32_e32 v54, v54, v62
	v_mul_f32_e32 v62, v54, v50
	v_mul_f32_e32 v50, 0xbfb8aa3b, v55
	v_exp_f32_e32 v50, v50
	s_nop 0
	v_add_f32_e32 v50, 1.0, v50
	v_rcp_f32_e32 v50, v50
	s_nop 0
	v_mul_f32_e32 v50, v55, v50
	v_mul_f32_e32 v63, v50, v51
	v_mul_f32_e32 v50, 0xbfb8aa3b, v56
	v_exp_f32_e32 v50, v50
	v_lshl_add_u64 v[54:55], v[66:67], 0, v[114:115]
	v_add_f32_e32 v50, 1.0, v50
	v_rcp_f32_e32 v50, v50
	s_nop 0
	v_mul_f32_e32 v50, v56, v50
	v_mul_f32_e32 v56, v50, v52
	v_mul_f32_e32 v50, 0xbfb8aa3b, v57
	v_exp_f32_e32 v50, v50
	s_nop 0
	v_add_f32_e32 v50, 1.0, v50
	v_rcp_f32_e32 v50, v50
	s_nop 0
	v_mul_f32_e32 v50, v57, v50
	v_mul_f32_e32 v53, v50, v53
	v_cvt_pk_bf16_f32 v50, v58, v59
	v_cvt_pk_bf16_f32 v51, v60, v61
	v_cvt_pk_bf16_f32 v52, v62, v63
	v_cvt_pk_bf16_f32 v53, v56, v53
	global_store_dwordx4 v[54:55], v[50:53], off
	s_nop 1
	v_mul_f32_e32 v52, 0xbfb8aa3b, v46
	v_exp_f32_e32 v52, v52
	v_add_u32_e32 v50, 0x90, v139
	v_mad_i64_i32 v[50:51], s[6:7], v50, s74, v[134:135]
	v_add_f32_e32 v52, 1.0, v52
	v_rcp_f32_e32 v52, v52
	s_nop 0
	v_mul_f32_e32 v46, v46, v52
	v_mul_f32_e32 v42, v46, v42
	v_mul_f32_e32 v46, 0xbfb8aa3b, v47
	v_exp_f32_e32 v46, v46
	s_nop 0
	v_add_f32_e32 v46, 1.0, v46
	v_rcp_f32_e32 v46, v46
	s_nop 0
	v_mul_f32_e32 v46, v47, v46
	v_mul_f32_e32 v43, v46, v43
	v_mul_f32_e32 v46, 0xbfb8aa3b, v48
	v_exp_f32_e32 v46, v46
	s_nop 0
	v_add_f32_e32 v46, 1.0, v46
	v_rcp_f32_e32 v46, v46
	s_nop 0
	v_mul_f32_e32 v46, v48, v46
	v_mul_f32_e32 v44, v46, v44
	v_mul_f32_e32 v46, 0xbfb8aa3b, v49
	v_exp_f32_e32 v46, v46
	s_nop 0
	v_add_f32_e32 v46, 1.0, v46
	v_rcp_f32_e32 v46, v46
	s_nop 0
	v_mul_f32_e32 v46, v49, v46
	v_mul_f32_e32 v45, v46, v45
	v_mul_f32_e32 v46, 0xbfb8aa3b, v38
	v_exp_f32_e32 v46, v46
	s_nop 0
	v_add_f32_e32 v46, 1.0, v46
	v_rcp_f32_e32 v46, v46
	s_nop 0
	v_mul_f32_e32 v38, v38, v46
	v_mul_f32_e32 v46, v38, v34
	v_mul_f32_e32 v34, 0xbfb8aa3b, v39
	v_exp_f32_e32 v34, v34
	s_nop 0
	v_add_f32_e32 v34, 1.0, v34
	v_rcp_f32_e32 v34, v34
	s_nop 0
	v_mul_f32_e32 v34, v39, v34
	v_mul_f32_e32 v47, v34, v35
	v_mul_f32_e32 v34, 0xbfb8aa3b, v40
	v_exp_f32_e32 v34, v34
	v_lshl_add_u64 v[38:39], v[50:51], 0, v[114:115]
	v_add_f32_e32 v34, 1.0, v34
	v_rcp_f32_e32 v34, v34
	s_nop 0
	v_mul_f32_e32 v34, v40, v34
	v_mul_f32_e32 v40, v34, v36
	v_mul_f32_e32 v34, 0xbfb8aa3b, v41
	v_exp_f32_e32 v34, v34
	s_nop 0
	v_add_f32_e32 v34, 1.0, v34
	v_rcp_f32_e32 v34, v34
	s_nop 0
	v_mul_f32_e32 v34, v41, v34
	v_mul_f32_e32 v37, v34, v37
	v_cvt_pk_bf16_f32 v34, v42, v43
	v_cvt_pk_bf16_f32 v35, v44, v45
	v_cvt_pk_bf16_f32 v36, v46, v47
	v_cvt_pk_bf16_f32 v37, v40, v37
	global_store_dwordx4 v[38:39], v[34:37], off
	s_nop 1
	v_mul_f32_e32 v36, 0xbfb8aa3b, v30
	v_exp_f32_e32 v36, v36
	v_add_u32_e32 v34, 0xa0, v139
	v_mad_i64_i32 v[34:35], s[6:7], v34, s74, v[134:135]
	v_add_f32_e32 v36, 1.0, v36
	v_rcp_f32_e32 v36, v36
	s_nop 0
	v_mul_f32_e32 v30, v30, v36
	v_mul_f32_e32 v26, v30, v26
	v_mul_f32_e32 v30, 0xbfb8aa3b, v31
	v_exp_f32_e32 v30, v30
	s_nop 0
	v_add_f32_e32 v30, 1.0, v30
	v_rcp_f32_e32 v30, v30
	s_nop 0
	v_mul_f32_e32 v30, v31, v30
	v_mul_f32_e32 v27, v30, v27
	v_mul_f32_e32 v30, 0xbfb8aa3b, v32
	v_exp_f32_e32 v30, v30
	s_nop 0
	v_add_f32_e32 v30, 1.0, v30
	v_rcp_f32_e32 v30, v30
	s_nop 0
	v_mul_f32_e32 v30, v32, v30
	v_mul_f32_e32 v28, v30, v28
	v_mul_f32_e32 v30, 0xbfb8aa3b, v33
	v_exp_f32_e32 v30, v30
	s_nop 0
	v_add_f32_e32 v30, 1.0, v30
	v_rcp_f32_e32 v30, v30
	s_nop 0
	v_mul_f32_e32 v30, v33, v30
	v_mul_f32_e32 v29, v30, v29
	v_mul_f32_e32 v30, 0xbfb8aa3b, v22
	v_exp_f32_e32 v30, v30
	s_nop 0
	v_add_f32_e32 v30, 1.0, v30
	v_rcp_f32_e32 v30, v30
	s_nop 0
	v_mul_f32_e32 v22, v22, v30
	v_mul_f32_e32 v30, v22, v18
	v_mul_f32_e32 v18, 0xbfb8aa3b, v23
	v_exp_f32_e32 v18, v18
	s_nop 0
	v_add_f32_e32 v18, 1.0, v18
	v_rcp_f32_e32 v18, v18
	s_nop 0
	v_mul_f32_e32 v18, v23, v18
	v_mul_f32_e32 v31, v18, v19
	v_mul_f32_e32 v18, 0xbfb8aa3b, v24
	v_exp_f32_e32 v18, v18
	v_lshl_add_u64 v[22:23], v[34:35], 0, v[114:115]
	v_add_f32_e32 v18, 1.0, v18
	v_rcp_f32_e32 v18, v18
	s_nop 0
	v_mul_f32_e32 v18, v24, v18
	v_mul_f32_e32 v24, v18, v20
	v_mul_f32_e32 v18, 0xbfb8aa3b, v25
	v_exp_f32_e32 v18, v18
	s_nop 0
	v_add_f32_e32 v18, 1.0, v18
	v_rcp_f32_e32 v18, v18
	s_nop 0
	v_mul_f32_e32 v18, v25, v18
	v_mul_f32_e32 v21, v18, v21
	v_cvt_pk_bf16_f32 v18, v26, v27
	v_cvt_pk_bf16_f32 v19, v28, v29
	v_cvt_pk_bf16_f32 v20, v30, v31
	v_cvt_pk_bf16_f32 v21, v24, v21
	global_store_dwordx4 v[22:23], v[18:21], off
	s_nop 1
	v_mul_f32_e32 v20, 0xbfb8aa3b, v14
	v_exp_f32_e32 v20, v20
	v_add_u32_e32 v18, 0xb0, v139
	v_mad_i64_i32 v[18:19], s[6:7], v18, s74, v[134:135]
	v_add_f32_e32 v20, 1.0, v20
	v_rcp_f32_e32 v20, v20
	s_mov_b64 s[6:7], s[42:43]
	v_mul_f32_e32 v14, v14, v20
	v_mul_f32_e32 v10, v14, v10
	v_mul_f32_e32 v14, 0xbfb8aa3b, v15
	v_exp_f32_e32 v14, v14
	s_nop 0
	v_add_f32_e32 v14, 1.0, v14
	v_rcp_f32_e32 v14, v14
	s_nop 0
	v_mul_f32_e32 v14, v15, v14
	v_mul_f32_e32 v11, v14, v11
	v_mul_f32_e32 v14, 0xbfb8aa3b, v16
	v_exp_f32_e32 v14, v14
	s_nop 0
	v_add_f32_e32 v14, 1.0, v14
	v_rcp_f32_e32 v14, v14
	s_nop 0
	v_mul_f32_e32 v14, v16, v14
	v_mul_f32_e32 v12, v14, v12
	v_mul_f32_e32 v14, 0xbfb8aa3b, v17
	v_exp_f32_e32 v14, v14
	s_nop 0
	v_add_f32_e32 v14, 1.0, v14
	v_rcp_f32_e32 v14, v14
	s_nop 0
	v_mul_f32_e32 v14, v17, v14
	v_mul_f32_e32 v13, v14, v13
	v_mul_f32_e32 v14, 0xbfb8aa3b, v6
	v_exp_f32_e32 v14, v14
	s_nop 0
	v_add_f32_e32 v14, 1.0, v14
	v_rcp_f32_e32 v14, v14
	s_nop 0
	v_mul_f32_e32 v6, v6, v14
	v_mul_f32_e32 v14, v6, v2
	v_mul_f32_e32 v2, 0xbfb8aa3b, v7
	v_exp_f32_e32 v2, v2
	s_nop 0
	v_add_f32_e32 v2, 1.0, v2
	v_rcp_f32_e32 v2, v2
	s_nop 0
	v_mul_f32_e32 v2, v7, v2
	v_mul_f32_e32 v15, v2, v3
	v_mul_f32_e32 v2, 0xbfb8aa3b, v8
	v_exp_f32_e32 v2, v2
	v_lshl_add_u64 v[6:7], v[18:19], 0, v[114:115]
	v_add_f32_e32 v2, 1.0, v2
	v_rcp_f32_e32 v2, v2
	s_nop 0
	v_mul_f32_e32 v2, v8, v2
	v_mul_f32_e32 v8, v2, v4
	v_mul_f32_e32 v2, 0xbfb8aa3b, v9
	v_exp_f32_e32 v2, v2
	s_nop 0
	v_add_f32_e32 v2, 1.0, v2
	v_rcp_f32_e32 v2, v2
	s_nop 0
	v_mul_f32_e32 v2, v9, v2
	v_mul_f32_e32 v5, v2, v5
	v_cvt_pk_bf16_f32 v2, v10, v11
	v_cvt_pk_bf16_f32 v3, v12, v13
	v_cvt_pk_bf16_f32 v4, v14, v15
	v_cvt_pk_bf16_f32 v5, v8, v5
	global_store_dwordx4 v[6:7], v[2:5], off
	s_cbranch_vccz .LBB0_48
	s_waitcnt vmcnt(0)
	v_readlane_b32 s0, v255, 8
	v_readlane_b32 s62, v255, 10
	v_readlane_b32 s84, v255, 12
	s_cmpk_gt_u32 s22, 0xff
	v_readlane_b32 s1, v255, 9
	s_mov_b64 s[58:59], s[92:93]
	v_readlane_b32 s63, v255, 11
	v_readlane_b32 s85, v255, 13
	s_cbranch_scc1 .LBB0_55
	s_barrier

.Lrot_enter_8:
	s_add_u32 s7, s50, 0xfff80080
	s_addc_u32 s11, s51, -1
	s_add_i32 s43, 0, 0x10000
	v_add_u32_e32 v132, s43, v135
	ds_read_b128 v[138:141], v132
	ds_read_b128 v[142:145], v132 offset:1024
	ds_read_b128 v[148:151], v132 offset:2048
	ds_read_b128 v[152:155], v132 offset:3072
	s_cmp_eq_u32 s6, 28
	s_cselect_b32 s79, s45, s11
	s_cselect_b32 s78, s44, s7
	s_cselect_b32 s91, s47, s9
	s_cselect_b32 s90, s46, s8
	v_lshl_add_u64 v[132:133], s[50:51], 0, v[130:131]
	s_add_i32 m0, s49, 0xc000
	ds_read_b128 v[156:159], v136
	ds_read_b128 v[160:163], v136 offset:1024
	ds_read_b128 v[164:167], v136 offset:2048
	ds_read_b128 v[168:171], v136 offset:3072
	ds_read_b128 v[172:175], v136 offset:4096
	ds_read_b128 v[176:179], v136 offset:5120
	ds_read_b128 v[180:183], v136 offset:6144
	ds_read_b128 v[184:187], v136 offset:7168
	global_load_lds_dwordx4 v[132:133], off
	v_lshl_add_u64 v[132:133], v[132:133], 0, s[60:61]
	s_add_i32 m0, s49, 0xe000
	s_nop 0
	global_load_lds_dwordx4 v[132:133], off
	s_waitcnt lgkmcnt(8)
	s_barrier
	s_waitcnt lgkmcnt(0)
	v_mfma_f32_16x16x32_bf16 v[126:129], v[138:141], v[156:159], v[126:129]
	v_mfma_f32_16x16x32_bf16 v[122:125], v[148:151], v[156:159], v[122:125]
	v_mfma_f32_16x16x32_bf16 v[118:121], v[138:141], v[164:167], v[118:121]
	v_mfma_f32_16x16x32_bf16 v[110:113], v[148:151], v[164:167], v[110:113]
	v_mfma_f32_16x16x32_bf16 v[102:105], v[138:141], v[172:175], v[102:105]
	v_mfma_f32_16x16x32_bf16 v[94:97], v[148:151], v[172:175], v[94:97]
	v_mfma_f32_16x16x32_bf16 v[86:89], v[138:141], v[180:183], v[86:89]
	v_mfma_f32_16x16x32_bf16 v[78:81], v[148:151], v[180:183], v[78:81]
	v_mfma_f32_16x16x32_bf16 v[126:129], v[142:145], v[160:163], v[126:129]
	v_mfma_f32_16x16x32_bf16 v[122:125], v[152:155], v[160:163], v[122:125]
	v_mfma_f32_16x16x32_bf16 v[118:121], v[142:145], v[168:171], v[118:121]
	v_mfma_f32_16x16x32_bf16 v[110:113], v[152:155], v[168:171], v[110:113]
	v_mfma_f32_16x16x32_bf16 v[102:105], v[142:145], v[176:179], v[102:105]
	v_mfma_f32_16x16x32_bf16 v[94:97], v[152:155], v[176:179], v[94:97]
	v_mfma_f32_16x16x32_bf16 v[86:89], v[142:145], v[184:187], v[86:89]
	v_mfma_f32_16x16x32_bf16 v[78:81], v[152:155], v[184:187], v[78:81]
	s_barrier
	s_add_i32 s7, 0, 0x14000
	v_add_u32_e32 v132, s7, v135
	s_add_i32 s11, s43, s57
	ds_read_b128 v[188:191], v132
	ds_read_b128 v[192:195], v132 offset:1024
	ds_read_b128 v[196:199], v132 offset:2048
	ds_read_b128 v[200:203], v132 offset:3072
	v_lshl_add_u64 v[132:133], s[90:91], 0, v[0:1]
	s_mov_b32 m0, s11
	v_lshl_add_u64 v[204:205], v[132:133], 0, s[60:61]
	global_load_lds_dwordx4 v[132:133], off
	s_add_i32 m0, s11, 0x2000
	s_nop 0
	global_load_lds_dwordx4 v[204:205], off
	s_waitcnt lgkmcnt(0)
	s_barrier
	v_mfma_f32_16x16x32_bf16 v[114:117], v[188:191], v[156:159], v[114:117]
	v_mfma_f32_16x16x32_bf16 v[106:109], v[196:199], v[156:159], v[106:109]
	v_mfma_f32_16x16x32_bf16 v[98:101], v[188:191], v[164:167], v[98:101]
	v_mfma_f32_16x16x32_bf16 v[90:93], v[196:199], v[164:167], v[90:93]
	v_mfma_f32_16x16x32_bf16 v[82:85], v[188:191], v[172:175], v[82:85]
	v_mfma_f32_16x16x32_bf16 v[74:77], v[196:199], v[172:175], v[74:77]
	v_mfma_f32_16x16x32_bf16 v[70:73], v[188:191], v[180:183], v[70:73]
	v_mfma_f32_16x16x32_bf16 v[66:69], v[196:199], v[180:183], v[66:69]
	v_mfma_f32_16x16x32_bf16 v[114:117], v[192:195], v[160:163], v[114:117]
	v_mfma_f32_16x16x32_bf16 v[106:109], v[200:203], v[160:163], v[106:109]
	v_mfma_f32_16x16x32_bf16 v[98:101], v[192:195], v[168:171], v[98:101]
	v_mfma_f32_16x16x32_bf16 v[90:93], v[200:203], v[168:171], v[90:93]
	v_mfma_f32_16x16x32_bf16 v[82:85], v[192:195], v[176:179], v[82:85]
	v_mfma_f32_16x16x32_bf16 v[74:77], v[200:203], v[176:179], v[74:77]
	v_mfma_f32_16x16x32_bf16 v[70:73], v[192:195], v[184:187], v[70:73]
	v_mfma_f32_16x16x32_bf16 v[66:69], v[200:203], v[184:187], v[66:69]
	s_barrier
	s_mov_b32 m0, s49
	v_lshl_add_u64 v[204:205], s[78:79], 0, v[0:1]
	ds_read_b128 v[156:159], v136 offset:16384
	ds_read_b128 v[160:163], v136 offset:17408
	ds_read_b128 v[164:167], v136 offset:18432
	ds_read_b128 v[168:171], v136 offset:19456
	ds_read_b128 v[172:175], v136 offset:20480
	ds_read_b128 v[176:179], v136 offset:21504
	ds_read_b128 v[180:183], v136 offset:22528
	ds_read_b128 v[184:187], v136 offset:23552
	global_load_lds_dwordx4 v[204:205], off
	v_lshl_add_u64 v[206:207], v[204:205], 0, s[60:61]
	s_mov_b32 m0, s58
	s_nop 0
	global_load_lds_dwordx4 v[206:207], off
	s_waitcnt lgkmcnt(0)
	s_barrier
	v_mfma_f32_16x16x32_bf16 v[62:65], v[138:141], v[156:159], v[62:65]
	v_mfma_f32_16x16x32_bf16 v[58:61], v[148:151], v[156:159], v[58:61]
	v_mfma_f32_16x16x32_bf16 v[54:57], v[138:141], v[164:167], v[54:57]
	v_mfma_f32_16x16x32_bf16 v[46:49], v[148:151], v[164:167], v[46:49]
	v_mfma_f32_16x16x32_bf16 v[38:41], v[138:141], v[172:175], v[38:41]
	v_mfma_f32_16x16x32_bf16 v[30:33], v[148:151], v[172:175], v[30:33]
	v_mfma_f32_16x16x32_bf16 v[22:25], v[138:141], v[180:183], v[22:25]
	v_mfma_f32_16x16x32_bf16 v[14:17], v[148:151], v[180:183], v[14:17]
	v_mfma_f32_16x16x32_bf16 v[62:65], v[142:145], v[160:163], v[62:65]
	v_mfma_f32_16x16x32_bf16 v[58:61], v[152:155], v[160:163], v[58:61]
	v_mfma_f32_16x16x32_bf16 v[54:57], v[142:145], v[168:171], v[54:57]
	v_mfma_f32_16x16x32_bf16 v[46:49], v[152:155], v[168:171], v[46:49]
	v_mfma_f32_16x16x32_bf16 v[38:41], v[142:145], v[176:179], v[38:41]
	v_mfma_f32_16x16x32_bf16 v[30:33], v[152:155], v[176:179], v[30:33]
	v_mfma_f32_16x16x32_bf16 v[22:25], v[142:145], v[184:187], v[22:25]
	v_mfma_f32_16x16x32_bf16 v[14:17], v[152:155], v[184:187], v[14:17]
	s_barrier
	s_add_i32 s7, s7, s57
	v_lshl_add_u64 v[138:139], v[132:133], 0, s[20:21]
	s_mov_b32 m0, s7
	s_nop 0
	global_load_lds_dwordx4 v[138:139], off
	v_lshl_add_u64 v[138:139], v[132:133], 0, s[64:65]
	s_add_i32 m0, s7, 0x2000
	s_nop 0
	global_load_lds_dwordx4 v[138:139], off
	v_lshl_add_u64 v[230:231], v[204:205], 0, s[20:21]
	s_mov_b32 m0, s59
	s_nop 0
	global_load_lds_dwordx4 v[230:231], off
	v_lshl_add_u64 v[230:231], v[204:205], 0, s[64:65]
	s_mov_b32 m0, s62
	s_nop 0
	global_load_lds_dwordx4 v[230:231], off
	s_waitcnt vmcnt(8)
	s_barrier
	v_mfma_f32_16x16x32_bf16 v[50:53], v[188:191], v[156:159], v[50:53]
	v_mfma_f32_16x16x32_bf16 v[42:45], v[196:199], v[156:159], v[42:45]
	v_mfma_f32_16x16x32_bf16 v[34:37], v[188:191], v[164:167], v[34:37]
	v_mfma_f32_16x16x32_bf16 v[26:29], v[196:199], v[164:167], v[26:29]
	v_mfma_f32_16x16x32_bf16 v[18:21], v[188:191], v[172:175], v[18:21]
	v_mfma_f32_16x16x32_bf16 v[10:13], v[196:199], v[172:175], v[10:13]
	v_mfma_f32_16x16x32_bf16 v[6:9], v[188:191], v[180:183], v[6:9]
	v_mfma_f32_16x16x32_bf16 v[2:5], v[196:199], v[180:183], v[2:5]
	v_mfma_f32_16x16x32_bf16 v[50:53], v[192:195], v[160:163], v[50:53]
	v_mfma_f32_16x16x32_bf16 v[42:45], v[200:203], v[160:163], v[42:45]
	v_mfma_f32_16x16x32_bf16 v[34:37], v[192:195], v[168:171], v[34:37]
	v_mfma_f32_16x16x32_bf16 v[26:29], v[200:203], v[168:171], v[26:29]
	v_mfma_f32_16x16x32_bf16 v[18:21], v[192:195], v[176:179], v[18:21]
	v_mfma_f32_16x16x32_bf16 v[10:13], v[200:203], v[176:179], v[10:13]
	v_mfma_f32_16x16x32_bf16 v[6:9], v[192:195], v[184:187], v[6:9]
	v_mfma_f32_16x16x32_bf16 v[2:5], v[200:203], v[184:187], v[2:5]
	s_barrier
	s_add_i32 s7, 0, 0x18000
	v_add_u32_e32 v137, s7, v135
	ds_read_b128 v[138:141], v137
	ds_read_b128 v[142:145], v137 offset:1024
	ds_read_b128 v[148:151], v137 offset:2048
	ds_read_b128 v[152:155], v137 offset:3072
	ds_read_b128 v[156:159], v136 offset:32768
	ds_read_b128 v[160:163], v136 offset:33792
	ds_read_b128 v[164:167], v136 offset:34816
	ds_read_b128 v[168:171], v136 offset:35840
	ds_read_b128 v[172:175], v136 offset:36864
	ds_read_b128 v[176:179], v136 offset:37888
	ds_read_b128 v[180:183], v136 offset:38912
	ds_read_b128 v[184:187], v136 offset:39936
	s_waitcnt lgkmcnt(8)
	s_barrier
	s_waitcnt lgkmcnt(0)
	v_mfma_f32_16x16x32_bf16 v[126:129], v[138:141], v[156:159], v[126:129]
	v_mfma_f32_16x16x32_bf16 v[122:125], v[148:151], v[156:159], v[122:125]
	v_mfma_f32_16x16x32_bf16 v[118:121], v[138:141], v[164:167], v[118:121]
	v_mfma_f32_16x16x32_bf16 v[110:113], v[148:151], v[164:167], v[110:113]
	v_mfma_f32_16x16x32_bf16 v[102:105], v[138:141], v[172:175], v[102:105]
	v_mfma_f32_16x16x32_bf16 v[94:97], v[148:151], v[172:175], v[94:97]
	v_mfma_f32_16x16x32_bf16 v[86:89], v[138:141], v[180:183], v[86:89]
	v_mfma_f32_16x16x32_bf16 v[78:81], v[148:151], v[180:183], v[78:81]
	v_mfma_f32_16x16x32_bf16 v[126:129], v[142:145], v[160:163], v[126:129]
	v_mfma_f32_16x16x32_bf16 v[122:125], v[152:155], v[160:163], v[122:125]
	v_mfma_f32_16x16x32_bf16 v[118:121], v[142:145], v[168:171], v[118:121]
	v_mfma_f32_16x16x32_bf16 v[110:113], v[152:155], v[168:171], v[110:113]
	v_mfma_f32_16x16x32_bf16 v[102:105], v[142:145], v[176:179], v[102:105]
	v_mfma_f32_16x16x32_bf16 v[94:97], v[152:155], v[176:179], v[94:97]
	v_mfma_f32_16x16x32_bf16 v[86:89], v[142:145], v[184:187], v[86:89]
	v_mfma_f32_16x16x32_bf16 v[78:81], v[152:155], v[184:187], v[78:81]
	s_barrier
	s_add_i32 s11, 0, 0x1c000
	s_add_i32 s7, s7, s57
	v_add_u32_e32 v137, s11, v135
	v_lshl_add_u64 v[206:207], v[132:133], 0, s[34:35]
	s_mov_b32 m0, s7
	ds_read_b128 v[188:191], v137
	ds_read_b128 v[192:195], v137 offset:1024
	ds_read_b128 v[196:199], v137 offset:2048
	ds_read_b128 v[200:203], v137 offset:3072
	global_load_lds_dwordx4 v[206:207], off
	v_lshl_add_u64 v[206:207], v[132:133], 0, s[66:67]
	s_add_i32 m0, s7, 0x2000
	s_nop 0
	global_load_lds_dwordx4 v[206:207], off
	s_waitcnt lgkmcnt(0)
	s_barrier
	v_mfma_f32_16x16x32_bf16 v[114:117], v[188:191], v[156:159], v[114:117]
	v_mfma_f32_16x16x32_bf16 v[106:109], v[196:199], v[156:159], v[106:109]
	v_mfma_f32_16x16x32_bf16 v[98:101], v[188:191], v[164:167], v[98:101]
	v_mfma_f32_16x16x32_bf16 v[90:93], v[196:199], v[164:167], v[90:93]
	v_mfma_f32_16x16x32_bf16 v[82:85], v[188:191], v[172:175], v[82:85]
	v_mfma_f32_16x16x32_bf16 v[74:77], v[196:199], v[172:175], v[74:77]
	v_mfma_f32_16x16x32_bf16 v[70:73], v[188:191], v[180:183], v[70:73]
	v_mfma_f32_16x16x32_bf16 v[66:69], v[196:199], v[180:183], v[66:69]
	v_mfma_f32_16x16x32_bf16 v[114:117], v[192:195], v[160:163], v[114:117]
	v_mfma_f32_16x16x32_bf16 v[106:109], v[200:203], v[160:163], v[106:109]
	v_mfma_f32_16x16x32_bf16 v[98:101], v[192:195], v[168:171], v[98:101]
	v_mfma_f32_16x16x32_bf16 v[90:93], v[200:203], v[168:171], v[90:93]
	v_mfma_f32_16x16x32_bf16 v[82:85], v[192:195], v[176:179], v[82:85]
	v_mfma_f32_16x16x32_bf16 v[74:77], v[200:203], v[176:179], v[74:77]
	v_mfma_f32_16x16x32_bf16 v[70:73], v[192:195], v[184:187], v[70:73]
	v_mfma_f32_16x16x32_bf16 v[66:69], v[200:203], v[184:187], v[66:69]
	s_barrier
	s_mov_b32 m0, s85
	v_lshl_add_u64 v[206:207], v[204:205], 0, s[34:35]
	ds_read_b128 v[156:159], v136 offset:49152
	ds_read_b128 v[160:163], v136 offset:50176
	ds_read_b128 v[164:167], v136 offset:51200
	ds_read_b128 v[168:171], v136 offset:52224
	ds_read_b128 v[172:175], v136 offset:53248
	ds_read_b128 v[176:179], v136 offset:54272
	ds_read_b128 v[180:183], v136 offset:55296
	ds_read_b128 v[184:187], v136 offset:56320
	global_load_lds_dwordx4 v[206:207], off
	v_lshl_add_u64 v[204:205], v[204:205], 0, s[66:67]
	s_mov_b32 m0, s86
	s_nop 0
	global_load_lds_dwordx4 v[204:205], off
	s_waitcnt lgkmcnt(0)
	s_barrier
	v_mfma_f32_16x16x32_bf16 v[62:65], v[138:141], v[156:159], v[62:65]
	v_mfma_f32_16x16x32_bf16 v[58:61], v[148:151], v[156:159], v[58:61]
	v_mfma_f32_16x16x32_bf16 v[54:57], v[138:141], v[164:167], v[54:57]
	v_mfma_f32_16x16x32_bf16 v[46:49], v[148:151], v[164:167], v[46:49]
	v_mfma_f32_16x16x32_bf16 v[38:41], v[138:141], v[172:175], v[38:41]
	v_mfma_f32_16x16x32_bf16 v[30:33], v[148:151], v[172:175], v[30:33]
	v_mfma_f32_16x16x32_bf16 v[22:25], v[138:141], v[180:183], v[22:25]
	v_mfma_f32_16x16x32_bf16 v[14:17], v[148:151], v[180:183], v[14:17]
	v_mfma_f32_16x16x32_bf16 v[62:65], v[142:145], v[160:163], v[62:65]
	v_mfma_f32_16x16x32_bf16 v[58:61], v[152:155], v[160:163], v[58:61]
	v_mfma_f32_16x16x32_bf16 v[54:57], v[142:145], v[168:171], v[54:57]
	v_mfma_f32_16x16x32_bf16 v[46:49], v[152:155], v[168:171], v[46:49]
	v_mfma_f32_16x16x32_bf16 v[38:41], v[142:145], v[176:179], v[38:41]
	v_mfma_f32_16x16x32_bf16 v[30:33], v[152:155], v[176:179], v[30:33]
	v_mfma_f32_16x16x32_bf16 v[22:25], v[142:145], v[184:187], v[22:25]
	v_mfma_f32_16x16x32_bf16 v[14:17], v[152:155], v[184:187], v[14:17]
	s_barrier
	s_add_i32 s7, s11, s57
	v_lshl_add_u64 v[138:139], v[132:133], 0, s[16:17]
	s_mov_b32 m0, s7
	v_lshl_add_u64 v[132:133], v[132:133], 0, s[80:81]
	global_load_lds_dwordx4 v[138:139], off
	s_add_i32 m0, s7, 0x2000
	s_nop 0
	global_load_lds_dwordx4 v[132:133], off
	s_waitcnt vmcnt(6)
	s_add_i32 s6, s6, 2
	s_add_u32 s8, s8, 0x100
	s_addc_u32 s9, s9, 0
	s_add_u32 s50, s50, 0x100
	s_addc_u32 s51, s51, 0
	s_cmp_gt_u32 s6, 29
	s_cbranch_scc0 .LBB0_97
	s_barrier
	v_mfma_f32_16x16x32_bf16 v[50:53], v[188:191], v[156:159], v[50:53]
	v_mfma_f32_16x16x32_bf16 v[42:45], v[196:199], v[156:159], v[42:45]
	v_mfma_f32_16x16x32_bf16 v[34:37], v[188:191], v[164:167], v[34:37]
	v_mfma_f32_16x16x32_bf16 v[26:29], v[196:199], v[164:167], v[26:29]
	v_mfma_f32_16x16x32_bf16 v[18:21], v[188:191], v[172:175], v[18:21]
	v_mfma_f32_16x16x32_bf16 v[10:13], v[196:199], v[172:175], v[10:13]
	v_mfma_f32_16x16x32_bf16 v[6:9], v[188:191], v[180:183], v[6:9]
	v_mfma_f32_16x16x32_bf16 v[2:5], v[196:199], v[180:183], v[2:5]
	v_mfma_f32_16x16x32_bf16 v[50:53], v[192:195], v[160:163], v[50:53]
	v_mfma_f32_16x16x32_bf16 v[42:45], v[200:203], v[160:163], v[42:45]
	v_mfma_f32_16x16x32_bf16 v[34:37], v[192:195], v[168:171], v[34:37]
	v_mfma_f32_16x16x32_bf16 v[26:29], v[200:203], v[168:171], v[26:29]
	v_mfma_f32_16x16x32_bf16 v[18:21], v[192:195], v[176:179], v[18:21]
	v_mfma_f32_16x16x32_bf16 v[10:13], v[200:203], v[176:179], v[10:13]
	v_mfma_f32_16x16x32_bf16 v[6:9], v[192:195], v[184:187], v[6:9]
	v_mfma_f32_16x16x32_bf16 v[2:5], v[200:203], v[184:187], v[2:5]
	s_barrier
	v_mov_b32_e32 v137, v134
	s_lshl_b32 s6, s88, 8
	v_ashrrev_i32_e32 v132, 2, v137
	s_or_b32 s6, s6, s84
	v_and_b32_e32 v132, -4, v132
	v_add_u32_e32 v132, s6, v132
	s_lshl_b32 s6, s48, 8
	s_add_i32 s6, s6, s63
	v_and_or_b32 v188, v137, 15, s6
	v_ashrrev_i32_e32 v189, 31, v188
	v_ashrrev_i32_e32 v133, 31, v132
	v_lshlrev_b64 v[206:207], 13, v[188:189]
	v_or_b32_e32 v156, 16, v188
	v_or_b32_e32 v172, 32, v188
	v_or_b32_e32 v188, 48, v188
	v_lshlrev_b64 v[132:133], 2, v[132:133]
	v_ashrrev_i32_e32 v157, 31, v156
	v_ashrrev_i32_e32 v173, 31, v172
	v_ashrrev_i32_e32 v189, 31, v188
	v_lshl_add_u64 v[204:205], s[4:5], 0, v[132:133]
	v_lshlrev_b64 v[208:209], 13, v[156:157]
	v_lshlrev_b64 v[210:211], 13, v[172:173]
	v_lshlrev_b64 v[212:213], 13, v[188:189]
	v_lshl_add_u64 v[152:153], v[204:205], 0, v[206:207]
	v_lshl_add_u64 v[168:169], v[204:205], 0, v[208:209]
	v_lshl_add_u64 v[184:185], v[204:205], 0, v[210:211]
	v_lshl_add_u64 v[200:201], v[204:205], 0, v[212:213]
	global_load_dwordx4 v[138:141], v[152:153], off
	global_load_dwordx4 v[142:145], v[152:153], off offset:64
	global_load_dwordx4 v[148:151], v[152:153], off offset:512
	s_nop 0
	global_load_dwordx4 v[152:155], v[152:153], off offset:576
	s_nop 0
	global_load_dwordx4 v[156:159], v[168:169], off
	global_load_dwordx4 v[160:163], v[168:169], off offset:64
	global_load_dwordx4 v[164:167], v[168:169], off offset:512
	s_nop 0
	global_load_dwordx4 v[168:171], v[168:169], off offset:576
	s_nop 0
	global_load_dwordx4 v[172:175], v[184:185], off
	global_load_dwordx4 v[176:179], v[184:185], off offset:64
	global_load_dwordx4 v[180:183], v[184:185], off offset:512
	s_nop 0
	global_load_dwordx4 v[184:187], v[184:185], off offset:576
	s_nop 0
	global_load_dwordx4 v[188:191], v[200:201], off
	global_load_dwordx4 v[192:195], v[200:201], off offset:64
	global_load_dwordx4 v[196:199], v[200:201], off offset:512
	s_nop 0
	global_load_dwordx4 v[200:203], v[200:201], off offset:576
	s_waitcnt vmcnt(0) lgkmcnt(0)
	v_pk_add_f32 v[126:127], v[126:127], v[138:139]
	v_lshl_add_u64 v[138:139], s[4:5], 0, v[206:207]
	v_lshl_add_u64 v[138:139], v[138:139], 0, v[132:133]
	v_pk_add_f32 v[116:117], v[116:117], v[150:151]
	v_pk_add_f32 v[114:115], v[114:115], v[148:149]
	global_store_dwordx4 v[138:139], v[114:117], off offset:512
	v_pk_add_f32 v[100:101], v[100:101], v[166:167]
	v_pk_add_f32 v[98:99], v[98:99], v[164:165]
	v_lshl_add_u64 v[114:115], s[4:5], 0, v[208:209]
	v_lshl_add_u64 v[114:115], v[114:115], 0, v[132:133]
	global_store_dwordx4 v[114:115], v[98:101], off offset:512
	v_pk_add_f32 v[84:85], v[84:85], v[182:183]
	v_pk_add_f32 v[82:83], v[82:83], v[180:181]
	v_lshl_add_u64 v[98:99], s[4:5], 0, v[210:211]
	v_lshl_add_u64 v[98:99], v[98:99], 0, v[132:133]
	v_pk_add_f32 v[108:109], v[108:109], v[154:155]
	v_pk_add_f32 v[106:107], v[106:107], v[152:153]
	v_pk_add_f32 v[92:93], v[92:93], v[170:171]
	v_pk_add_f32 v[90:91], v[90:91], v[168:169]
	global_store_dwordx4 v[98:99], v[82:85], off offset:512
	v_pk_add_f32 v[76:77], v[76:77], v[186:187]
	v_pk_add_f32 v[74:75], v[74:75], v[184:185]
	v_lshl_add_u64 v[82:83], s[4:5], 0, v[212:213]
	global_store_dwordx4 v[138:139], v[106:109], off offset:576
	global_store_dwordx4 v[114:115], v[90:93], off offset:576
	global_store_dwordx4 v[98:99], v[74:77], off offset:576
	v_pk_add_f32 v[108:109], v[120:121], v[158:159]
	v_pk_add_f32 v[106:107], v[118:119], v[156:157]
	v_pk_add_f32 v[92:93], v[104:105], v[174:175]
	v_pk_add_f32 v[90:91], v[102:103], v[172:173]
	v_pk_add_f32 v[76:77], v[88:89], v[190:191]
	v_pk_add_f32 v[74:75], v[86:87], v[188:189]
	v_lshl_add_u64 v[82:83], v[82:83], 0, v[132:133]
	v_pk_add_f32 v[128:129], v[128:129], v[140:141]
	v_pk_add_f32 v[124:125], v[124:125], v[144:145]
	v_pk_add_f32 v[122:123], v[122:123], v[142:143]
	global_store_dwordx4 v[114:115], v[106:109], off
	global_store_dwordx4 v[98:99], v[90:93], off
	global_store_dwordx4 v[82:83], v[74:77], off
	v_pk_add_f32 v[108:109], v[112:113], v[162:163]
	v_pk_add_f32 v[106:107], v[110:111], v[160:161]
	v_pk_add_f32 v[92:93], v[96:97], v[178:179]
	v_pk_add_f32 v[90:91], v[94:95], v[176:177]
	v_pk_add_f32 v[76:77], v[80:81], v[194:195]
	v_pk_add_f32 v[74:75], v[78:79], v[192:193]
	v_pk_add_f32 v[72:73], v[72:73], v[198:199]
	v_pk_add_f32 v[70:71], v[70:71], v[196:197]
	v_pk_add_f32 v[68:69], v[68:69], v[202:203]
	v_pk_add_f32 v[66:67], v[66:67], v[200:201]
	global_store_dwordx4 v[138:139], v[126:129], off
	global_store_dwordx4 v[138:139], v[122:125], off offset:64
	global_store_dwordx4 v[114:115], v[106:109], off offset:64
	global_store_dwordx4 v[98:99], v[90:93], off offset:64
	global_store_dwordx4 v[82:83], v[74:77], off offset:64
	global_store_dwordx4 v[82:83], v[70:73], off offset:512
	global_store_dwordx4 v[82:83], v[66:69], off offset:576
	s_mov_b64 s[6:7], 0x120000
	v_lshl_add_u64 v[140:141], v[206:207], 0, s[6:7]
	s_mov_b64 s[6:7], 0x140000
	v_lshl_add_u64 v[138:139], v[206:207], 0, s[0:1]
	v_lshl_add_u64 v[142:143], v[206:207], 0, s[6:7]
	v_lshl_add_u64 v[144:145], v[206:207], 0, s[28:29]
	v_lshl_add_u64 v[78:79], v[204:205], 0, v[138:139]
	v_lshl_add_u64 v[94:95], v[204:205], 0, v[140:141]
	v_lshl_add_u64 v[110:111], v[204:205], 0, v[142:143]
	v_lshl_add_u64 v[126:127], v[204:205], 0, v[144:145]
	global_load_dwordx4 v[66:69], v[78:79], off
	global_load_dwordx4 v[70:73], v[78:79], off offset:64
	global_load_dwordx4 v[74:77], v[78:79], off offset:512
	s_nop 0
	global_load_dwordx4 v[78:81], v[78:79], off offset:576
	s_nop 0
	global_load_dwordx4 v[82:85], v[94:95], off
	global_load_dwordx4 v[86:89], v[94:95], off offset:64
	global_load_dwordx4 v[90:93], v[94:95], off offset:512
	s_nop 0
	global_load_dwordx4 v[94:97], v[94:95], off offset:576
	s_nop 0
	global_load_dwordx4 v[98:101], v[110:111], off
	global_load_dwordx4 v[102:105], v[110:111], off offset:64
	global_load_dwordx4 v[106:109], v[110:111], off offset:512
	s_nop 0
	global_load_dwordx4 v[110:113], v[110:111], off offset:576
	s_nop 0
	global_load_dwordx4 v[114:117], v[126:127], off
	global_load_dwordx4 v[118:121], v[126:127], off offset:64
	global_load_dwordx4 v[122:125], v[126:127], off offset:512
	s_nop 0
	global_load_dwordx4 v[126:129], v[126:127], off offset:576
	s_waitcnt vmcnt(0) lgkmcnt(0)
	v_pk_add_f32 v[62:63], v[62:63], v[66:67]
	v_lshl_add_u64 v[66:67], s[4:5], 0, v[138:139]
	v_lshl_add_u64 v[66:67], v[66:67], 0, v[132:133]
	v_pk_add_f32 v[52:53], v[52:53], v[76:77]
	v_pk_add_f32 v[50:51], v[50:51], v[74:75]
	global_store_dwordx4 v[66:67], v[50:53], off offset:512
	v_pk_add_f32 v[36:37], v[36:37], v[92:93]
	v_pk_add_f32 v[34:35], v[34:35], v[90:91]
	v_lshl_add_u64 v[50:51], s[4:5], 0, v[140:141]
	v_lshl_add_u64 v[50:51], v[50:51], 0, v[132:133]
	global_store_dwordx4 v[50:51], v[34:37], off offset:512
	v_pk_add_f32 v[20:21], v[20:21], v[108:109]
	v_pk_add_f32 v[18:19], v[18:19], v[106:107]
	v_lshl_add_u64 v[34:35], s[4:5], 0, v[142:143]
	v_lshl_add_u64 v[34:35], v[34:35], 0, v[132:133]
	v_pk_add_f32 v[44:45], v[44:45], v[80:81]
	v_pk_add_f32 v[42:43], v[42:43], v[78:79]
	v_pk_add_f32 v[28:29], v[28:29], v[96:97]
	v_pk_add_f32 v[26:27], v[26:27], v[94:95]
	global_store_dwordx4 v[34:35], v[18:21], off offset:512
	v_pk_add_f32 v[12:13], v[12:13], v[112:113]
	v_pk_add_f32 v[10:11], v[10:11], v[110:111]
	v_lshl_add_u64 v[18:19], s[4:5], 0, v[144:145]
	global_store_dwordx4 v[66:67], v[42:45], off offset:576
	global_store_dwordx4 v[50:51], v[26:29], off offset:576
	global_store_dwordx4 v[34:35], v[10:13], off offset:576
	v_pk_add_f32 v[44:45], v[56:57], v[84:85]
	v_pk_add_f32 v[42:43], v[54:55], v[82:83]
	v_pk_add_f32 v[28:29], v[40:41], v[100:101]
	v_pk_add_f32 v[26:27], v[38:39], v[98:99]
	v_pk_add_f32 v[12:13], v[24:25], v[116:117]
	v_pk_add_f32 v[10:11], v[22:23], v[114:115]
	v_lshl_add_u64 v[18:19], v[18:19], 0, v[132:133]
	v_pk_add_f32 v[64:65], v[64:65], v[68:69]
	v_pk_add_f32 v[60:61], v[60:61], v[72:73]
	v_pk_add_f32 v[58:59], v[58:59], v[70:71]
	global_store_dwordx4 v[50:51], v[42:45], off
	global_store_dwordx4 v[34:35], v[26:29], off
	global_store_dwordx4 v[18:19], v[10:13], off
	v_pk_add_f32 v[44:45], v[48:49], v[88:89]
	v_pk_add_f32 v[42:43], v[46:47], v[86:87]
	v_pk_add_f32 v[28:29], v[32:33], v[104:105]
	v_pk_add_f32 v[26:27], v[30:31], v[102:103]
	v_pk_add_f32 v[12:13], v[16:17], v[120:121]
	v_pk_add_f32 v[10:11], v[14:15], v[118:119]
	v_pk_add_f32 v[8:9], v[8:9], v[124:125]
	v_pk_add_f32 v[6:7], v[6:7], v[122:123]
	v_pk_add_f32 v[4:5], v[4:5], v[128:129]
	v_pk_add_f32 v[2:3], v[2:3], v[126:127]
	global_store_dwordx4 v[66:67], v[62:65], off
	global_store_dwordx4 v[66:67], v[58:61], off offset:64
	global_store_dwordx4 v[50:51], v[42:45], off offset:64
	global_store_dwordx4 v[34:35], v[26:29], off offset:64
	global_store_dwordx4 v[18:19], v[10:13], off offset:64
	global_store_dwordx4 v[18:19], v[6:9], off offset:512
	global_store_dwordx4 v[18:19], v[2:5], off offset:576
	v_readlane_b32 s50, v255, 28
	s_and_b64 vcc, exec, s[40:41]
	s_mov_b32 s48, s42
	s_mov_b32 s88, s10
	s_mov_b64 s[8:9], s[46:47]
	s_mov_b64 s[6:7], s[44:45]
	v_readlane_b32 s51, v255, 29
	s_movk_i32 s91, 0x60
	s_mov_b32 s78, 0x2a000000
	s_mov_b32 s79, 0x3fffe
	s_mov_b32 s90, 0xc0000
	s_cbranch_vccz .LBB0_90
	s_waitcnt vmcnt(0)
	s_cmpk_gt_u32 s52, 0xff
	s_cbranch_scc1 .LBB0_101
	s_barrier

.LBB0_229:
	s_add_i32 s11, 0, 0x10000
	v_add_u32_e32 v206, s11, v148
	ds_read_b128 v[4:7], v206
	ds_read_b128 v[8:11], v206 offset:1024
	ds_read_b128 v[12:15], v206 offset:2048
	ds_read_b128 v[16:19], v206 offset:3072
	v_lshl_add_u64 v[2:3], s[8:9], 0, v[138:139]
	s_add_i32 s10, s57, 0xc000
	v_lshl_add_u64 v[52:53], v[2:3], 0, s[72:73]
	s_mov_b32 m0, s10
	s_mov_b64 vcc, 0x18080
	s_add_i32 s8, s57, 0xe000
	ds_read_b128 v[20:23], v149
	ds_read_b128 v[24:27], v149 offset:1024
	ds_read_b128 v[28:31], v149 offset:2048
	ds_read_b128 v[32:35], v149 offset:3072
	ds_read_b128 v[36:39], v149 offset:4096
	ds_read_b128 v[40:43], v149 offset:5120
	ds_read_b128 v[44:47], v149 offset:6144
	ds_read_b128 v[48:51], v149 offset:7168
	global_load_lds_dwordx4 v[52:53], off
	v_lshl_add_u64 v[52:53], v[2:3], 0, vcc
	s_mov_b32 m0, s8
	s_nop 0
	global_load_lds_dwordx4 v[52:53], off
	s_waitcnt lgkmcnt(8)
	s_barrier
	s_waitcnt lgkmcnt(0)
	v_mfma_f32_16x16x32_bf16 v[52:55], v[4:7], v[20:23], 0
	v_mfma_f32_16x16x32_bf16 v[56:59], v[12:15], v[20:23], 0
	v_mfma_f32_16x16x32_bf16 v[60:63], v[4:7], v[28:31], 0
	v_mfma_f32_16x16x32_bf16 v[64:67], v[12:15], v[28:31], 0
	v_mfma_f32_16x16x32_bf16 v[68:71], v[4:7], v[36:39], 0
	v_mfma_f32_16x16x32_bf16 v[72:75], v[12:15], v[36:39], 0
	v_mfma_f32_16x16x32_bf16 v[80:83], v[12:15], v[44:47], 0
	v_mfma_f32_16x16x32_bf16 v[52:55], v[8:11], v[24:27], v[52:55]
	v_mfma_f32_16x16x32_bf16 v[56:59], v[16:19], v[24:27], v[56:59]
	v_mfma_f32_16x16x32_bf16 v[60:63], v[8:11], v[32:35], v[60:63]
	v_mfma_f32_16x16x32_bf16 v[64:67], v[16:19], v[32:35], v[64:67]
	v_mfma_f32_16x16x32_bf16 v[68:71], v[8:11], v[40:43], v[68:71]
	v_mfma_f32_16x16x32_bf16 v[72:75], v[16:19], v[40:43], v[72:75]
	v_mfma_f32_16x16x32_bf16 v[76:79], v[4:7], v[44:47], 0
	v_mfma_f32_16x16x32_bf16 v[80:83], v[16:19], v[48:51], v[80:83]
	v_mfma_f32_16x16x32_bf16 v[76:79], v[8:11], v[48:51], v[76:79]
	s_barrier
	s_add_i32 s9, 0, 0x14000
	v_lshl_add_u64 v[136:137], s[6:7], 0, v[0:1]
	s_mov_b64 s[40:41], 0x100
	s_add_i32 s11, s11, s56
	v_add_u32_e32 v207, s9, v148
	v_lshl_add_u64 v[100:101], v[136:137], 0, s[40:41]
	s_mov_b32 m0, s11
	s_mov_b64 s[78:79], 0x8100
	s_add_i32 s6, s11, 0x2000
	ds_read_b128 v[84:87], v207
	ds_read_b128 v[88:91], v207 offset:1024
	ds_read_b128 v[92:95], v207 offset:2048
	ds_read_b128 v[96:99], v207 offset:3072
	global_load_lds_dwordx4 v[100:101], off
	v_lshl_add_u64 v[100:101], v[136:137], 0, s[78:79]
	s_mov_b32 m0, s6
	s_nop 0
	global_load_lds_dwordx4 v[100:101], off
	s_waitcnt lgkmcnt(0)
	s_barrier
	v_mfma_f32_16x16x32_bf16 v[100:103], v[84:87], v[20:23], 0
	v_mfma_f32_16x16x32_bf16 v[20:23], v[92:95], v[20:23], 0
	v_mfma_f32_16x16x32_bf16 v[100:103], v[88:91], v[24:27], v[100:103]
	v_mfma_f32_16x16x32_bf16 v[20:23], v[96:99], v[24:27], v[20:23]
	v_mfma_f32_16x16x32_bf16 v[24:27], v[84:87], v[28:31], 0
	v_mfma_f32_16x16x32_bf16 v[28:31], v[92:95], v[28:31], 0
	v_mfma_f32_16x16x32_bf16 v[24:27], v[88:91], v[32:35], v[24:27]
	v_mfma_f32_16x16x32_bf16 v[28:31], v[96:99], v[32:35], v[28:31]
	v_mfma_f32_16x16x32_bf16 v[32:35], v[84:87], v[36:39], 0
	v_mfma_f32_16x16x32_bf16 v[36:39], v[92:95], v[36:39], 0
	v_mfma_f32_16x16x32_bf16 v[32:35], v[88:91], v[40:43], v[32:35]
	v_mfma_f32_16x16x32_bf16 v[36:39], v[96:99], v[40:43], v[36:39]
	v_mfma_f32_16x16x32_bf16 v[40:43], v[84:87], v[44:47], 0
	v_mfma_f32_16x16x32_bf16 v[44:47], v[92:95], v[44:47], 0
	v_mfma_f32_16x16x32_bf16 v[40:43], v[88:91], v[48:51], v[40:43]
	v_mfma_f32_16x16x32_bf16 v[44:47], v[96:99], v[48:51], v[44:47]
	s_barrier
	s_mov_b32 m0, s57
	v_lshl_add_u64 v[132:133], v[2:3], 0, s[40:41]
	ds_read_b128 v[48:51], v149 offset:16384
	ds_read_b128 v[104:107], v149 offset:17408
	ds_read_b128 v[108:111], v149 offset:18432
	ds_read_b128 v[112:115], v149 offset:19456
	ds_read_b128 v[116:119], v149 offset:20480
	ds_read_b128 v[120:123], v149 offset:21504
	ds_read_b128 v[124:127], v149 offset:22528
	ds_read_b128 v[128:131], v149 offset:23552
	global_load_lds_dwordx4 v[132:133], off
	v_lshl_add_u64 v[132:133], v[2:3], 0, s[78:79]
	s_mov_b32 m0, s58
	s_nop 0
	global_load_lds_dwordx4 v[132:133], off
	s_waitcnt lgkmcnt(0)
	s_barrier
	v_mfma_f32_16x16x32_bf16 v[132:135], v[4:7], v[48:51], 0
	v_mfma_f32_16x16x32_bf16 v[150:153], v[4:7], v[108:111], 0
	v_mfma_f32_16x16x32_bf16 v[158:161], v[4:7], v[116:119], 0
	v_mfma_f32_16x16x32_bf16 v[4:7], v[4:7], v[124:127], 0
	v_mfma_f32_16x16x32_bf16 v[132:135], v[8:11], v[104:107], v[132:135]
	v_mfma_f32_16x16x32_bf16 v[150:153], v[8:11], v[112:115], v[150:153]
	v_mfma_f32_16x16x32_bf16 v[158:161], v[8:11], v[120:123], v[158:161]
	v_mfma_f32_16x16x32_bf16 v[4:7], v[8:11], v[128:131], v[4:7]
	v_mfma_f32_16x16x32_bf16 v[8:11], v[12:15], v[124:127], 0
	v_mfma_f32_16x16x32_bf16 v[140:143], v[12:15], v[48:51], 0
	v_mfma_f32_16x16x32_bf16 v[154:157], v[12:15], v[108:111], 0
	v_mfma_f32_16x16x32_bf16 v[162:165], v[12:15], v[116:119], 0
	v_mfma_f32_16x16x32_bf16 v[8:11], v[16:19], v[128:131], v[8:11]
	v_mfma_f32_16x16x32_bf16 v[140:143], v[16:19], v[104:107], v[140:143]
	v_mfma_f32_16x16x32_bf16 v[154:157], v[16:19], v[112:115], v[154:157]
	v_mfma_f32_16x16x32_bf16 v[162:165], v[16:19], v[120:123], v[162:165]
	s_barrier
	s_mov_b64 s[40:41], 0x10100
	s_add_i32 s9, s9, s56
	v_lshl_add_u64 v[12:13], v[136:137], 0, s[40:41]
	s_mov_b32 m0, s9
	s_mov_b64 s[78:79], 0x18100
	s_add_i32 s7, s9, 0x2000
	global_load_lds_dwordx4 v[12:13], off
	v_lshl_add_u64 v[12:13], v[136:137], 0, s[78:79]
	s_mov_b32 m0, s7
	s_nop 0
	global_load_lds_dwordx4 v[12:13], off
	s_waitcnt vmcnt(6)
	s_barrier
	v_mfma_f32_16x16x32_bf16 v[12:15], v[84:87], v[48:51], 0
	v_mfma_f32_16x16x32_bf16 v[16:19], v[92:95], v[48:51], 0
	v_mfma_f32_16x16x32_bf16 v[12:15], v[88:91], v[104:107], v[12:15]
	v_mfma_f32_16x16x32_bf16 v[16:19], v[96:99], v[104:107], v[16:19]
	v_mfma_f32_16x16x32_bf16 v[48:51], v[84:87], v[108:111], 0
	v_mfma_f32_16x16x32_bf16 v[104:107], v[92:95], v[108:111], 0
	v_mfma_f32_16x16x32_bf16 v[108:111], v[84:87], v[116:119], 0
	v_mfma_f32_16x16x32_bf16 v[84:87], v[84:87], v[124:127], 0
	v_mfma_f32_16x16x32_bf16 v[48:51], v[88:91], v[112:115], v[48:51]
	v_mfma_f32_16x16x32_bf16 v[104:107], v[96:99], v[112:115], v[104:107]
	v_mfma_f32_16x16x32_bf16 v[108:111], v[88:91], v[120:123], v[108:111]
	v_mfma_f32_16x16x32_bf16 v[112:115], v[92:95], v[116:119], 0
	v_mfma_f32_16x16x32_bf16 v[84:87], v[88:91], v[128:131], v[84:87]
	v_mfma_f32_16x16x32_bf16 v[88:91], v[92:95], v[124:127], 0
	v_mfma_f32_16x16x32_bf16 v[112:115], v[96:99], v[120:123], v[112:115]
	v_mfma_f32_16x16x32_bf16 v[88:91], v[96:99], v[128:131], v[88:91]
	s_barrier
	s_add_i32 s53, 0, 0x18000
	v_add_u32_e32 v222, s53, v148
	ds_read_b128 v[92:95], v222
	ds_read_b128 v[96:99], v222 offset:1024
	ds_read_b128 v[116:119], v222 offset:2048
	ds_read_b128 v[120:123], v222 offset:3072
	s_mov_b32 m0, s59
	v_lshl_add_u64 v[144:145], v[2:3], 0, s[40:41]
	ds_read_b128 v[124:127], v149 offset:32768
	ds_read_b128 v[128:131], v149 offset:33792
	ds_read_b128 v[166:169], v149 offset:34816
	ds_read_b128 v[170:173], v149 offset:35840
	ds_read_b128 v[174:177], v149 offset:36864
	ds_read_b128 v[178:181], v149 offset:37888
	ds_read_b128 v[182:185], v149 offset:38912
	ds_read_b128 v[186:189], v149 offset:39936
	global_load_lds_dwordx4 v[144:145], off
	v_lshl_add_u64 v[144:145], v[2:3], 0, s[78:79]
	s_mov_b32 m0, s62
	s_nop 0
	global_load_lds_dwordx4 v[144:145], off
	s_waitcnt lgkmcnt(8)
	s_barrier
	s_waitcnt lgkmcnt(0)
	v_mfma_f32_16x16x32_bf16 v[52:55], v[92:95], v[124:127], v[52:55]
	v_mfma_f32_16x16x32_bf16 v[56:59], v[116:119], v[124:127], v[56:59]
	v_mfma_f32_16x16x32_bf16 v[60:63], v[92:95], v[166:169], v[60:63]
	v_mfma_f32_16x16x32_bf16 v[64:67], v[116:119], v[166:169], v[64:67]
	v_mfma_f32_16x16x32_bf16 v[68:71], v[92:95], v[174:177], v[68:71]
	v_mfma_f32_16x16x32_bf16 v[72:75], v[116:119], v[174:177], v[72:75]
	v_mfma_f32_16x16x32_bf16 v[80:83], v[116:119], v[182:185], v[80:83]
	v_mfma_f32_16x16x32_bf16 v[52:55], v[96:99], v[128:131], v[52:55]
	v_mfma_f32_16x16x32_bf16 v[56:59], v[120:123], v[128:131], v[56:59]
	v_mfma_f32_16x16x32_bf16 v[60:63], v[96:99], v[170:173], v[60:63]
	v_mfma_f32_16x16x32_bf16 v[64:67], v[120:123], v[170:173], v[64:67]
	v_mfma_f32_16x16x32_bf16 v[68:71], v[96:99], v[178:181], v[68:71]
	v_mfma_f32_16x16x32_bf16 v[72:75], v[120:123], v[178:181], v[72:75]
	v_mfma_f32_16x16x32_bf16 v[76:79], v[92:95], v[182:185], v[76:79]
	v_mfma_f32_16x16x32_bf16 v[80:83], v[120:123], v[186:189], v[80:83]
	v_mfma_f32_16x16x32_bf16 v[76:79], v[96:99], v[186:189], v[76:79]
	s_barrier
	s_add_i32 s41, 0, 0x1c000
	s_mov_b64 s[78:79], 0x180
	s_add_i32 s53, s53, s56
	v_add_u32_e32 v226, s41, v148
	v_lshl_add_u64 v[144:145], v[136:137], 0, s[78:79]
	s_mov_b32 m0, s53
	s_mov_b64 s[0:1], 0x8180
	s_add_i32 s22, s53, 0x2000
	ds_read_b128 v[190:193], v226
	ds_read_b128 v[194:197], v226 offset:1024
	ds_read_b128 v[198:201], v226 offset:2048
	ds_read_b128 v[202:205], v226 offset:3072
	global_load_lds_dwordx4 v[144:145], off
	v_lshl_add_u64 v[144:145], v[136:137], 0, s[0:1]
	s_mov_b32 m0, s22
	s_nop 0
	global_load_lds_dwordx4 v[144:145], off
	s_waitcnt lgkmcnt(0)
	s_barrier
	v_mfma_f32_16x16x32_bf16 v[100:103], v[190:193], v[124:127], v[100:103]
	v_mfma_f32_16x16x32_bf16 v[20:23], v[198:201], v[124:127], v[20:23]
	v_mfma_f32_16x16x32_bf16 v[24:27], v[190:193], v[166:169], v[24:27]
	v_mfma_f32_16x16x32_bf16 v[28:31], v[198:201], v[166:169], v[28:31]
	v_mfma_f32_16x16x32_bf16 v[32:35], v[190:193], v[174:177], v[32:35]
	v_mfma_f32_16x16x32_bf16 v[36:39], v[198:201], v[174:177], v[36:39]
	v_mfma_f32_16x16x32_bf16 v[40:43], v[190:193], v[182:185], v[40:43]
	v_mfma_f32_16x16x32_bf16 v[44:47], v[198:201], v[182:185], v[44:47]
	v_mfma_f32_16x16x32_bf16 v[100:103], v[194:197], v[128:131], v[100:103]
	v_mfma_f32_16x16x32_bf16 v[20:23], v[202:205], v[128:131], v[20:23]
	v_mfma_f32_16x16x32_bf16 v[24:27], v[194:197], v[170:173], v[24:27]
	v_mfma_f32_16x16x32_bf16 v[28:31], v[202:205], v[170:173], v[28:31]
	v_mfma_f32_16x16x32_bf16 v[32:35], v[194:197], v[178:181], v[32:35]
	v_mfma_f32_16x16x32_bf16 v[36:39], v[202:205], v[178:181], v[36:39]
	v_mfma_f32_16x16x32_bf16 v[40:43], v[194:197], v[186:189], v[40:43]
	v_mfma_f32_16x16x32_bf16 v[44:47], v[202:205], v[186:189], v[44:47]
	s_barrier
	s_mov_b32 m0, s85
	v_lshl_add_u64 v[144:145], v[2:3], 0, s[78:79]
	ds_read_b128 v[124:127], v149 offset:49152
	ds_read_b128 v[128:131], v149 offset:50176
	ds_read_b128 v[166:169], v149 offset:51200
	ds_read_b128 v[170:173], v149 offset:52224
	ds_read_b128 v[174:177], v149 offset:53248
	ds_read_b128 v[178:181], v149 offset:54272
	ds_read_b128 v[182:185], v149 offset:55296
	ds_read_b128 v[186:189], v149 offset:56320
	global_load_lds_dwordx4 v[144:145], off
	v_lshl_add_u64 v[144:145], v[2:3], 0, s[0:1]
	s_mov_b32 m0, s86
	s_nop 0
	global_load_lds_dwordx4 v[144:145], off
	s_waitcnt lgkmcnt(0)
	s_barrier
	v_mfma_f32_16x16x32_bf16 v[132:135], v[92:95], v[124:127], v[132:135]
	v_mfma_f32_16x16x32_bf16 v[150:153], v[92:95], v[166:169], v[150:153]
	v_mfma_f32_16x16x32_bf16 v[4:7], v[92:95], v[182:185], v[4:7]
	v_mfma_f32_16x16x32_bf16 v[8:11], v[116:119], v[182:185], v[8:11]
	v_mfma_f32_16x16x32_bf16 v[132:135], v[96:99], v[128:131], v[132:135]
	v_mfma_f32_16x16x32_bf16 v[140:143], v[116:119], v[124:127], v[140:143]
	v_mfma_f32_16x16x32_bf16 v[150:153], v[96:99], v[170:173], v[150:153]
	v_mfma_f32_16x16x32_bf16 v[154:157], v[116:119], v[166:169], v[154:157]
	v_mfma_f32_16x16x32_bf16 v[158:161], v[92:95], v[174:177], v[158:161]
	v_mfma_f32_16x16x32_bf16 v[162:165], v[116:119], v[174:177], v[162:165]
	v_mfma_f32_16x16x32_bf16 v[4:7], v[96:99], v[186:189], v[4:7]
	v_mfma_f32_16x16x32_bf16 v[8:11], v[120:123], v[186:189], v[8:11]
	v_mfma_f32_16x16x32_bf16 v[140:143], v[120:123], v[128:131], v[140:143]
	v_mfma_f32_16x16x32_bf16 v[154:157], v[120:123], v[170:173], v[154:157]
	v_mfma_f32_16x16x32_bf16 v[158:161], v[96:99], v[178:181], v[158:161]
	v_mfma_f32_16x16x32_bf16 v[162:165], v[120:123], v[178:181], v[162:165]
	s_barrier
	s_mov_b64 s[0:1], 0x10180
	s_add_i32 s41, s41, s56
	v_lshl_add_u64 v[92:93], v[136:137], 0, s[0:1]
	s_mov_b32 m0, s41
	s_mov_b64 s[78:79], 0x18180
	s_add_i32 s40, s41, 0x2000
	global_load_lds_dwordx4 v[92:93], off
	v_lshl_add_u64 v[92:93], v[136:137], 0, s[78:79]
	s_mov_b32 m0, s40
	s_nop 0
	global_load_lds_dwordx4 v[92:93], off
	s_waitcnt vmcnt(6)
	s_barrier
	v_mfma_f32_16x16x32_bf16 v[12:15], v[190:193], v[124:127], v[12:15]
	v_mfma_f32_16x16x32_bf16 v[16:19], v[198:201], v[124:127], v[16:19]
	v_mfma_f32_16x16x32_bf16 v[48:51], v[190:193], v[166:169], v[48:51]
	v_mfma_f32_16x16x32_bf16 v[92:95], v[198:201], v[166:169], v[104:107]
	v_mfma_f32_16x16x32_bf16 v[96:99], v[190:193], v[174:177], v[108:111]
	v_mfma_f32_16x16x32_bf16 v[104:107], v[198:201], v[174:177], v[112:115]
	v_mfma_f32_16x16x32_bf16 v[84:87], v[190:193], v[182:185], v[84:87]
	v_mfma_f32_16x16x32_bf16 v[88:91], v[198:201], v[182:185], v[88:91]
	v_mfma_f32_16x16x32_bf16 v[12:15], v[194:197], v[128:131], v[12:15]
	v_mfma_f32_16x16x32_bf16 v[16:19], v[202:205], v[128:131], v[16:19]
	v_mfma_f32_16x16x32_bf16 v[48:51], v[194:197], v[170:173], v[48:51]
	v_mfma_f32_16x16x32_bf16 v[92:95], v[202:205], v[170:173], v[92:95]
	v_mfma_f32_16x16x32_bf16 v[96:99], v[194:197], v[178:181], v[96:99]
	v_mfma_f32_16x16x32_bf16 v[104:107], v[202:205], v[178:181], v[104:107]
	v_mfma_f32_16x16x32_bf16 v[84:87], v[194:197], v[186:189], v[84:87]
	v_mfma_f32_16x16x32_bf16 v[88:91], v[202:205], v[186:189], v[88:91]
	s_barrier
	ds_read_b128 v[108:111], v206
	ds_read_b128 v[112:115], v206 offset:1024
	ds_read_b128 v[116:119], v206 offset:2048
	ds_read_b128 v[120:123], v206 offset:3072
	s_mov_b32 m0, s10
	v_lshl_add_u64 v[136:137], v[2:3], 0, s[0:1]
	ds_read_b128 v[124:127], v149
	ds_read_b128 v[128:131], v149 offset:1024
	ds_read_b128 v[166:169], v149 offset:2048
	ds_read_b128 v[170:173], v149 offset:3072
	ds_read_b128 v[174:177], v149 offset:4096
	ds_read_b128 v[178:181], v149 offset:5120
	ds_read_b128 v[182:185], v149 offset:6144
	ds_read_b128 v[186:189], v149 offset:7168
	global_load_lds_dwordx4 v[136:137], off
	v_lshl_add_u64 v[2:3], v[2:3], 0, s[78:79]
	s_mov_b32 m0, s8
	s_nop 0
	global_load_lds_dwordx4 v[2:3], off
	s_waitcnt lgkmcnt(8)
	s_barrier
	s_waitcnt lgkmcnt(0)
	v_mfma_f32_16x16x32_bf16 v[52:55], v[108:111], v[124:127], v[52:55]
	v_mfma_f32_16x16x32_bf16 v[56:59], v[116:119], v[124:127], v[56:59]
	v_mfma_f32_16x16x32_bf16 v[60:63], v[108:111], v[166:169], v[60:63]
	v_mfma_f32_16x16x32_bf16 v[64:67], v[116:119], v[166:169], v[64:67]
	v_mfma_f32_16x16x32_bf16 v[68:71], v[108:111], v[174:177], v[68:71]
	v_mfma_f32_16x16x32_bf16 v[72:75], v[116:119], v[174:177], v[72:75]
	v_mfma_f32_16x16x32_bf16 v[80:83], v[116:119], v[182:185], v[80:83]
	v_mfma_f32_16x16x32_bf16 v[52:55], v[112:115], v[128:131], v[52:55]
	v_mfma_f32_16x16x32_bf16 v[56:59], v[120:123], v[128:131], v[56:59]
	v_mfma_f32_16x16x32_bf16 v[60:63], v[112:115], v[170:173], v[60:63]
	v_mfma_f32_16x16x32_bf16 v[64:67], v[120:123], v[170:173], v[64:67]
	v_mfma_f32_16x16x32_bf16 v[68:71], v[112:115], v[178:181], v[68:71]
	v_mfma_f32_16x16x32_bf16 v[72:75], v[120:123], v[178:181], v[72:75]
	v_mfma_f32_16x16x32_bf16 v[76:79], v[108:111], v[182:185], v[76:79]
	v_mfma_f32_16x16x32_bf16 v[80:83], v[120:123], v[186:189], v[80:83]
	v_mfma_f32_16x16x32_bf16 v[76:79], v[112:115], v[186:189], v[76:79]
	s_barrier
	s_mov_b32 m0, s11
	v_lshl_add_u64 v[144:145], s[50:51], 0, v[0:1]
	ds_read_b128 v[190:193], v207
	ds_read_b128 v[194:197], v207 offset:1024
	ds_read_b128 v[198:201], v207 offset:2048
	ds_read_b128 v[202:205], v207 offset:3072
	global_load_lds_dwordx4 v[144:145], off
	v_lshl_add_u64 v[2:3], v[144:145], 0, s[68:69]
	s_mov_b32 m0, s6
	s_nop 0
	global_load_lds_dwordx4 v[2:3], off
	s_waitcnt lgkmcnt(0)
	s_barrier
	v_mfma_f32_16x16x32_bf16 v[100:103], v[190:193], v[124:127], v[100:103]
	v_mfma_f32_16x16x32_bf16 v[20:23], v[198:201], v[124:127], v[20:23]
	v_mfma_f32_16x16x32_bf16 v[24:27], v[190:193], v[166:169], v[24:27]
	v_mfma_f32_16x16x32_bf16 v[28:31], v[198:201], v[166:169], v[28:31]
	v_mfma_f32_16x16x32_bf16 v[32:35], v[190:193], v[174:177], v[32:35]
	v_mfma_f32_16x16x32_bf16 v[36:39], v[198:201], v[174:177], v[36:39]
	v_mfma_f32_16x16x32_bf16 v[40:43], v[190:193], v[182:185], v[40:43]
	v_mfma_f32_16x16x32_bf16 v[100:103], v[194:197], v[128:131], v[100:103]
	v_mfma_f32_16x16x32_bf16 v[20:23], v[202:205], v[128:131], v[20:23]
	v_mfma_f32_16x16x32_bf16 v[24:27], v[194:197], v[170:173], v[24:27]
	v_mfma_f32_16x16x32_bf16 v[28:31], v[202:205], v[170:173], v[28:31]
	v_mfma_f32_16x16x32_bf16 v[32:35], v[194:197], v[178:181], v[32:35]
	v_mfma_f32_16x16x32_bf16 v[36:39], v[202:205], v[178:181], v[36:39]
	v_mfma_f32_16x16x32_bf16 v[166:169], v[194:197], v[186:189], v[40:43]
	v_mfma_f32_16x16x32_bf16 v[40:43], v[198:201], v[182:185], v[44:47]
	v_mfma_f32_16x16x32_bf16 v[170:173], v[202:205], v[186:189], v[40:43]
	s_barrier
	s_mov_b32 m0, s57
	v_lshl_add_u64 v[234:235], s[48:49], 0, v[138:139]
	s_nop 2
	ds_read_b128 v[40:43], v149 offset:16384
	ds_read_b128 v[44:47], v149 offset:17408
	ds_read_b128 v[124:127], v149 offset:18432
	ds_read_b128 v[128:131], v149 offset:19456
	ds_read_b128 v[174:177], v149 offset:20480
	ds_read_b128 v[178:181], v149 offset:21504
	ds_read_b128 v[182:185], v149 offset:22528
	ds_read_b128 v[186:189], v149 offset:23552
	global_load_lds_dwordx4 v[234:235], off
	v_lshl_add_u64 v[2:3], v[234:235], 0, s[68:69]
	s_mov_b32 m0, s58
	s_nop 0
	global_load_lds_dwordx4 v[2:3], off
	s_waitcnt lgkmcnt(0)
	s_barrier
	v_mfma_f32_16x16x32_bf16 v[132:135], v[108:111], v[40:43], v[132:135]
	v_mfma_f32_16x16x32_bf16 v[206:209], v[112:115], v[44:47], v[132:135]
	v_mfma_f32_16x16x32_bf16 v[132:135], v[116:119], v[40:43], v[140:143]
	v_mfma_f32_16x16x32_bf16 v[140:143], v[120:123], v[44:47], v[132:135]
	v_mfma_f32_16x16x32_bf16 v[132:135], v[108:111], v[124:127], v[150:153]
	v_mfma_f32_16x16x32_bf16 v[150:153], v[112:115], v[128:131], v[132:135]
	v_mfma_f32_16x16x32_bf16 v[132:135], v[116:119], v[124:127], v[154:157]
	v_mfma_f32_16x16x32_bf16 v[154:157], v[120:123], v[128:131], v[132:135]
	v_mfma_f32_16x16x32_bf16 v[132:135], v[108:111], v[174:177], v[158:161]
	v_mfma_f32_16x16x32_bf16 v[2:5], v[108:111], v[182:185], v[4:7]
	v_mfma_f32_16x16x32_bf16 v[6:9], v[116:119], v[182:185], v[8:11]
	v_mfma_f32_16x16x32_bf16 v[158:161], v[112:115], v[178:181], v[132:135]
	v_mfma_f32_16x16x32_bf16 v[132:135], v[116:119], v[174:177], v[162:165]
	v_mfma_f32_16x16x32_bf16 v[2:5], v[112:115], v[186:189], v[2:5]
	v_mfma_f32_16x16x32_bf16 v[6:9], v[120:123], v[186:189], v[6:9]
	v_mfma_f32_16x16x32_bf16 v[162:165], v[120:123], v[178:181], v[132:135]
	s_barrier
	s_mov_b32 m0, s9
	v_lshl_add_u64 v[10:11], v[144:145], 0, s[38:39]
	s_mov_b64 s[8:9], 0x18000
	global_load_lds_dwordx4 v[10:11], off
	v_lshl_add_u64 v[10:11], v[144:145], 0, s[8:9]
	s_mov_b32 m0, s7
	s_nop 0
	global_load_lds_dwordx4 v[10:11], off
	s_waitcnt vmcnt(6)
	s_barrier
	v_mfma_f32_16x16x32_bf16 v[10:13], v[190:193], v[40:43], v[12:15]
	v_mfma_f32_16x16x32_bf16 v[14:17], v[198:201], v[40:43], v[16:19]
	v_mfma_f32_16x16x32_bf16 v[40:43], v[190:193], v[124:127], v[48:51]
	v_mfma_f32_16x16x32_bf16 v[210:213], v[194:197], v[128:131], v[40:43]
	v_mfma_f32_16x16x32_bf16 v[40:43], v[198:201], v[124:127], v[92:95]
	v_mfma_f32_16x16x32_bf16 v[214:217], v[202:205], v[128:131], v[40:43]
	v_mfma_f32_16x16x32_bf16 v[40:43], v[190:193], v[174:177], v[96:99]
	v_mfma_f32_16x16x32_bf16 v[218:221], v[194:197], v[178:181], v[40:43]
	v_mfma_f32_16x16x32_bf16 v[40:43], v[198:201], v[174:177], v[104:107]
	v_mfma_f32_16x16x32_bf16 v[174:177], v[202:205], v[178:181], v[40:43]
	v_mfma_f32_16x16x32_bf16 v[40:43], v[190:193], v[182:185], v[84:87]
	v_mfma_f32_16x16x32_bf16 v[10:13], v[194:197], v[44:47], v[10:13]
	v_mfma_f32_16x16x32_bf16 v[14:17], v[202:205], v[44:47], v[14:17]
	v_mfma_f32_16x16x32_bf16 v[178:181], v[194:197], v[186:189], v[40:43]
	v_mfma_f32_16x16x32_bf16 v[40:43], v[198:201], v[182:185], v[88:91]
	v_mfma_f32_16x16x32_bf16 v[182:185], v[202:205], v[186:189], v[40:43]
	s_barrier
	ds_read_b128 v[186:189], v222
	ds_read_b128 v[190:193], v222 offset:1024
	ds_read_b128 v[194:197], v222 offset:2048
	ds_read_b128 v[198:201], v222 offset:3072
	s_mov_b32 m0, s59
	v_lshl_add_u64 v[18:19], v[234:235], 0, s[38:39]
	ds_read_b128 v[40:43], v149 offset:32768
	ds_read_b128 v[44:47], v149 offset:33792
	ds_read_b128 v[48:51], v149 offset:34816
	ds_read_b128 v[84:87], v149 offset:35840
	ds_read_b128 v[88:91], v149 offset:36864
	ds_read_b128 v[92:95], v149 offset:37888
	ds_read_b128 v[96:99], v149 offset:38912
	ds_read_b128 v[202:205], v149 offset:39936
	global_load_lds_dwordx4 v[18:19], off
	v_lshl_add_u64 v[18:19], v[234:235], 0, s[8:9]
	s_mov_b32 m0, s62
	s_nop 0
	global_load_lds_dwordx4 v[18:19], off
	s_waitcnt lgkmcnt(8)
	s_barrier
	s_waitcnt lgkmcnt(0)
	v_mfma_f32_16x16x32_bf16 v[52:55], v[186:189], v[40:43], v[52:55]
	v_mfma_f32_16x16x32_bf16 v[134:137], v[190:193], v[44:47], v[52:55]
	v_mfma_f32_16x16x32_bf16 v[52:55], v[194:197], v[40:43], v[56:59]
	v_mfma_f32_16x16x32_bf16 v[130:133], v[198:201], v[44:47], v[52:55]
	v_mfma_f32_16x16x32_bf16 v[52:55], v[186:189], v[48:51], v[60:63]
	v_mfma_f32_16x16x32_bf16 v[126:129], v[190:193], v[84:87], v[52:55]
	v_mfma_f32_16x16x32_bf16 v[52:55], v[194:197], v[48:51], v[64:67]
	v_mfma_f32_16x16x32_bf16 v[122:125], v[198:201], v[84:87], v[52:55]
	v_mfma_f32_16x16x32_bf16 v[52:55], v[186:189], v[88:91], v[68:71]
	v_mfma_f32_16x16x32_bf16 v[118:121], v[190:193], v[92:95], v[52:55]
	v_mfma_f32_16x16x32_bf16 v[52:55], v[194:197], v[88:91], v[72:75]
	v_mfma_f32_16x16x32_bf16 v[114:117], v[198:201], v[92:95], v[52:55]
	v_mfma_f32_16x16x32_bf16 v[52:55], v[186:189], v[96:99], v[76:79]
	v_mfma_f32_16x16x32_bf16 v[110:113], v[190:193], v[202:205], v[52:55]
	v_mfma_f32_16x16x32_bf16 v[52:55], v[194:197], v[96:99], v[80:83]
	v_mfma_f32_16x16x32_bf16 v[106:109], v[198:201], v[202:205], v[52:55]
	s_barrier
	s_mov_b32 m0, s53
	v_lshl_add_u64 v[18:19], v[144:145], 0, s[34:35]
	s_mov_b64 s[6:7], 0x8080
	ds_read_b128 v[74:77], v226
	ds_read_b128 v[78:81], v226 offset:1024
	ds_read_b128 v[222:225], v226 offset:2048
	ds_read_b128 v[226:229], v226 offset:3072
	global_load_lds_dwordx4 v[18:19], off
	v_lshl_add_u64 v[18:19], v[144:145], 0, s[6:7]
	s_mov_b32 m0, s22
	s_nop 0
	global_load_lds_dwordx4 v[18:19], off
	s_waitcnt lgkmcnt(0)
	s_barrier
	v_mfma_f32_16x16x32_bf16 v[18:21], v[222:225], v[40:43], v[20:23]
	v_mfma_f32_16x16x32_bf16 v[52:55], v[74:77], v[40:43], v[100:103]
	v_mfma_f32_16x16x32_bf16 v[58:61], v[226:229], v[44:47], v[18:21]
	v_mfma_f32_16x16x32_bf16 v[18:21], v[74:77], v[48:51], v[24:27]
	v_mfma_f32_16x16x32_bf16 v[62:65], v[78:81], v[44:47], v[52:55]
	v_mfma_f32_16x16x32_bf16 v[54:57], v[78:81], v[84:87], v[18:21]
	v_mfma_f32_16x16x32_bf16 v[18:21], v[222:225], v[48:51], v[28:31]
	v_mfma_f32_16x16x32_bf16 v[50:53], v[226:229], v[84:87], v[18:21]
	v_mfma_f32_16x16x32_bf16 v[18:21], v[74:77], v[88:91], v[32:35]
	v_mfma_f32_16x16x32_bf16 v[46:49], v[78:81], v[92:95], v[18:21]
	v_mfma_f32_16x16x32_bf16 v[18:21], v[222:225], v[88:91], v[36:39]
	v_mfma_f32_16x16x32_bf16 v[42:45], v[226:229], v[92:95], v[18:21]
	v_mfma_f32_16x16x32_bf16 v[18:21], v[74:77], v[96:99], v[166:169]
	v_mfma_f32_16x16x32_bf16 v[38:41], v[78:81], v[202:205], v[18:21]
	v_mfma_f32_16x16x32_bf16 v[18:21], v[222:225], v[96:99], v[170:173]
	v_mfma_f32_16x16x32_bf16 v[34:37], v[226:229], v[202:205], v[18:21]
	s_barrier
	s_mov_b32 m0, s85
	v_lshl_add_u64 v[26:27], v[234:235], 0, s[34:35]
	s_nop 2
	ds_read_b128 v[18:21], v149 offset:49152
	ds_read_b128 v[22:25], v149 offset:50176
	ds_read_b128 v[166:169], v149 offset:51200
	ds_read_b128 v[170:173], v149 offset:52224
	ds_read_b128 v[202:205], v149 offset:53248
	ds_read_b128 v[230:233], v149 offset:54272
	ds_read_b128 v[248:251], v149 offset:55296
	ds_read_b128 v[244:247], v149 offset:56320
	global_load_lds_dwordx4 v[26:27], off
	v_lshl_add_u64 v[26:27], v[234:235], 0, s[6:7]
	s_mov_b32 m0, s86
	s_nop 0
	global_load_lds_dwordx4 v[26:27], off
	s_waitcnt lgkmcnt(0)
	s_barrier
	v_mfma_f32_16x16x32_bf16 v[26:29], v[186:189], v[18:21], v[206:209]
	v_mfma_f32_16x16x32_bf16 v[102:105], v[190:193], v[22:25], v[26:29]
	v_mfma_f32_16x16x32_bf16 v[26:29], v[194:197], v[18:21], v[140:143]
	v_mfma_f32_16x16x32_bf16 v[98:101], v[198:201], v[22:25], v[26:29]
	v_mfma_f32_16x16x32_bf16 v[26:29], v[186:189], v[166:169], v[150:153]
	v_mfma_f32_16x16x32_bf16 v[94:97], v[190:193], v[170:173], v[26:29]
	v_mfma_f32_16x16x32_bf16 v[26:29], v[194:197], v[166:169], v[154:157]
	v_mfma_f32_16x16x32_bf16 v[90:93], v[198:201], v[170:173], v[26:29]
	v_mfma_f32_16x16x32_bf16 v[26:29], v[186:189], v[202:205], v[158:161]
	v_mfma_f32_16x16x32_bf16 v[2:5], v[186:189], v[248:251], v[2:5]
	v_mfma_f32_16x16x32_bf16 v[86:89], v[190:193], v[230:233], v[26:29]
	v_mfma_f32_16x16x32_bf16 v[26:29], v[194:197], v[202:205], v[162:165]
	v_mfma_f32_16x16x32_bf16 v[70:73], v[190:193], v[244:247], v[2:5]
	v_mfma_f32_16x16x32_bf16 v[2:5], v[194:197], v[248:251], v[6:9]
	v_mfma_f32_16x16x32_bf16 v[82:85], v[198:201], v[230:233], v[26:29]
	v_mfma_f32_16x16x32_bf16 v[66:69], v[198:201], v[244:247], v[2:5]
	s_barrier
	s_mov_b32 m0, s41
	s_nop 2
	v_lshl_add_u64 v[2:3], v[144:145], 0, s[72:73]
	global_load_lds_dwordx4 v[2:3], off
	v_lshl_add_u64 v[2:3], v[144:145], 0, vcc
	s_mov_b32 m0, s40
	s_nop 0
	global_load_lds_dwordx4 v[2:3], off
	s_waitcnt vmcnt(6)
	s_barrier
	v_mfma_f32_16x16x32_bf16 v[2:5], v[74:77], v[18:21], v[10:13]
	v_mfma_f32_16x16x32_bf16 v[30:33], v[78:81], v[22:25], v[2:5]
	v_mfma_f32_16x16x32_bf16 v[2:5], v[222:225], v[18:21], v[14:17]
	v_mfma_f32_16x16x32_bf16 v[26:29], v[226:229], v[22:25], v[2:5]
	v_mfma_f32_16x16x32_bf16 v[2:5], v[74:77], v[166:169], v[210:213]
	v_mfma_f32_16x16x32_bf16 v[22:25], v[78:81], v[170:173], v[2:5]
	v_mfma_f32_16x16x32_bf16 v[2:5], v[222:225], v[166:169], v[214:217]
	v_mfma_f32_16x16x32_bf16 v[18:21], v[226:229], v[170:173], v[2:5]
	v_mfma_f32_16x16x32_bf16 v[2:5], v[74:77], v[202:205], v[218:221]
	v_mfma_f32_16x16x32_bf16 v[14:17], v[78:81], v[230:233], v[2:5]
	v_mfma_f32_16x16x32_bf16 v[2:5], v[222:225], v[202:205], v[174:177]
	v_mfma_f32_16x16x32_bf16 v[10:13], v[226:229], v[230:233], v[2:5]
	v_mfma_f32_16x16x32_bf16 v[2:5], v[74:77], v[248:251], v[178:181]
	v_mfma_f32_16x16x32_bf16 v[6:9], v[78:81], v[244:247], v[2:5]
	v_mfma_f32_16x16x32_bf16 v[2:5], v[222:225], v[248:251], v[182:185]
	v_mfma_f32_16x16x32_bf16 v[2:5], v[226:229], v[244:247], v[2:5]
	s_barrier
	v_mov_b32_e32 v150, v146
	s_cmp_gt_i32 s52, 1
	s_mov_b64 s[8:9], -1
	s_cbranch_scc0 .LBB0_231
	s_lshl_b32 s6, s52, 13
	s_and_b32 s6, s6, 0x2000
	s_add_u32 s6, s44, s6
	s_addc_u32 s7, s45, 0
	s_mov_b64 s[8:9], 0

.Lrot_enter_7:
	s_add_u32 s6, s4, 0x100
	s_addc_u32 s7, s5, 0
	s_add_i32 s11, 0, 0x10000
	v_add_u32_e32 v138, s11, v141
	ds_read_b128 v[130:133], v138
	ds_read_b128 v[148:151], v138 offset:1024
	ds_read_b128 v[152:155], v138 offset:2048
	ds_read_b128 v[156:159], v138 offset:3072
	s_cmp_eq_u32 s10, 28
	s_cselect_b32 s41, s47, s7
	s_cselect_b32 s40, s46, s6
	s_cselect_b32 s93, s49, s9
	s_cselect_b32 s92, s48, s8
	v_lshl_add_u64 v[144:145], s[4:5], 0, v[136:137]
	v_lshl_add_u64 v[192:193], v[144:145], 0, s[16:17]
	s_add_i32 m0, s54, 0xc000
	ds_read_b128 v[160:163], v142
	ds_read_b128 v[164:167], v142 offset:1024
	ds_read_b128 v[168:171], v142 offset:2048
	ds_read_b128 v[172:175], v142 offset:3072
	ds_read_b128 v[176:179], v142 offset:4096
	ds_read_b128 v[180:183], v142 offset:5120
	ds_read_b128 v[184:187], v142 offset:6144
	ds_read_b128 v[188:191], v142 offset:7168
	global_load_lds_dwordx4 v[192:193], off
	v_lshl_add_u64 v[144:145], v[144:145], 0, s[80:81]
	s_add_i32 m0, s54, 0xe000
	s_nop 0
	global_load_lds_dwordx4 v[144:145], off
	s_waitcnt lgkmcnt(8)
	s_barrier
	s_waitcnt lgkmcnt(0)
	v_mfma_f32_16x16x32_bf16 v[126:129], v[130:133], v[160:163], v[126:129]
	v_mfma_f32_16x16x32_bf16 v[122:125], v[152:155], v[160:163], v[122:125]
	v_mfma_f32_16x16x32_bf16 v[110:113], v[130:133], v[168:171], v[110:113]
	v_mfma_f32_16x16x32_bf16 v[106:109], v[152:155], v[168:171], v[106:109]
	v_mfma_f32_16x16x32_bf16 v[94:97], v[130:133], v[176:179], v[94:97]
	v_mfma_f32_16x16x32_bf16 v[90:93], v[152:155], v[176:179], v[90:93]
	v_mfma_f32_16x16x32_bf16 v[78:81], v[130:133], v[184:187], v[78:81]
	v_mfma_f32_16x16x32_bf16 v[74:77], v[152:155], v[184:187], v[74:77]
	v_mfma_f32_16x16x32_bf16 v[126:129], v[148:151], v[164:167], v[126:129]
	v_mfma_f32_16x16x32_bf16 v[122:125], v[156:159], v[164:167], v[122:125]
	v_mfma_f32_16x16x32_bf16 v[110:113], v[148:151], v[172:175], v[110:113]
	v_mfma_f32_16x16x32_bf16 v[106:109], v[156:159], v[172:175], v[106:109]
	v_mfma_f32_16x16x32_bf16 v[94:97], v[148:151], v[180:183], v[94:97]
	v_mfma_f32_16x16x32_bf16 v[90:93], v[156:159], v[180:183], v[90:93]
	v_mfma_f32_16x16x32_bf16 v[78:81], v[148:151], v[188:191], v[78:81]
	v_mfma_f32_16x16x32_bf16 v[74:77], v[156:159], v[188:191], v[74:77]
	s_barrier
	s_add_i32 s4, 0, 0x14000
	s_add_i32 s5, s11, s53
	v_add_u32_e32 v138, s4, v141
	v_lshl_add_u64 v[144:145], s[92:93], 0, v[0:1]
	s_mov_b32 m0, s5
	ds_read_b128 v[192:195], v138
	ds_read_b128 v[196:199], v138 offset:1024
	ds_read_b128 v[200:203], v138 offset:2048
	ds_read_b128 v[204:207], v138 offset:3072
	global_load_lds_dwordx4 v[144:145], off
	v_lshl_add_u64 v[208:209], v[144:145], 0, s[60:61]
	s_add_i32 m0, s5, 0x2000
	s_nop 0
	global_load_lds_dwordx4 v[208:209], off
	s_waitcnt lgkmcnt(0)
	s_barrier
	v_mfma_f32_16x16x32_bf16 v[118:121], v[192:195], v[160:163], v[118:121]
	v_mfma_f32_16x16x32_bf16 v[114:117], v[200:203], v[160:163], v[114:117]
	v_mfma_f32_16x16x32_bf16 v[102:105], v[192:195], v[168:171], v[102:105]
	v_mfma_f32_16x16x32_bf16 v[98:101], v[200:203], v[168:171], v[98:101]
	v_mfma_f32_16x16x32_bf16 v[86:89], v[192:195], v[176:179], v[86:89]
	v_mfma_f32_16x16x32_bf16 v[82:85], v[200:203], v[176:179], v[82:85]
	v_mfma_f32_16x16x32_bf16 v[70:73], v[192:195], v[184:187], v[70:73]
	v_mfma_f32_16x16x32_bf16 v[66:69], v[200:203], v[184:187], v[66:69]
	v_mfma_f32_16x16x32_bf16 v[118:121], v[196:199], v[164:167], v[118:121]
	v_mfma_f32_16x16x32_bf16 v[114:117], v[204:207], v[164:167], v[114:117]
	v_mfma_f32_16x16x32_bf16 v[102:105], v[196:199], v[172:175], v[102:105]
	v_mfma_f32_16x16x32_bf16 v[98:101], v[204:207], v[172:175], v[98:101]
	v_mfma_f32_16x16x32_bf16 v[86:89], v[196:199], v[180:183], v[86:89]
	v_mfma_f32_16x16x32_bf16 v[82:85], v[204:207], v[180:183], v[82:85]
	v_mfma_f32_16x16x32_bf16 v[70:73], v[196:199], v[188:191], v[70:73]
	v_mfma_f32_16x16x32_bf16 v[66:69], v[204:207], v[188:191], v[66:69]
	s_barrier
	s_mov_b32 m0, s54
	v_lshl_add_u64 v[208:209], s[40:41], 0, v[134:135]
	ds_read_b128 v[160:163], v142 offset:16384
	ds_read_b128 v[164:167], v142 offset:17408
	ds_read_b128 v[168:171], v142 offset:18432
	ds_read_b128 v[172:175], v142 offset:19456
	ds_read_b128 v[176:179], v142 offset:20480
	ds_read_b128 v[180:183], v142 offset:21504
	ds_read_b128 v[184:187], v142 offset:22528
	ds_read_b128 v[188:191], v142 offset:23552
	global_load_lds_dwordx4 v[208:209], off
	v_lshl_add_u64 v[210:211], v[208:209], 0, s[60:61]
	s_mov_b32 m0, s55
	s_nop 0
	global_load_lds_dwordx4 v[210:211], off
	s_waitcnt lgkmcnt(0)
	s_barrier
	v_mfma_f32_16x16x32_bf16 v[62:65], v[130:133], v[160:163], v[62:65]
	v_mfma_f32_16x16x32_bf16 v[58:61], v[152:155], v[160:163], v[58:61]
	v_mfma_f32_16x16x32_bf16 v[46:49], v[130:133], v[168:171], v[46:49]
	v_mfma_f32_16x16x32_bf16 v[42:45], v[152:155], v[168:171], v[42:45]
	v_mfma_f32_16x16x32_bf16 v[30:33], v[130:133], v[176:179], v[30:33]
	v_mfma_f32_16x16x32_bf16 v[26:29], v[152:155], v[176:179], v[26:29]
	v_mfma_f32_16x16x32_bf16 v[14:17], v[130:133], v[184:187], v[14:17]
	v_mfma_f32_16x16x32_bf16 v[10:13], v[152:155], v[184:187], v[10:13]
	v_mfma_f32_16x16x32_bf16 v[62:65], v[148:151], v[164:167], v[62:65]
	v_mfma_f32_16x16x32_bf16 v[58:61], v[156:159], v[164:167], v[58:61]
	v_mfma_f32_16x16x32_bf16 v[46:49], v[148:151], v[172:175], v[46:49]
	v_mfma_f32_16x16x32_bf16 v[42:45], v[156:159], v[172:175], v[42:45]
	v_mfma_f32_16x16x32_bf16 v[30:33], v[148:151], v[180:183], v[30:33]
	v_mfma_f32_16x16x32_bf16 v[26:29], v[156:159], v[180:183], v[26:29]
	v_mfma_f32_16x16x32_bf16 v[14:17], v[148:151], v[188:191], v[14:17]
	v_mfma_f32_16x16x32_bf16 v[10:13], v[156:159], v[188:191], v[10:13]
	s_barrier
	s_add_i32 s4, s4, s53
	v_lshl_add_u64 v[130:131], v[144:145], 0, s[20:21]
	s_mov_b32 m0, s4
	s_nop 0
	global_load_lds_dwordx4 v[130:131], off
	v_lshl_add_u64 v[130:131], v[144:145], 0, s[64:65]
	s_add_i32 m0, s4, 0x2000
	s_nop 0
	global_load_lds_dwordx4 v[130:131], off
	v_lshl_add_u64 v[230:231], v[208:209], 0, s[20:21]
	s_mov_b32 m0, s56
	s_nop 0
	global_load_lds_dwordx4 v[230:231], off
	v_lshl_add_u64 v[230:231], v[208:209], 0, s[64:65]
	s_mov_b32 m0, s57
	s_nop 0
	global_load_lds_dwordx4 v[230:231], off
	s_waitcnt vmcnt(8)
	s_barrier
	v_mfma_f32_16x16x32_bf16 v[54:57], v[192:195], v[160:163], v[54:57]
	v_mfma_f32_16x16x32_bf16 v[50:53], v[200:203], v[160:163], v[50:53]
	v_mfma_f32_16x16x32_bf16 v[38:41], v[192:195], v[168:171], v[38:41]
	v_mfma_f32_16x16x32_bf16 v[34:37], v[200:203], v[168:171], v[34:37]
	v_mfma_f32_16x16x32_bf16 v[22:25], v[192:195], v[176:179], v[22:25]
	v_mfma_f32_16x16x32_bf16 v[18:21], v[200:203], v[176:179], v[18:21]
	v_mfma_f32_16x16x32_bf16 v[6:9], v[192:195], v[184:187], v[6:9]
	v_mfma_f32_16x16x32_bf16 v[2:5], v[200:203], v[184:187], v[2:5]
	v_mfma_f32_16x16x32_bf16 v[54:57], v[196:199], v[164:167], v[54:57]
	v_mfma_f32_16x16x32_bf16 v[50:53], v[204:207], v[164:167], v[50:53]
	v_mfma_f32_16x16x32_bf16 v[38:41], v[196:199], v[172:175], v[38:41]
	v_mfma_f32_16x16x32_bf16 v[34:37], v[204:207], v[172:175], v[34:37]
	v_mfma_f32_16x16x32_bf16 v[22:25], v[196:199], v[180:183], v[22:25]
	v_mfma_f32_16x16x32_bf16 v[18:21], v[204:207], v[180:183], v[18:21]
	v_mfma_f32_16x16x32_bf16 v[6:9], v[196:199], v[188:191], v[6:9]
	v_mfma_f32_16x16x32_bf16 v[2:5], v[204:207], v[188:191], v[2:5]
	s_barrier
	s_add_i32 s4, 0, 0x18000
	v_add_u32_e32 v138, s4, v141
	ds_read_b128 v[130:133], v138
	ds_read_b128 v[148:151], v138 offset:1024
	ds_read_b128 v[152:155], v138 offset:2048
	ds_read_b128 v[156:159], v138 offset:3072
	ds_read_b128 v[160:163], v142 offset:32768
	ds_read_b128 v[164:167], v142 offset:33792
	ds_read_b128 v[168:171], v142 offset:34816
	ds_read_b128 v[172:175], v142 offset:35840
	ds_read_b128 v[176:179], v142 offset:36864
	ds_read_b128 v[180:183], v142 offset:37888
	ds_read_b128 v[184:187], v142 offset:38912
	ds_read_b128 v[188:191], v142 offset:39936
	s_waitcnt lgkmcnt(8)
	s_barrier
	s_waitcnt lgkmcnt(0)
	v_mfma_f32_16x16x32_bf16 v[126:129], v[130:133], v[160:163], v[126:129]
	v_mfma_f32_16x16x32_bf16 v[122:125], v[152:155], v[160:163], v[122:125]
	v_mfma_f32_16x16x32_bf16 v[110:113], v[130:133], v[168:171], v[110:113]
	v_mfma_f32_16x16x32_bf16 v[106:109], v[152:155], v[168:171], v[106:109]
	v_mfma_f32_16x16x32_bf16 v[94:97], v[130:133], v[176:179], v[94:97]
	v_mfma_f32_16x16x32_bf16 v[90:93], v[152:155], v[176:179], v[90:93]
	v_mfma_f32_16x16x32_bf16 v[78:81], v[130:133], v[184:187], v[78:81]
	v_mfma_f32_16x16x32_bf16 v[74:77], v[152:155], v[184:187], v[74:77]
	v_mfma_f32_16x16x32_bf16 v[126:129], v[148:151], v[164:167], v[126:129]
	v_mfma_f32_16x16x32_bf16 v[122:125], v[156:159], v[164:167], v[122:125]
	v_mfma_f32_16x16x32_bf16 v[110:113], v[148:151], v[172:175], v[110:113]
	v_mfma_f32_16x16x32_bf16 v[106:109], v[156:159], v[172:175], v[106:109]
	v_mfma_f32_16x16x32_bf16 v[94:97], v[148:151], v[180:183], v[94:97]
	v_mfma_f32_16x16x32_bf16 v[90:93], v[156:159], v[180:183], v[90:93]
	v_mfma_f32_16x16x32_bf16 v[78:81], v[148:151], v[188:191], v[78:81]
	v_mfma_f32_16x16x32_bf16 v[74:77], v[156:159], v[188:191], v[74:77]
	s_barrier
	s_add_i32 s5, 0, 0x1c000
	s_add_i32 s4, s4, s53
	v_add_u32_e32 v138, s5, v141
	v_lshl_add_u64 v[210:211], v[144:145], 0, s[34:35]
	s_mov_b32 m0, s4
	ds_read_b128 v[192:195], v138
	ds_read_b128 v[196:199], v138 offset:1024
	ds_read_b128 v[200:203], v138 offset:2048
	ds_read_b128 v[204:207], v138 offset:3072
	global_load_lds_dwordx4 v[210:211], off
	v_lshl_add_u64 v[210:211], v[144:145], 0, s[66:67]
	s_add_i32 m0, s4, 0x2000
	s_nop 0
	global_load_lds_dwordx4 v[210:211], off
	s_waitcnt lgkmcnt(0)
	s_barrier
	v_mfma_f32_16x16x32_bf16 v[118:121], v[192:195], v[160:163], v[118:121]
	v_mfma_f32_16x16x32_bf16 v[114:117], v[200:203], v[160:163], v[114:117]
	v_mfma_f32_16x16x32_bf16 v[102:105], v[192:195], v[168:171], v[102:105]
	v_mfma_f32_16x16x32_bf16 v[98:101], v[200:203], v[168:171], v[98:101]
	v_mfma_f32_16x16x32_bf16 v[86:89], v[192:195], v[176:179], v[86:89]
	v_mfma_f32_16x16x32_bf16 v[82:85], v[200:203], v[176:179], v[82:85]
	v_mfma_f32_16x16x32_bf16 v[70:73], v[192:195], v[184:187], v[70:73]
	v_mfma_f32_16x16x32_bf16 v[66:69], v[200:203], v[184:187], v[66:69]
	v_mfma_f32_16x16x32_bf16 v[118:121], v[196:199], v[164:167], v[118:121]
	v_mfma_f32_16x16x32_bf16 v[114:117], v[204:207], v[164:167], v[114:117]
	v_mfma_f32_16x16x32_bf16 v[102:105], v[196:199], v[172:175], v[102:105]
	v_mfma_f32_16x16x32_bf16 v[98:101], v[204:207], v[172:175], v[98:101]
	v_mfma_f32_16x16x32_bf16 v[86:89], v[196:199], v[180:183], v[86:89]
	v_mfma_f32_16x16x32_bf16 v[82:85], v[204:207], v[180:183], v[82:85]
	v_mfma_f32_16x16x32_bf16 v[70:73], v[196:199], v[188:191], v[70:73]
	v_mfma_f32_16x16x32_bf16 v[66:69], v[204:207], v[188:191], v[66:69]
	s_barrier
	s_mov_b32 m0, s62
	v_lshl_add_u64 v[210:211], v[208:209], 0, s[34:35]
	ds_read_b128 v[160:163], v142 offset:49152
	ds_read_b128 v[164:167], v142 offset:50176
	ds_read_b128 v[168:171], v142 offset:51200
	ds_read_b128 v[172:175], v142 offset:52224
	ds_read_b128 v[176:179], v142 offset:53248
	ds_read_b128 v[180:183], v142 offset:54272
	ds_read_b128 v[184:187], v142 offset:55296
	ds_read_b128 v[188:191], v142 offset:56320
	global_load_lds_dwordx4 v[210:211], off
	v_lshl_add_u64 v[208:209], v[208:209], 0, s[66:67]
	s_mov_b32 m0, s63
	s_nop 0
	global_load_lds_dwordx4 v[208:209], off
	s_waitcnt lgkmcnt(0)
	s_barrier
	v_mfma_f32_16x16x32_bf16 v[62:65], v[130:133], v[160:163], v[62:65]
	v_mfma_f32_16x16x32_bf16 v[58:61], v[152:155], v[160:163], v[58:61]
	v_mfma_f32_16x16x32_bf16 v[46:49], v[130:133], v[168:171], v[46:49]
	v_mfma_f32_16x16x32_bf16 v[42:45], v[152:155], v[168:171], v[42:45]
	v_mfma_f32_16x16x32_bf16 v[30:33], v[130:133], v[176:179], v[30:33]
	v_mfma_f32_16x16x32_bf16 v[26:29], v[152:155], v[176:179], v[26:29]
	v_mfma_f32_16x16x32_bf16 v[14:17], v[130:133], v[184:187], v[14:17]
	v_mfma_f32_16x16x32_bf16 v[10:13], v[152:155], v[184:187], v[10:13]
	v_mfma_f32_16x16x32_bf16 v[62:65], v[148:151], v[164:167], v[62:65]
	v_mfma_f32_16x16x32_bf16 v[58:61], v[156:159], v[164:167], v[58:61]
	v_mfma_f32_16x16x32_bf16 v[46:49], v[148:151], v[172:175], v[46:49]
	v_mfma_f32_16x16x32_bf16 v[42:45], v[156:159], v[172:175], v[42:45]
	v_mfma_f32_16x16x32_bf16 v[30:33], v[148:151], v[180:183], v[30:33]
	v_mfma_f32_16x16x32_bf16 v[26:29], v[156:159], v[180:183], v[26:29]
	v_mfma_f32_16x16x32_bf16 v[14:17], v[148:151], v[188:191], v[14:17]
	v_mfma_f32_16x16x32_bf16 v[10:13], v[156:159], v[188:191], v[10:13]
	s_barrier
	s_add_i32 s4, s5, s53
	v_lshl_add_u64 v[130:131], v[144:145], 0, s[16:17]
	s_mov_b32 m0, s4
	s_nop 0
	global_load_lds_dwordx4 v[130:131], off
	v_lshl_add_u64 v[130:131], v[144:145], 0, s[80:81]
	s_add_i32 m0, s4, 0x2000
	s_nop 0
	global_load_lds_dwordx4 v[130:131], off
	s_waitcnt vmcnt(6)
	s_add_i32 s10, s10, 2
	s_add_u32 s8, s8, 0x100
	s_addc_u32 s9, s9, 0
	s_cmp_gt_u32 s10, 29
	s_mov_b64 s[4:5], s[6:7]
	s_cbranch_scc0 .LBB0_292
	s_barrier
	v_mfma_f32_16x16x32_bf16 v[54:57], v[192:195], v[160:163], v[54:57]
	v_mfma_f32_16x16x32_bf16 v[50:53], v[200:203], v[160:163], v[50:53]
	v_mfma_f32_16x16x32_bf16 v[38:41], v[192:195], v[168:171], v[38:41]
	v_mfma_f32_16x16x32_bf16 v[34:37], v[200:203], v[168:171], v[34:37]
	v_mfma_f32_16x16x32_bf16 v[22:25], v[192:195], v[176:179], v[22:25]
	v_mfma_f32_16x16x32_bf16 v[18:21], v[200:203], v[176:179], v[18:21]
	v_mfma_f32_16x16x32_bf16 v[6:9], v[192:195], v[184:187], v[6:9]
	v_mfma_f32_16x16x32_bf16 v[2:5], v[200:203], v[184:187], v[2:5]
	v_mfma_f32_16x16x32_bf16 v[54:57], v[196:199], v[164:167], v[54:57]
	v_mfma_f32_16x16x32_bf16 v[50:53], v[204:207], v[164:167], v[50:53]
	v_mfma_f32_16x16x32_bf16 v[38:41], v[196:199], v[172:175], v[38:41]
	v_mfma_f32_16x16x32_bf16 v[34:37], v[204:207], v[172:175], v[34:37]
	v_mfma_f32_16x16x32_bf16 v[22:25], v[196:199], v[180:183], v[22:25]
	v_mfma_f32_16x16x32_bf16 v[18:21], v[204:207], v[180:183], v[18:21]
	v_mfma_f32_16x16x32_bf16 v[6:9], v[196:199], v[188:191], v[6:9]
	v_mfma_f32_16x16x32_bf16 v[2:5], v[204:207], v[188:191], v[2:5]
	s_barrier
	s_cmp_eq_u32 s52, 3
	v_mov_b32_e32 v144, v139
	s_cselect_b64 s[4:5], -1, 0
	s_cmp_lt_i32 s52, 5
	s_cbranch_scc1 .LBB0_295
	s_cmp_eq_u32 s52, 5
	s_cselect_b64 s[6:7], -1, 0
	s_movk_i32 s93, 0xf800
	s_cbranch_execz .LBB0_296
	s_branch .LBB0_297

.Lrot_enter_6:
	s_add_u32 s7, s46, 0xffea0080
	s_addc_u32 s78, s47, -1
	s_add_i32 s79, 0, 0x10000
	v_add_u32_e32 v132, s79, v135
	ds_read_b128 v[138:141], v132
	ds_read_b128 v[142:145], v132 offset:1024
	ds_read_b128 v[148:151], v132 offset:2048
	ds_read_b128 v[152:155], v132 offset:3072
	s_cmpk_eq_i32 s6, 0x54
	s_cselect_b32 s89, s43, s78
	s_cselect_b32 s88, s42, s7
	s_cselect_b32 s91, s45, s9
	s_cselect_b32 s90, s44, s8
	v_lshl_add_u64 v[132:133], s[46:47], 0, v[130:131]
	s_add_i32 m0, s54, 0xc000
	ds_read_b128 v[156:159], v136
	ds_read_b128 v[160:163], v136 offset:1024
	ds_read_b128 v[164:167], v136 offset:2048
	ds_read_b128 v[168:171], v136 offset:3072
	ds_read_b128 v[172:175], v136 offset:4096
	ds_read_b128 v[176:179], v136 offset:5120
	ds_read_b128 v[180:183], v136 offset:6144
	ds_read_b128 v[184:187], v136 offset:7168
	global_load_lds_dwordx4 v[132:133], off
	v_lshl_add_u64 v[132:133], v[132:133], 0, s[26:27]
	s_add_i32 m0, s54, 0xe000
	s_nop 0
	global_load_lds_dwordx4 v[132:133], off
	s_waitcnt lgkmcnt(8)
	s_barrier
	s_waitcnt lgkmcnt(0)
	v_mfma_f32_16x16x32_bf16 v[126:129], v[138:141], v[156:159], v[126:129]
	v_mfma_f32_16x16x32_bf16 v[122:125], v[148:151], v[156:159], v[122:125]
	v_mfma_f32_16x16x32_bf16 v[118:121], v[138:141], v[164:167], v[118:121]
	v_mfma_f32_16x16x32_bf16 v[110:113], v[148:151], v[164:167], v[110:113]
	v_mfma_f32_16x16x32_bf16 v[102:105], v[138:141], v[172:175], v[102:105]
	v_mfma_f32_16x16x32_bf16 v[94:97], v[148:151], v[172:175], v[94:97]
	v_mfma_f32_16x16x32_bf16 v[86:89], v[138:141], v[180:183], v[86:89]
	v_mfma_f32_16x16x32_bf16 v[78:81], v[148:151], v[180:183], v[78:81]
	v_mfma_f32_16x16x32_bf16 v[126:129], v[142:145], v[160:163], v[126:129]
	v_mfma_f32_16x16x32_bf16 v[122:125], v[152:155], v[160:163], v[122:125]
	v_mfma_f32_16x16x32_bf16 v[118:121], v[142:145], v[168:171], v[118:121]
	v_mfma_f32_16x16x32_bf16 v[110:113], v[152:155], v[168:171], v[110:113]
	v_mfma_f32_16x16x32_bf16 v[102:105], v[142:145], v[176:179], v[102:105]
	v_mfma_f32_16x16x32_bf16 v[94:97], v[152:155], v[176:179], v[94:97]
	v_mfma_f32_16x16x32_bf16 v[86:89], v[142:145], v[184:187], v[86:89]
	v_mfma_f32_16x16x32_bf16 v[78:81], v[152:155], v[184:187], v[78:81]
	s_barrier
	s_add_i32 s7, 0, 0x14000
	v_add_u32_e32 v132, s7, v135
	s_add_i32 s78, s79, s53
	ds_read_b128 v[188:191], v132
	ds_read_b128 v[192:195], v132 offset:1024
	ds_read_b128 v[196:199], v132 offset:2048
	ds_read_b128 v[200:203], v132 offset:3072
	v_lshl_add_u64 v[132:133], s[90:91], 0, v[0:1]
	s_mov_b32 m0, s78
	v_lshl_add_u64 v[204:205], v[132:133], 0, s[26:27]
	global_load_lds_dwordx4 v[132:133], off
	s_add_i32 m0, s78, 0x2000
	s_nop 0
	global_load_lds_dwordx4 v[204:205], off
	s_waitcnt lgkmcnt(0)
	s_barrier
	v_mfma_f32_16x16x32_bf16 v[114:117], v[188:191], v[156:159], v[114:117]
	v_mfma_f32_16x16x32_bf16 v[106:109], v[196:199], v[156:159], v[106:109]
	v_mfma_f32_16x16x32_bf16 v[98:101], v[188:191], v[164:167], v[98:101]
	v_mfma_f32_16x16x32_bf16 v[90:93], v[196:199], v[164:167], v[90:93]
	v_mfma_f32_16x16x32_bf16 v[82:85], v[188:191], v[172:175], v[82:85]
	v_mfma_f32_16x16x32_bf16 v[74:77], v[196:199], v[172:175], v[74:77]
	v_mfma_f32_16x16x32_bf16 v[70:73], v[188:191], v[180:183], v[70:73]
	v_mfma_f32_16x16x32_bf16 v[66:69], v[196:199], v[180:183], v[66:69]
	v_mfma_f32_16x16x32_bf16 v[114:117], v[192:195], v[160:163], v[114:117]
	v_mfma_f32_16x16x32_bf16 v[106:109], v[200:203], v[160:163], v[106:109]
	v_mfma_f32_16x16x32_bf16 v[98:101], v[192:195], v[168:171], v[98:101]
	v_mfma_f32_16x16x32_bf16 v[90:93], v[200:203], v[168:171], v[90:93]
	v_mfma_f32_16x16x32_bf16 v[82:85], v[192:195], v[176:179], v[82:85]
	v_mfma_f32_16x16x32_bf16 v[74:77], v[200:203], v[176:179], v[74:77]
	v_mfma_f32_16x16x32_bf16 v[70:73], v[192:195], v[184:187], v[70:73]
	v_mfma_f32_16x16x32_bf16 v[66:69], v[200:203], v[184:187], v[66:69]
	s_barrier
	s_mov_b32 m0, s54
	v_lshl_add_u64 v[204:205], s[88:89], 0, v[0:1]
	ds_read_b128 v[156:159], v136 offset:16384
	ds_read_b128 v[160:163], v136 offset:17408
	ds_read_b128 v[164:167], v136 offset:18432
	ds_read_b128 v[168:171], v136 offset:19456
	ds_read_b128 v[172:175], v136 offset:20480
	ds_read_b128 v[176:179], v136 offset:21504
	ds_read_b128 v[180:183], v136 offset:22528
	ds_read_b128 v[184:187], v136 offset:23552
	global_load_lds_dwordx4 v[204:205], off
	v_lshl_add_u64 v[206:207], v[204:205], 0, s[26:27]
	s_mov_b32 m0, s55
	s_nop 0
	global_load_lds_dwordx4 v[206:207], off
	s_waitcnt lgkmcnt(0)
	s_barrier
	v_mfma_f32_16x16x32_bf16 v[62:65], v[138:141], v[156:159], v[62:65]
	v_mfma_f32_16x16x32_bf16 v[58:61], v[148:151], v[156:159], v[58:61]
	v_mfma_f32_16x16x32_bf16 v[54:57], v[138:141], v[164:167], v[54:57]
	v_mfma_f32_16x16x32_bf16 v[46:49], v[148:151], v[164:167], v[46:49]
	v_mfma_f32_16x16x32_bf16 v[38:41], v[138:141], v[172:175], v[38:41]
	v_mfma_f32_16x16x32_bf16 v[30:33], v[148:151], v[172:175], v[30:33]
	v_mfma_f32_16x16x32_bf16 v[22:25], v[138:141], v[180:183], v[22:25]
	v_mfma_f32_16x16x32_bf16 v[14:17], v[148:151], v[180:183], v[14:17]
	v_mfma_f32_16x16x32_bf16 v[62:65], v[142:145], v[160:163], v[62:65]
	v_mfma_f32_16x16x32_bf16 v[58:61], v[152:155], v[160:163], v[58:61]
	v_mfma_f32_16x16x32_bf16 v[54:57], v[142:145], v[168:171], v[54:57]
	v_mfma_f32_16x16x32_bf16 v[46:49], v[152:155], v[168:171], v[46:49]
	v_mfma_f32_16x16x32_bf16 v[38:41], v[142:145], v[176:179], v[38:41]
	v_mfma_f32_16x16x32_bf16 v[30:33], v[152:155], v[176:179], v[30:33]
	v_mfma_f32_16x16x32_bf16 v[22:25], v[142:145], v[184:187], v[22:25]
	v_mfma_f32_16x16x32_bf16 v[14:17], v[152:155], v[184:187], v[14:17]
	s_barrier
	s_add_i32 s7, s7, s53
	v_lshl_add_u64 v[138:139], v[132:133], 0, s[28:29]
	s_mov_b32 m0, s7
	s_nop 0
	global_load_lds_dwordx4 v[138:139], off
	v_lshl_add_u64 v[138:139], v[132:133], 0, s[30:31]
	s_add_i32 m0, s7, 0x2000
	s_nop 0
	global_load_lds_dwordx4 v[138:139], off
	v_lshl_add_u64 v[230:231], v[204:205], 0, s[28:29]
	s_mov_b32 m0, s56
	s_nop 0
	global_load_lds_dwordx4 v[230:231], off
	v_lshl_add_u64 v[230:231], v[204:205], 0, s[30:31]
	s_mov_b32 m0, s57
	s_nop 0
	global_load_lds_dwordx4 v[230:231], off
	s_waitcnt vmcnt(8)
	s_barrier
	v_mfma_f32_16x16x32_bf16 v[50:53], v[188:191], v[156:159], v[50:53]
	v_mfma_f32_16x16x32_bf16 v[42:45], v[196:199], v[156:159], v[42:45]
	v_mfma_f32_16x16x32_bf16 v[34:37], v[188:191], v[164:167], v[34:37]
	v_mfma_f32_16x16x32_bf16 v[26:29], v[196:199], v[164:167], v[26:29]
	v_mfma_f32_16x16x32_bf16 v[18:21], v[188:191], v[172:175], v[18:21]
	v_mfma_f32_16x16x32_bf16 v[10:13], v[196:199], v[172:175], v[10:13]
	v_mfma_f32_16x16x32_bf16 v[6:9], v[188:191], v[180:183], v[6:9]
	v_mfma_f32_16x16x32_bf16 v[2:5], v[196:199], v[180:183], v[2:5]
	v_mfma_f32_16x16x32_bf16 v[50:53], v[192:195], v[160:163], v[50:53]
	v_mfma_f32_16x16x32_bf16 v[42:45], v[200:203], v[160:163], v[42:45]
	v_mfma_f32_16x16x32_bf16 v[34:37], v[192:195], v[168:171], v[34:37]
	v_mfma_f32_16x16x32_bf16 v[26:29], v[200:203], v[168:171], v[26:29]
	v_mfma_f32_16x16x32_bf16 v[18:21], v[192:195], v[176:179], v[18:21]
	v_mfma_f32_16x16x32_bf16 v[10:13], v[200:203], v[176:179], v[10:13]
	v_mfma_f32_16x16x32_bf16 v[6:9], v[192:195], v[184:187], v[6:9]
	v_mfma_f32_16x16x32_bf16 v[2:5], v[200:203], v[184:187], v[2:5]
	s_barrier
	s_add_i32 s7, 0, 0x18000
	v_add_u32_e32 v137, s7, v135
	ds_read_b128 v[138:141], v137
	ds_read_b128 v[142:145], v137 offset:1024
	ds_read_b128 v[148:151], v137 offset:2048
	ds_read_b128 v[152:155], v137 offset:3072
	ds_read_b128 v[156:159], v136 offset:32768
	ds_read_b128 v[160:163], v136 offset:33792
	ds_read_b128 v[164:167], v136 offset:34816
	ds_read_b128 v[168:171], v136 offset:35840
	ds_read_b128 v[172:175], v136 offset:36864
	ds_read_b128 v[176:179], v136 offset:37888
	ds_read_b128 v[180:183], v136 offset:38912
	ds_read_b128 v[184:187], v136 offset:39936
	s_waitcnt lgkmcnt(8)
	s_barrier
	s_waitcnt lgkmcnt(0)
	v_mfma_f32_16x16x32_bf16 v[126:129], v[138:141], v[156:159], v[126:129]
	v_mfma_f32_16x16x32_bf16 v[122:125], v[148:151], v[156:159], v[122:125]
	v_mfma_f32_16x16x32_bf16 v[118:121], v[138:141], v[164:167], v[118:121]
	v_mfma_f32_16x16x32_bf16 v[110:113], v[148:151], v[164:167], v[110:113]
	v_mfma_f32_16x16x32_bf16 v[102:105], v[138:141], v[172:175], v[102:105]
	v_mfma_f32_16x16x32_bf16 v[94:97], v[148:151], v[172:175], v[94:97]
	v_mfma_f32_16x16x32_bf16 v[86:89], v[138:141], v[180:183], v[86:89]
	v_mfma_f32_16x16x32_bf16 v[78:81], v[148:151], v[180:183], v[78:81]
	v_mfma_f32_16x16x32_bf16 v[126:129], v[142:145], v[160:163], v[126:129]
	v_mfma_f32_16x16x32_bf16 v[122:125], v[152:155], v[160:163], v[122:125]
	v_mfma_f32_16x16x32_bf16 v[118:121], v[142:145], v[168:171], v[118:121]
	v_mfma_f32_16x16x32_bf16 v[110:113], v[152:155], v[168:171], v[110:113]
	v_mfma_f32_16x16x32_bf16 v[102:105], v[142:145], v[176:179], v[102:105]
	v_mfma_f32_16x16x32_bf16 v[94:97], v[152:155], v[176:179], v[94:97]
	v_mfma_f32_16x16x32_bf16 v[86:89], v[142:145], v[184:187], v[86:89]
	v_mfma_f32_16x16x32_bf16 v[78:81], v[152:155], v[184:187], v[78:81]
	s_barrier
	s_add_i32 s78, 0, 0x1c000
	s_add_i32 s7, s7, s53
	v_add_u32_e32 v137, s78, v135
	v_lshl_add_u64 v[206:207], v[132:133], 0, s[34:35]
	s_mov_b32 m0, s7
	ds_read_b128 v[188:191], v137
	ds_read_b128 v[192:195], v137 offset:1024
	ds_read_b128 v[196:199], v137 offset:2048
	ds_read_b128 v[200:203], v137 offset:3072
	global_load_lds_dwordx4 v[206:207], off
	v_lshl_add_u64 v[206:207], v[132:133], 0, s[36:37]
	s_add_i32 m0, s7, 0x2000
	s_nop 0
	global_load_lds_dwordx4 v[206:207], off
	s_waitcnt lgkmcnt(0)
	s_barrier
	v_mfma_f32_16x16x32_bf16 v[114:117], v[188:191], v[156:159], v[114:117]
	v_mfma_f32_16x16x32_bf16 v[106:109], v[196:199], v[156:159], v[106:109]
	v_mfma_f32_16x16x32_bf16 v[98:101], v[188:191], v[164:167], v[98:101]
	v_mfma_f32_16x16x32_bf16 v[90:93], v[196:199], v[164:167], v[90:93]
	v_mfma_f32_16x16x32_bf16 v[82:85], v[188:191], v[172:175], v[82:85]
	v_mfma_f32_16x16x32_bf16 v[74:77], v[196:199], v[172:175], v[74:77]
	v_mfma_f32_16x16x32_bf16 v[70:73], v[188:191], v[180:183], v[70:73]
	v_mfma_f32_16x16x32_bf16 v[66:69], v[196:199], v[180:183], v[66:69]
	v_mfma_f32_16x16x32_bf16 v[114:117], v[192:195], v[160:163], v[114:117]
	v_mfma_f32_16x16x32_bf16 v[106:109], v[200:203], v[160:163], v[106:109]
	v_mfma_f32_16x16x32_bf16 v[98:101], v[192:195], v[168:171], v[98:101]
	v_mfma_f32_16x16x32_bf16 v[90:93], v[200:203], v[168:171], v[90:93]
	v_mfma_f32_16x16x32_bf16 v[82:85], v[192:195], v[176:179], v[82:85]
	v_mfma_f32_16x16x32_bf16 v[74:77], v[200:203], v[176:179], v[74:77]
	v_mfma_f32_16x16x32_bf16 v[70:73], v[192:195], v[184:187], v[70:73]
	v_mfma_f32_16x16x32_bf16 v[66:69], v[200:203], v[184:187], v[66:69]
	s_barrier
	s_mov_b32 m0, s62
	v_lshl_add_u64 v[206:207], v[204:205], 0, s[34:35]
	ds_read_b128 v[156:159], v136 offset:49152
	ds_read_b128 v[160:163], v136 offset:50176
	ds_read_b128 v[164:167], v136 offset:51200
	ds_read_b128 v[168:171], v136 offset:52224
	ds_read_b128 v[172:175], v136 offset:53248
	ds_read_b128 v[176:179], v136 offset:54272
	ds_read_b128 v[180:183], v136 offset:55296
	ds_read_b128 v[184:187], v136 offset:56320
	global_load_lds_dwordx4 v[206:207], off
	v_lshl_add_u64 v[204:205], v[204:205], 0, s[36:37]
	s_mov_b32 m0, s63
	s_nop 0
	global_load_lds_dwordx4 v[204:205], off
	s_waitcnt lgkmcnt(0)
	s_barrier
	v_mfma_f32_16x16x32_bf16 v[62:65], v[138:141], v[156:159], v[62:65]
	v_mfma_f32_16x16x32_bf16 v[58:61], v[148:151], v[156:159], v[58:61]
	v_mfma_f32_16x16x32_bf16 v[54:57], v[138:141], v[164:167], v[54:57]
	v_mfma_f32_16x16x32_bf16 v[46:49], v[148:151], v[164:167], v[46:49]
	v_mfma_f32_16x16x32_bf16 v[38:41], v[138:141], v[172:175], v[38:41]
	v_mfma_f32_16x16x32_bf16 v[30:33], v[148:151], v[172:175], v[30:33]
	v_mfma_f32_16x16x32_bf16 v[22:25], v[138:141], v[180:183], v[22:25]
	v_mfma_f32_16x16x32_bf16 v[14:17], v[148:151], v[180:183], v[14:17]
	v_mfma_f32_16x16x32_bf16 v[62:65], v[142:145], v[160:163], v[62:65]
	v_mfma_f32_16x16x32_bf16 v[58:61], v[152:155], v[160:163], v[58:61]
	v_mfma_f32_16x16x32_bf16 v[54:57], v[142:145], v[168:171], v[54:57]
	v_mfma_f32_16x16x32_bf16 v[46:49], v[152:155], v[168:171], v[46:49]
	v_mfma_f32_16x16x32_bf16 v[38:41], v[142:145], v[176:179], v[38:41]
	v_mfma_f32_16x16x32_bf16 v[30:33], v[152:155], v[176:179], v[30:33]
	v_mfma_f32_16x16x32_bf16 v[22:25], v[142:145], v[184:187], v[22:25]
	v_mfma_f32_16x16x32_bf16 v[14:17], v[152:155], v[184:187], v[14:17]
	s_barrier
	s_add_i32 s7, s78, s53
	v_lshl_add_u64 v[138:139], v[132:133], 0, s[18:19]
	s_mov_b32 m0, s7
	v_lshl_add_u64 v[132:133], v[132:133], 0, s[14:15]
	global_load_lds_dwordx4 v[138:139], off
	s_add_i32 m0, s7, 0x2000
	s_nop 0
	global_load_lds_dwordx4 v[132:133], off
	s_waitcnt vmcnt(6)
	s_add_i32 s6, s6, 2
	s_add_u32 s8, s8, 0x100
	s_addc_u32 s9, s9, 0
	s_add_u32 s46, s46, 0x100
	s_addc_u32 s47, s47, 0
	s_cmpk_gt_u32 s6, 0x55
	s_cbranch_scc0 .LBB0_485
	s_barrier
	v_mfma_f32_16x16x32_bf16 v[50:53], v[188:191], v[156:159], v[50:53]
	v_mfma_f32_16x16x32_bf16 v[42:45], v[196:199], v[156:159], v[42:45]
	v_mfma_f32_16x16x32_bf16 v[34:37], v[188:191], v[164:167], v[34:37]
	v_mfma_f32_16x16x32_bf16 v[26:29], v[196:199], v[164:167], v[26:29]
	v_mfma_f32_16x16x32_bf16 v[18:21], v[188:191], v[172:175], v[18:21]
	v_mfma_f32_16x16x32_bf16 v[10:13], v[196:199], v[172:175], v[10:13]
	v_mfma_f32_16x16x32_bf16 v[6:9], v[188:191], v[180:183], v[6:9]
	v_mfma_f32_16x16x32_bf16 v[2:5], v[196:199], v[180:183], v[2:5]
	v_mfma_f32_16x16x32_bf16 v[50:53], v[192:195], v[160:163], v[50:53]
	v_mfma_f32_16x16x32_bf16 v[42:45], v[200:203], v[160:163], v[42:45]
	v_mfma_f32_16x16x32_bf16 v[34:37], v[192:195], v[168:171], v[34:37]
	v_mfma_f32_16x16x32_bf16 v[26:29], v[200:203], v[168:171], v[26:29]
	v_mfma_f32_16x16x32_bf16 v[18:21], v[192:195], v[176:179], v[18:21]
	v_mfma_f32_16x16x32_bf16 v[10:13], v[200:203], v[176:179], v[10:13]
	v_mfma_f32_16x16x32_bf16 v[6:9], v[192:195], v[184:187], v[6:9]
	v_mfma_f32_16x16x32_bf16 v[2:5], v[200:203], v[184:187], v[2:5]
	s_barrier
	v_mov_b32_e32 v137, v134
	s_lshl_b32 s6, s86, 8
	v_ashrrev_i32_e32 v132, 2, v137
	s_or_b32 s6, s6, s59
	v_and_b32_e32 v132, -4, v132
	v_add_u32_e32 v132, s6, v132
	s_lshl_b32 s6, s85, 8
	s_add_i32 s6, s6, s58
	v_and_or_b32 v188, v137, 15, s6
	v_ashrrev_i32_e32 v189, 31, v188
	v_ashrrev_i32_e32 v133, 31, v132
	v_lshlrev_b64 v[206:207], 13, v[188:189]
	v_or_b32_e32 v156, 16, v188
	v_or_b32_e32 v172, 32, v188
	v_or_b32_e32 v188, 48, v188
	v_lshlrev_b64 v[132:133], 2, v[132:133]
	v_ashrrev_i32_e32 v157, 31, v156
	v_ashrrev_i32_e32 v173, 31, v172
	v_ashrrev_i32_e32 v189, 31, v188
	v_lshl_add_u64 v[204:205], s[4:5], 0, v[132:133]
	v_lshlrev_b64 v[208:209], 13, v[156:157]
	v_lshlrev_b64 v[210:211], 13, v[172:173]
	v_lshlrev_b64 v[212:213], 13, v[188:189]
	v_lshl_add_u64 v[152:153], v[204:205], 0, v[206:207]
	v_lshl_add_u64 v[168:169], v[204:205], 0, v[208:209]
	v_lshl_add_u64 v[184:185], v[204:205], 0, v[210:211]
	v_lshl_add_u64 v[200:201], v[204:205], 0, v[212:213]
	global_load_dwordx4 v[138:141], v[152:153], off
	global_load_dwordx4 v[142:145], v[152:153], off offset:64
	global_load_dwordx4 v[148:151], v[152:153], off offset:512
	s_nop 0
	global_load_dwordx4 v[152:155], v[152:153], off offset:576
	s_nop 0
	global_load_dwordx4 v[156:159], v[168:169], off
	global_load_dwordx4 v[160:163], v[168:169], off offset:64
	global_load_dwordx4 v[164:167], v[168:169], off offset:512
	s_nop 0
	global_load_dwordx4 v[168:171], v[168:169], off offset:576
	s_nop 0
	global_load_dwordx4 v[172:175], v[184:185], off
	global_load_dwordx4 v[176:179], v[184:185], off offset:64
	global_load_dwordx4 v[180:183], v[184:185], off offset:512
	s_nop 0
	global_load_dwordx4 v[184:187], v[184:185], off offset:576
	s_nop 0
	global_load_dwordx4 v[188:191], v[200:201], off
	global_load_dwordx4 v[192:195], v[200:201], off offset:64
	global_load_dwordx4 v[196:199], v[200:201], off offset:512
	s_nop 0
	global_load_dwordx4 v[200:203], v[200:201], off offset:576
	s_waitcnt vmcnt(0) lgkmcnt(0)
	v_pk_fma_f32 v[126:127], v[126:127], 0.5, v[138:139] op_sel_hi:[1,0,1]
	v_lshl_add_u64 v[138:139], s[4:5], 0, v[206:207]
	v_lshl_add_u64 v[138:139], v[138:139], 0, v[132:133]
	v_pk_fma_f32 v[116:117], v[116:117], 0.5, v[150:151] op_sel_hi:[1,0,1]
	v_pk_fma_f32 v[114:115], v[114:115], 0.5, v[148:149] op_sel_hi:[1,0,1]
	global_store_dwordx4 v[138:139], v[114:117], off offset:512
	v_pk_fma_f32 v[100:101], v[100:101], 0.5, v[166:167] op_sel_hi:[1,0,1]
	v_pk_fma_f32 v[98:99], v[98:99], 0.5, v[164:165] op_sel_hi:[1,0,1]
	v_lshl_add_u64 v[114:115], s[4:5], 0, v[208:209]
	v_lshl_add_u64 v[114:115], v[114:115], 0, v[132:133]
	global_store_dwordx4 v[114:115], v[98:101], off offset:512
	v_pk_fma_f32 v[84:85], v[84:85], 0.5, v[182:183] op_sel_hi:[1,0,1]
	v_pk_fma_f32 v[82:83], v[82:83], 0.5, v[180:181] op_sel_hi:[1,0,1]
	v_lshl_add_u64 v[98:99], s[4:5], 0, v[210:211]
	v_lshl_add_u64 v[98:99], v[98:99], 0, v[132:133]
	v_pk_fma_f32 v[108:109], v[108:109], 0.5, v[154:155] op_sel_hi:[1,0,1]
	v_pk_fma_f32 v[106:107], v[106:107], 0.5, v[152:153] op_sel_hi:[1,0,1]
	v_pk_fma_f32 v[92:93], v[92:93], 0.5, v[170:171] op_sel_hi:[1,0,1]
	v_pk_fma_f32 v[90:91], v[90:91], 0.5, v[168:169] op_sel_hi:[1,0,1]
	global_store_dwordx4 v[98:99], v[82:85], off offset:512
	v_pk_fma_f32 v[76:77], v[76:77], 0.5, v[186:187] op_sel_hi:[1,0,1]
	v_pk_fma_f32 v[74:75], v[74:75], 0.5, v[184:185] op_sel_hi:[1,0,1]
	v_lshl_add_u64 v[82:83], s[4:5], 0, v[212:213]
	global_store_dwordx4 v[138:139], v[106:109], off offset:576
	global_store_dwordx4 v[114:115], v[90:93], off offset:576
	global_store_dwordx4 v[98:99], v[74:77], off offset:576
	v_pk_fma_f32 v[108:109], v[120:121], 0.5, v[158:159] op_sel_hi:[1,0,1]
	v_pk_fma_f32 v[106:107], v[118:119], 0.5, v[156:157] op_sel_hi:[1,0,1]
	v_pk_fma_f32 v[92:93], v[104:105], 0.5, v[174:175] op_sel_hi:[1,0,1]
	v_pk_fma_f32 v[90:91], v[102:103], 0.5, v[172:173] op_sel_hi:[1,0,1]
	v_pk_fma_f32 v[76:77], v[88:89], 0.5, v[190:191] op_sel_hi:[1,0,1]
	v_pk_fma_f32 v[74:75], v[86:87], 0.5, v[188:189] op_sel_hi:[1,0,1]
	v_lshl_add_u64 v[82:83], v[82:83], 0, v[132:133]
	v_pk_fma_f32 v[128:129], v[128:129], 0.5, v[140:141] op_sel_hi:[1,0,1]
	v_pk_fma_f32 v[124:125], v[124:125], 0.5, v[144:145] op_sel_hi:[1,0,1]
	v_pk_fma_f32 v[122:123], v[122:123], 0.5, v[142:143] op_sel_hi:[1,0,1]
	global_store_dwordx4 v[114:115], v[106:109], off
	global_store_dwordx4 v[98:99], v[90:93], off
	global_store_dwordx4 v[82:83], v[74:77], off
	v_pk_fma_f32 v[108:109], v[112:113], 0.5, v[162:163] op_sel_hi:[1,0,1]
	v_pk_fma_f32 v[106:107], v[110:111], 0.5, v[160:161] op_sel_hi:[1,0,1]
	v_pk_fma_f32 v[92:93], v[96:97], 0.5, v[178:179] op_sel_hi:[1,0,1]
	v_pk_fma_f32 v[90:91], v[94:95], 0.5, v[176:177] op_sel_hi:[1,0,1]
	v_pk_fma_f32 v[76:77], v[80:81], 0.5, v[194:195] op_sel_hi:[1,0,1]
	v_pk_fma_f32 v[74:75], v[78:79], 0.5, v[192:193] op_sel_hi:[1,0,1]
	v_pk_fma_f32 v[72:73], v[72:73], 0.5, v[198:199] op_sel_hi:[1,0,1]
	v_pk_fma_f32 v[70:71], v[70:71], 0.5, v[196:197] op_sel_hi:[1,0,1]
	v_pk_fma_f32 v[68:69], v[68:69], 0.5, v[202:203] op_sel_hi:[1,0,1]
	v_pk_fma_f32 v[66:67], v[66:67], 0.5, v[200:201] op_sel_hi:[1,0,1]
	global_store_dwordx4 v[138:139], v[126:129], off
	global_store_dwordx4 v[138:139], v[122:125], off offset:64
	global_store_dwordx4 v[114:115], v[106:109], off offset:64
	global_store_dwordx4 v[98:99], v[90:93], off offset:64
	global_store_dwordx4 v[82:83], v[74:77], off offset:64
	global_store_dwordx4 v[82:83], v[70:73], off offset:512
	global_store_dwordx4 v[82:83], v[66:69], off offset:576
	s_mov_b64 s[6:7], 0x120000
	v_lshl_add_u64 v[140:141], v[206:207], 0, s[6:7]
	s_mov_b64 s[6:7], 0x140000
	v_lshl_add_u64 v[138:139], v[206:207], 0, s[0:1]
	v_lshl_add_u64 v[142:143], v[206:207], 0, s[6:7]
	v_lshl_add_u64 v[144:145], v[206:207], 0, s[28:29]
	v_lshl_add_u64 v[78:79], v[204:205], 0, v[138:139]
	v_lshl_add_u64 v[94:95], v[204:205], 0, v[140:141]
	v_lshl_add_u64 v[110:111], v[204:205], 0, v[142:143]
	v_lshl_add_u64 v[126:127], v[204:205], 0, v[144:145]
	global_load_dwordx4 v[66:69], v[78:79], off
	global_load_dwordx4 v[70:73], v[78:79], off offset:64
	global_load_dwordx4 v[74:77], v[78:79], off offset:512
	s_nop 0
	global_load_dwordx4 v[78:81], v[78:79], off offset:576
	s_nop 0
	global_load_dwordx4 v[82:85], v[94:95], off
	global_load_dwordx4 v[86:89], v[94:95], off offset:64
	global_load_dwordx4 v[90:93], v[94:95], off offset:512
	s_nop 0
	global_load_dwordx4 v[94:97], v[94:95], off offset:576
	s_nop 0
	global_load_dwordx4 v[98:101], v[110:111], off
	global_load_dwordx4 v[102:105], v[110:111], off offset:64
	global_load_dwordx4 v[106:109], v[110:111], off offset:512
	s_nop 0
	global_load_dwordx4 v[110:113], v[110:111], off offset:576
	s_nop 0
	global_load_dwordx4 v[114:117], v[126:127], off
	global_load_dwordx4 v[118:121], v[126:127], off offset:64
	global_load_dwordx4 v[122:125], v[126:127], off offset:512
	s_nop 0
	global_load_dwordx4 v[126:129], v[126:127], off offset:576
	s_waitcnt vmcnt(0) lgkmcnt(0)
	v_pk_fma_f32 v[62:63], v[62:63], 0.5, v[66:67] op_sel_hi:[1,0,1]
	v_lshl_add_u64 v[66:67], s[4:5], 0, v[138:139]
	v_lshl_add_u64 v[66:67], v[66:67], 0, v[132:133]
	v_pk_fma_f32 v[52:53], v[52:53], 0.5, v[76:77] op_sel_hi:[1,0,1]
	v_pk_fma_f32 v[50:51], v[50:51], 0.5, v[74:75] op_sel_hi:[1,0,1]
	global_store_dwordx4 v[66:67], v[50:53], off offset:512
	v_pk_fma_f32 v[36:37], v[36:37], 0.5, v[92:93] op_sel_hi:[1,0,1]
	v_pk_fma_f32 v[34:35], v[34:35], 0.5, v[90:91] op_sel_hi:[1,0,1]
	v_lshl_add_u64 v[50:51], s[4:5], 0, v[140:141]
	v_lshl_add_u64 v[50:51], v[50:51], 0, v[132:133]
	global_store_dwordx4 v[50:51], v[34:37], off offset:512
	v_pk_fma_f32 v[20:21], v[20:21], 0.5, v[108:109] op_sel_hi:[1,0,1]
	v_pk_fma_f32 v[18:19], v[18:19], 0.5, v[106:107] op_sel_hi:[1,0,1]
	v_lshl_add_u64 v[34:35], s[4:5], 0, v[142:143]
	v_lshl_add_u64 v[34:35], v[34:35], 0, v[132:133]
	v_pk_fma_f32 v[44:45], v[44:45], 0.5, v[80:81] op_sel_hi:[1,0,1]
	v_pk_fma_f32 v[42:43], v[42:43], 0.5, v[78:79] op_sel_hi:[1,0,1]
	v_pk_fma_f32 v[28:29], v[28:29], 0.5, v[96:97] op_sel_hi:[1,0,1]
	v_pk_fma_f32 v[26:27], v[26:27], 0.5, v[94:95] op_sel_hi:[1,0,1]
	global_store_dwordx4 v[34:35], v[18:21], off offset:512
	v_pk_fma_f32 v[12:13], v[12:13], 0.5, v[112:113] op_sel_hi:[1,0,1]
	v_pk_fma_f32 v[10:11], v[10:11], 0.5, v[110:111] op_sel_hi:[1,0,1]
	v_lshl_add_u64 v[18:19], s[4:5], 0, v[144:145]
	global_store_dwordx4 v[66:67], v[42:45], off offset:576
	global_store_dwordx4 v[50:51], v[26:29], off offset:576
	global_store_dwordx4 v[34:35], v[10:13], off offset:576
	v_pk_fma_f32 v[44:45], v[56:57], 0.5, v[84:85] op_sel_hi:[1,0,1]
	v_pk_fma_f32 v[42:43], v[54:55], 0.5, v[82:83] op_sel_hi:[1,0,1]
	v_pk_fma_f32 v[28:29], v[40:41], 0.5, v[100:101] op_sel_hi:[1,0,1]
	v_pk_fma_f32 v[26:27], v[38:39], 0.5, v[98:99] op_sel_hi:[1,0,1]
	v_pk_fma_f32 v[12:13], v[24:25], 0.5, v[116:117] op_sel_hi:[1,0,1]
	v_pk_fma_f32 v[10:11], v[22:23], 0.5, v[114:115] op_sel_hi:[1,0,1]
	v_lshl_add_u64 v[18:19], v[18:19], 0, v[132:133]
	v_pk_fma_f32 v[64:65], v[64:65], 0.5, v[68:69] op_sel_hi:[1,0,1]
	v_pk_fma_f32 v[60:61], v[60:61], 0.5, v[72:73] op_sel_hi:[1,0,1]
	v_pk_fma_f32 v[58:59], v[58:59], 0.5, v[70:71] op_sel_hi:[1,0,1]
	global_store_dwordx4 v[50:51], v[42:45], off
	global_store_dwordx4 v[34:35], v[26:29], off
	global_store_dwordx4 v[18:19], v[10:13], off
	v_pk_fma_f32 v[44:45], v[48:49], 0.5, v[88:89] op_sel_hi:[1,0,1]
	v_pk_fma_f32 v[42:43], v[46:47], 0.5, v[86:87] op_sel_hi:[1,0,1]
	v_pk_fma_f32 v[28:29], v[32:33], 0.5, v[104:105] op_sel_hi:[1,0,1]
	v_pk_fma_f32 v[26:27], v[30:31], 0.5, v[102:103] op_sel_hi:[1,0,1]
	v_pk_fma_f32 v[12:13], v[16:17], 0.5, v[120:121] op_sel_hi:[1,0,1]
	v_pk_fma_f32 v[10:11], v[14:15], 0.5, v[118:119] op_sel_hi:[1,0,1]
	v_pk_fma_f32 v[8:9], v[8:9], 0.5, v[124:125] op_sel_hi:[1,0,1]
	v_pk_fma_f32 v[6:7], v[6:7], 0.5, v[122:123] op_sel_hi:[1,0,1]
	v_pk_fma_f32 v[4:5], v[4:5], 0.5, v[128:129] op_sel_hi:[1,0,1]
	v_pk_fma_f32 v[2:3], v[2:3], 0.5, v[126:127] op_sel_hi:[1,0,1]
	global_store_dwordx4 v[66:67], v[62:65], off
	global_store_dwordx4 v[66:67], v[58:61], off offset:64
	global_store_dwordx4 v[50:51], v[42:45], off offset:64
	global_store_dwordx4 v[34:35], v[26:29], off offset:64
	global_store_dwordx4 v[18:19], v[10:13], off offset:64
	global_store_dwordx4 v[18:19], v[6:9], off offset:512
	global_store_dwordx4 v[18:19], v[2:5], off offset:576
	s_and_b64 vcc, exec, s[40:41]
	s_mov_b32 s85, s10
	s_mov_b32 s86, s11
	s_mov_b64 s[8:9], s[44:45]
	s_mov_b64 s[6:7], s[42:43]
	s_movk_i32 s89, 0x37ff
	s_mov_b32 s88, 0x16000
	s_movk_i32 s91, 0x60
	s_mov_b32 s78, 0x2a000000
	s_mov_b32 s79, 0x3fffe
	s_mov_b32 s90, 0xc0000
	s_cbranch_vccz .LBB0_478
	s_waitcnt vmcnt(0)
	s_cmpk_gt_u32 s48, 0xff
	s_cbranch_scc1 .LBB0_489
	s_barrier

.Lrot_enter_5:
	s_add_u32 s8, s6, 0x100
	s_addc_u32 s9, s7, 0
	s_add_i32 s78, 0, 0x10000
	v_add_u32_e32 v134, s78, v137
	ds_read_b128 v[140:143], v134
	ds_read_b128 v[148:151], v134 offset:1024
	ds_read_b128 v[152:155], v134 offset:2048
	ds_read_b128 v[156:159], v134 offset:3072
	s_cmp_eq_u32 s87, 28
	s_cselect_b32 s89, s43, s9
	s_cselect_b32 s88, s42, s8
	s_cselect_b32 s91, s47, s86
	s_cselect_b32 s90, s46, s41
	v_lshl_add_u64 v[134:135], s[6:7], 0, v[132:133]
	v_lshl_add_u64 v[144:145], v[134:135], 0, s[16:17]
	s_add_i32 m0, s49, 0xc000
	ds_read_b128 v[160:163], v138
	ds_read_b128 v[164:167], v138 offset:1024
	ds_read_b128 v[168:171], v138 offset:2048
	ds_read_b128 v[172:175], v138 offset:3072
	ds_read_b128 v[176:179], v138 offset:4096
	ds_read_b128 v[180:183], v138 offset:5120
	ds_read_b128 v[184:187], v138 offset:6144
	ds_read_b128 v[188:191], v138 offset:7168
	global_load_lds_dwordx4 v[144:145], off
	v_lshl_add_u64 v[134:135], v[134:135], 0, s[80:81]
	s_add_i32 m0, s49, 0xe000
	s_nop 0
	global_load_lds_dwordx4 v[134:135], off
	s_waitcnt lgkmcnt(8)
	s_barrier
	s_waitcnt lgkmcnt(0)
	v_mfma_f32_16x16x32_bf16 v[126:129], v[140:143], v[160:163], v[126:129]
	v_mfma_f32_16x16x32_bf16 v[118:121], v[152:155], v[160:163], v[118:121]
	v_mfma_f32_16x16x32_bf16 v[110:113], v[140:143], v[168:171], v[110:113]
	v_mfma_f32_16x16x32_bf16 v[102:105], v[152:155], v[168:171], v[102:105]
	v_mfma_f32_16x16x32_bf16 v[94:97], v[140:143], v[176:179], v[94:97]
	v_mfma_f32_16x16x32_bf16 v[86:89], v[152:155], v[176:179], v[86:89]
	v_mfma_f32_16x16x32_bf16 v[78:81], v[140:143], v[184:187], v[78:81]
	v_mfma_f32_16x16x32_bf16 v[70:73], v[152:155], v[184:187], v[70:73]
	v_mfma_f32_16x16x32_bf16 v[126:129], v[148:151], v[164:167], v[126:129]
	v_mfma_f32_16x16x32_bf16 v[118:121], v[156:159], v[164:167], v[118:121]
	v_mfma_f32_16x16x32_bf16 v[110:113], v[148:151], v[172:175], v[110:113]
	v_mfma_f32_16x16x32_bf16 v[102:105], v[156:159], v[172:175], v[102:105]
	v_mfma_f32_16x16x32_bf16 v[94:97], v[148:151], v[180:183], v[94:97]
	v_mfma_f32_16x16x32_bf16 v[86:89], v[156:159], v[180:183], v[86:89]
	v_mfma_f32_16x16x32_bf16 v[78:81], v[148:151], v[188:191], v[78:81]
	v_mfma_f32_16x16x32_bf16 v[70:73], v[156:159], v[188:191], v[70:73]
	s_barrier
	s_add_i32 s6, 0, 0x14000
	v_add_u32_e32 v134, s6, v137
	s_add_i32 s7, s78, s54
	ds_read_b128 v[192:195], v134
	ds_read_b128 v[196:199], v134 offset:1024
	ds_read_b128 v[200:203], v134 offset:2048
	ds_read_b128 v[204:207], v134 offset:3072
	v_lshl_add_u64 v[134:135], s[90:91], 0, v[0:1]
	s_mov_b32 m0, s7
	v_lshl_add_u64 v[144:145], v[134:135], 0, s[60:61]
	global_load_lds_dwordx4 v[134:135], off
	s_add_i32 m0, s7, 0x2000
	s_nop 0
	global_load_lds_dwordx4 v[144:145], off
	s_waitcnt lgkmcnt(0)
	s_barrier
	v_mfma_f32_16x16x32_bf16 v[122:125], v[192:195], v[160:163], v[122:125]
	v_mfma_f32_16x16x32_bf16 v[114:117], v[200:203], v[160:163], v[114:117]
	v_mfma_f32_16x16x32_bf16 v[106:109], v[192:195], v[168:171], v[106:109]
	v_mfma_f32_16x16x32_bf16 v[98:101], v[200:203], v[168:171], v[98:101]
	v_mfma_f32_16x16x32_bf16 v[90:93], v[192:195], v[176:179], v[90:93]
	v_mfma_f32_16x16x32_bf16 v[82:85], v[200:203], v[176:179], v[82:85]
	v_mfma_f32_16x16x32_bf16 v[74:77], v[192:195], v[184:187], v[74:77]
	v_mfma_f32_16x16x32_bf16 v[66:69], v[200:203], v[184:187], v[66:69]
	v_mfma_f32_16x16x32_bf16 v[122:125], v[196:199], v[164:167], v[122:125]
	v_mfma_f32_16x16x32_bf16 v[114:117], v[204:207], v[164:167], v[114:117]
	v_mfma_f32_16x16x32_bf16 v[106:109], v[196:199], v[172:175], v[106:109]
	v_mfma_f32_16x16x32_bf16 v[98:101], v[204:207], v[172:175], v[98:101]
	v_mfma_f32_16x16x32_bf16 v[90:93], v[196:199], v[180:183], v[90:93]
	v_mfma_f32_16x16x32_bf16 v[82:85], v[204:207], v[180:183], v[82:85]
	v_mfma_f32_16x16x32_bf16 v[74:77], v[196:199], v[188:191], v[74:77]
	v_mfma_f32_16x16x32_bf16 v[66:69], v[204:207], v[188:191], v[66:69]
	s_barrier
	s_mov_b32 m0, s49
	v_lshl_add_u64 v[144:145], s[88:89], 0, v[130:131]
	ds_read_b128 v[160:163], v138 offset:16384
	ds_read_b128 v[164:167], v138 offset:17408
	ds_read_b128 v[168:171], v138 offset:18432
	ds_read_b128 v[172:175], v138 offset:19456
	ds_read_b128 v[176:179], v138 offset:20480
	ds_read_b128 v[180:183], v138 offset:21504
	ds_read_b128 v[184:187], v138 offset:22528
	ds_read_b128 v[188:191], v138 offset:23552
	global_load_lds_dwordx4 v[144:145], off
	v_lshl_add_u64 v[208:209], v[144:145], 0, s[60:61]
	s_mov_b32 m0, s55
	s_nop 0
	global_load_lds_dwordx4 v[208:209], off
	s_waitcnt lgkmcnt(0)
	s_barrier
	v_mfma_f32_16x16x32_bf16 v[62:65], v[140:143], v[160:163], v[62:65]
	v_mfma_f32_16x16x32_bf16 v[54:57], v[152:155], v[160:163], v[54:57]
	v_mfma_f32_16x16x32_bf16 v[46:49], v[140:143], v[168:171], v[46:49]
	v_mfma_f32_16x16x32_bf16 v[38:41], v[152:155], v[168:171], v[38:41]
	v_mfma_f32_16x16x32_bf16 v[30:33], v[140:143], v[176:179], v[30:33]
	v_mfma_f32_16x16x32_bf16 v[22:25], v[152:155], v[176:179], v[22:25]
	v_mfma_f32_16x16x32_bf16 v[14:17], v[140:143], v[184:187], v[14:17]
	v_mfma_f32_16x16x32_bf16 v[6:9], v[152:155], v[184:187], v[6:9]
	v_mfma_f32_16x16x32_bf16 v[62:65], v[148:151], v[164:167], v[62:65]
	v_mfma_f32_16x16x32_bf16 v[54:57], v[156:159], v[164:167], v[54:57]
	v_mfma_f32_16x16x32_bf16 v[46:49], v[148:151], v[172:175], v[46:49]
	v_mfma_f32_16x16x32_bf16 v[38:41], v[156:159], v[172:175], v[38:41]
	v_mfma_f32_16x16x32_bf16 v[30:33], v[148:151], v[180:183], v[30:33]
	v_mfma_f32_16x16x32_bf16 v[22:25], v[156:159], v[180:183], v[22:25]
	v_mfma_f32_16x16x32_bf16 v[14:17], v[148:151], v[188:191], v[14:17]
	v_mfma_f32_16x16x32_bf16 v[6:9], v[156:159], v[188:191], v[6:9]
	s_barrier
	s_add_i32 s6, s6, s54
	v_lshl_add_u64 v[140:141], v[134:135], 0, s[20:21]
	s_mov_b32 m0, s6
	s_nop 0
	global_load_lds_dwordx4 v[140:141], off
	v_lshl_add_u64 v[140:141], v[134:135], 0, s[64:65]
	s_add_i32 m0, s6, 0x2000
	s_nop 0
	global_load_lds_dwordx4 v[140:141], off
	v_lshl_add_u64 v[230:231], v[144:145], 0, s[20:21]
	s_mov_b32 m0, s56
	s_nop 0
	global_load_lds_dwordx4 v[230:231], off
	v_lshl_add_u64 v[230:231], v[144:145], 0, s[64:65]
	s_mov_b32 m0, s57
	s_nop 0
	global_load_lds_dwordx4 v[230:231], off
	s_waitcnt vmcnt(8)
	s_barrier
	v_mfma_f32_16x16x32_bf16 v[58:61], v[192:195], v[160:163], v[58:61]
	v_mfma_f32_16x16x32_bf16 v[50:53], v[200:203], v[160:163], v[50:53]
	v_mfma_f32_16x16x32_bf16 v[42:45], v[192:195], v[168:171], v[42:45]
	v_mfma_f32_16x16x32_bf16 v[34:37], v[200:203], v[168:171], v[34:37]
	v_mfma_f32_16x16x32_bf16 v[26:29], v[192:195], v[176:179], v[26:29]
	v_mfma_f32_16x16x32_bf16 v[18:21], v[200:203], v[176:179], v[18:21]
	v_mfma_f32_16x16x32_bf16 v[10:13], v[192:195], v[184:187], v[10:13]
	v_mfma_f32_16x16x32_bf16 v[2:5], v[200:203], v[184:187], v[2:5]
	v_mfma_f32_16x16x32_bf16 v[58:61], v[196:199], v[164:167], v[58:61]
	v_mfma_f32_16x16x32_bf16 v[50:53], v[204:207], v[164:167], v[50:53]
	v_mfma_f32_16x16x32_bf16 v[42:45], v[196:199], v[172:175], v[42:45]
	v_mfma_f32_16x16x32_bf16 v[34:37], v[204:207], v[172:175], v[34:37]
	v_mfma_f32_16x16x32_bf16 v[26:29], v[196:199], v[180:183], v[26:29]
	v_mfma_f32_16x16x32_bf16 v[18:21], v[204:207], v[180:183], v[18:21]
	v_mfma_f32_16x16x32_bf16 v[10:13], v[196:199], v[188:191], v[10:13]
	v_mfma_f32_16x16x32_bf16 v[2:5], v[204:207], v[188:191], v[2:5]
	s_barrier
	s_add_i32 s6, 0, 0x18000
	v_add_u32_e32 v139, s6, v137
	ds_read_b128 v[140:143], v139
	ds_read_b128 v[148:151], v139 offset:1024
	ds_read_b128 v[152:155], v139 offset:2048
	ds_read_b128 v[156:159], v139 offset:3072
	ds_read_b128 v[160:163], v138 offset:32768
	ds_read_b128 v[164:167], v138 offset:33792
	ds_read_b128 v[168:171], v138 offset:34816
	ds_read_b128 v[172:175], v138 offset:35840
	ds_read_b128 v[176:179], v138 offset:36864
	ds_read_b128 v[180:183], v138 offset:37888
	ds_read_b128 v[184:187], v138 offset:38912
	ds_read_b128 v[188:191], v138 offset:39936
	s_waitcnt lgkmcnt(8)
	s_barrier
	s_waitcnt lgkmcnt(0)
	v_mfma_f32_16x16x32_bf16 v[126:129], v[140:143], v[160:163], v[126:129]
	v_mfma_f32_16x16x32_bf16 v[118:121], v[152:155], v[160:163], v[118:121]
	v_mfma_f32_16x16x32_bf16 v[110:113], v[140:143], v[168:171], v[110:113]
	v_mfma_f32_16x16x32_bf16 v[102:105], v[152:155], v[168:171], v[102:105]
	v_mfma_f32_16x16x32_bf16 v[94:97], v[140:143], v[176:179], v[94:97]
	v_mfma_f32_16x16x32_bf16 v[86:89], v[152:155], v[176:179], v[86:89]
	v_mfma_f32_16x16x32_bf16 v[78:81], v[140:143], v[184:187], v[78:81]
	v_mfma_f32_16x16x32_bf16 v[70:73], v[152:155], v[184:187], v[70:73]
	v_mfma_f32_16x16x32_bf16 v[126:129], v[148:151], v[164:167], v[126:129]
	v_mfma_f32_16x16x32_bf16 v[118:121], v[156:159], v[164:167], v[118:121]
	v_mfma_f32_16x16x32_bf16 v[110:113], v[148:151], v[172:175], v[110:113]
	v_mfma_f32_16x16x32_bf16 v[102:105], v[156:159], v[172:175], v[102:105]
	v_mfma_f32_16x16x32_bf16 v[94:97], v[148:151], v[180:183], v[94:97]
	v_mfma_f32_16x16x32_bf16 v[86:89], v[156:159], v[180:183], v[86:89]
	v_mfma_f32_16x16x32_bf16 v[78:81], v[148:151], v[188:191], v[78:81]
	v_mfma_f32_16x16x32_bf16 v[70:73], v[156:159], v[188:191], v[70:73]
	s_barrier
	s_add_i32 s7, 0, 0x1c000
	s_add_i32 s6, s6, s54
	v_add_u32_e32 v139, s7, v137
	v_lshl_add_u64 v[208:209], v[134:135], 0, s[34:35]
	s_mov_b32 m0, s6
	ds_read_b128 v[192:195], v139
	ds_read_b128 v[196:199], v139 offset:1024
	ds_read_b128 v[200:203], v139 offset:2048
	ds_read_b128 v[204:207], v139 offset:3072
	global_load_lds_dwordx4 v[208:209], off
	v_lshl_add_u64 v[208:209], v[134:135], 0, s[66:67]
	s_add_i32 m0, s6, 0x2000
	s_nop 0
	global_load_lds_dwordx4 v[208:209], off
	s_waitcnt lgkmcnt(0)
	s_barrier
	v_mfma_f32_16x16x32_bf16 v[122:125], v[192:195], v[160:163], v[122:125]
	v_mfma_f32_16x16x32_bf16 v[114:117], v[200:203], v[160:163], v[114:117]
	v_mfma_f32_16x16x32_bf16 v[106:109], v[192:195], v[168:171], v[106:109]
	v_mfma_f32_16x16x32_bf16 v[98:101], v[200:203], v[168:171], v[98:101]
	v_mfma_f32_16x16x32_bf16 v[90:93], v[192:195], v[176:179], v[90:93]
	v_mfma_f32_16x16x32_bf16 v[82:85], v[200:203], v[176:179], v[82:85]
	v_mfma_f32_16x16x32_bf16 v[74:77], v[192:195], v[184:187], v[74:77]
	v_mfma_f32_16x16x32_bf16 v[66:69], v[200:203], v[184:187], v[66:69]
	v_mfma_f32_16x16x32_bf16 v[122:125], v[196:199], v[164:167], v[122:125]
	v_mfma_f32_16x16x32_bf16 v[114:117], v[204:207], v[164:167], v[114:117]
	v_mfma_f32_16x16x32_bf16 v[106:109], v[196:199], v[172:175], v[106:109]
	v_mfma_f32_16x16x32_bf16 v[98:101], v[204:207], v[172:175], v[98:101]
	v_mfma_f32_16x16x32_bf16 v[90:93], v[196:199], v[180:183], v[90:93]
	v_mfma_f32_16x16x32_bf16 v[82:85], v[204:207], v[180:183], v[82:85]
	v_mfma_f32_16x16x32_bf16 v[74:77], v[196:199], v[188:191], v[74:77]
	v_mfma_f32_16x16x32_bf16 v[66:69], v[204:207], v[188:191], v[66:69]
	s_barrier
	s_mov_b32 m0, s59
	v_lshl_add_u64 v[208:209], v[144:145], 0, s[34:35]
	ds_read_b128 v[160:163], v138 offset:49152
	ds_read_b128 v[164:167], v138 offset:50176
	ds_read_b128 v[168:171], v138 offset:51200
	ds_read_b128 v[172:175], v138 offset:52224
	ds_read_b128 v[176:179], v138 offset:53248
	ds_read_b128 v[180:183], v138 offset:54272
	ds_read_b128 v[184:187], v138 offset:55296
	ds_read_b128 v[188:191], v138 offset:56320
	global_load_lds_dwordx4 v[208:209], off
	v_lshl_add_u64 v[144:145], v[144:145], 0, s[66:67]
	s_mov_b32 m0, s62
	s_nop 0
	global_load_lds_dwordx4 v[144:145], off
	s_waitcnt lgkmcnt(0)
	s_barrier
	v_mfma_f32_16x16x32_bf16 v[62:65], v[140:143], v[160:163], v[62:65]
	v_mfma_f32_16x16x32_bf16 v[54:57], v[152:155], v[160:163], v[54:57]
	v_mfma_f32_16x16x32_bf16 v[46:49], v[140:143], v[168:171], v[46:49]
	v_mfma_f32_16x16x32_bf16 v[38:41], v[152:155], v[168:171], v[38:41]
	v_mfma_f32_16x16x32_bf16 v[30:33], v[140:143], v[176:179], v[30:33]
	v_mfma_f32_16x16x32_bf16 v[22:25], v[152:155], v[176:179], v[22:25]
	v_mfma_f32_16x16x32_bf16 v[14:17], v[140:143], v[184:187], v[14:17]
	v_mfma_f32_16x16x32_bf16 v[6:9], v[152:155], v[184:187], v[6:9]
	v_mfma_f32_16x16x32_bf16 v[62:65], v[148:151], v[164:167], v[62:65]
	v_mfma_f32_16x16x32_bf16 v[54:57], v[156:159], v[164:167], v[54:57]
	v_mfma_f32_16x16x32_bf16 v[46:49], v[148:151], v[172:175], v[46:49]
	v_mfma_f32_16x16x32_bf16 v[38:41], v[156:159], v[172:175], v[38:41]
	v_mfma_f32_16x16x32_bf16 v[30:33], v[148:151], v[180:183], v[30:33]
	v_mfma_f32_16x16x32_bf16 v[22:25], v[156:159], v[180:183], v[22:25]
	v_mfma_f32_16x16x32_bf16 v[14:17], v[148:151], v[188:191], v[14:17]
	v_mfma_f32_16x16x32_bf16 v[6:9], v[156:159], v[188:191], v[6:9]
	s_barrier
	s_add_i32 s6, s7, s54
	v_lshl_add_u64 v[140:141], v[134:135], 0, s[16:17]
	s_mov_b32 m0, s6
	v_lshl_add_u64 v[134:135], v[134:135], 0, s[80:81]
	global_load_lds_dwordx4 v[140:141], off
	s_add_i32 m0, s6, 0x2000
	s_nop 0
	global_load_lds_dwordx4 v[134:135], off
	s_waitcnt vmcnt(6)
	s_add_i32 s87, s87, 2
	s_add_u32 s41, s41, 0x100
	s_addc_u32 s86, s86, 0
	s_cmp_gt_u32 s87, 29
	s_mov_b64 s[6:7], s[8:9]
	s_cbranch_scc0 .LBB0_503
	s_barrier
	v_mfma_f32_16x16x32_bf16 v[58:61], v[192:195], v[160:163], v[58:61]
	v_mfma_f32_16x16x32_bf16 v[50:53], v[200:203], v[160:163], v[50:53]
	v_mfma_f32_16x16x32_bf16 v[42:45], v[192:195], v[168:171], v[42:45]
	v_mfma_f32_16x16x32_bf16 v[34:37], v[200:203], v[168:171], v[34:37]
	v_mfma_f32_16x16x32_bf16 v[26:29], v[192:195], v[176:179], v[26:29]
	v_mfma_f32_16x16x32_bf16 v[18:21], v[200:203], v[176:179], v[18:21]
	v_mfma_f32_16x16x32_bf16 v[10:13], v[192:195], v[184:187], v[10:13]
	v_mfma_f32_16x16x32_bf16 v[2:5], v[200:203], v[184:187], v[2:5]
	v_mfma_f32_16x16x32_bf16 v[58:61], v[196:199], v[164:167], v[58:61]
	v_mfma_f32_16x16x32_bf16 v[50:53], v[204:207], v[164:167], v[50:53]
	v_mfma_f32_16x16x32_bf16 v[42:45], v[196:199], v[172:175], v[42:45]
	v_mfma_f32_16x16x32_bf16 v[34:37], v[204:207], v[172:175], v[34:37]
	v_mfma_f32_16x16x32_bf16 v[26:29], v[196:199], v[180:183], v[26:29]
	v_mfma_f32_16x16x32_bf16 v[18:21], v[204:207], v[180:183], v[18:21]
	v_mfma_f32_16x16x32_bf16 v[10:13], v[196:199], v[188:191], v[10:13]
	v_mfma_f32_16x16x32_bf16 v[2:5], v[204:207], v[188:191], v[2:5]
	s_barrier
	v_mul_f32_e32 v144, 0xbfb8aa3b, v126
	v_exp_f32_e32 v144, v144
	v_mov_b32_e32 v134, v136
	s_lshl_b32 s6, s48, 8
	v_add_f32_e32 v144, 1.0, v144
	v_rcp_f32_e32 v144, v144
	s_add_i32 s6, s6, s10
	v_and_or_b32 v139, v134, 15, s6
	s_lshl_b32 s6, s85, 7
	v_mul_f32_e32 v126, v126, v144
	v_mul_f32_e32 v122, v126, v122
	v_mul_f32_e32 v126, 0xbfb8aa3b, v127
	v_exp_f32_e32 v126, v126
	v_ashrrev_i32_e32 v134, 1, v134
	s_or_b32 s6, s6, s58
	v_and_b32_e32 v134, -8, v134
	v_add_f32_e32 v126, 1.0, v126
	v_rcp_f32_e32 v126, v126
	v_add_u32_e32 v140, s6, v134
	v_ashrrev_i32_e32 v141, 31, v140
	v_mov_b64_e32 v[134:135], s[4:5]
	v_mul_f32_e32 v126, v127, v126
	v_mul_f32_e32 v123, v126, v123
	v_mul_f32_e32 v126, 0xbfb8aa3b, v128
	v_exp_f32_e32 v126, v126
	v_mad_i64_i32 v[142:143], s[6:7], v139, s74, v[134:135]
	s_and_b64 vcc, exec, s[44:45]
	v_add_f32_e32 v126, 1.0, v126
	v_rcp_f32_e32 v126, v126
	s_mov_b32 s48, s40
	s_mov_b32 s85, s84
	s_mov_b64 s[8:9], s[46:47]
	v_mul_f32_e32 v126, v128, v126
	v_mul_f32_e32 v124, v126, v124
	v_mul_f32_e32 v126, 0xbfb8aa3b, v129
	v_exp_f32_e32 v126, v126
	s_nop 0
	v_add_f32_e32 v126, 1.0, v126
	v_rcp_f32_e32 v126, v126
	s_nop 0
	v_mul_f32_e32 v126, v129, v126
	v_mul_f32_e32 v125, v126, v125
	v_mul_f32_e32 v126, 0xbfb8aa3b, v118
	v_exp_f32_e32 v126, v126
	s_nop 0
	v_add_f32_e32 v126, 1.0, v126
	v_rcp_f32_e32 v126, v126
	s_nop 0
	v_mul_f32_e32 v118, v118, v126
	v_mul_f32_e32 v118, v118, v114
	v_mul_f32_e32 v114, 0xbfb8aa3b, v119
	v_exp_f32_e32 v114, v114
	s_nop 0
	v_add_f32_e32 v114, 1.0, v114
	v_rcp_f32_e32 v114, v114
	s_nop 0
	v_mul_f32_e32 v114, v119, v114
	v_mul_f32_e32 v119, v114, v115
	v_mul_f32_e32 v114, 0xbfb8aa3b, v120
	v_exp_f32_e32 v114, v114
	s_nop 0
	v_add_f32_e32 v114, 1.0, v114
	v_rcp_f32_e32 v114, v114
	s_nop 0
	v_mul_f32_e32 v114, v120, v114
	v_mul_f32_e32 v126, v114, v116
	v_mul_f32_e32 v114, 0xbfb8aa3b, v121
	v_exp_f32_e32 v114, v114
	v_cvt_pk_bf16_f32 v116, v122, v123
	s_nop 0
	v_add_f32_e32 v114, 1.0, v114
	v_rcp_f32_e32 v114, v114
	s_nop 0
	v_mul_f32_e32 v114, v121, v114
	v_mul_f32_e32 v127, v114, v117
	v_lshlrev_b64 v[114:115], 1, v[140:141]
	v_lshl_add_u64 v[120:121], v[142:143], 0, v[114:115]
	v_cvt_pk_bf16_f32 v117, v124, v125
	v_cvt_pk_bf16_f32 v118, v118, v119
	v_cvt_pk_bf16_f32 v119, v126, v127
	global_store_dwordx4 v[120:121], v[116:119], off
	s_nop 1
	v_mul_f32_e32 v118, 0xbfb8aa3b, v110
	v_exp_f32_e32 v118, v118
	v_or_b32_e32 v116, 16, v139
	v_mad_i64_i32 v[116:117], s[6:7], v116, s74, v[134:135]
	v_add_f32_e32 v118, 1.0, v118
	v_rcp_f32_e32 v118, v118
	s_nop 0
	v_mul_f32_e32 v110, v110, v118
	v_mul_f32_e32 v106, v110, v106
	v_mul_f32_e32 v110, 0xbfb8aa3b, v111
	v_exp_f32_e32 v110, v110
	s_nop 0
	v_add_f32_e32 v110, 1.0, v110
	v_rcp_f32_e32 v110, v110
	s_nop 0
	v_mul_f32_e32 v110, v111, v110
	v_mul_f32_e32 v107, v110, v107
	v_mul_f32_e32 v110, 0xbfb8aa3b, v112
	v_exp_f32_e32 v110, v110
	s_nop 0
	v_add_f32_e32 v110, 1.0, v110
	v_rcp_f32_e32 v110, v110
	s_nop 0
	v_mul_f32_e32 v110, v112, v110
	v_mul_f32_e32 v108, v110, v108
	v_mul_f32_e32 v110, 0xbfb8aa3b, v113
	v_exp_f32_e32 v110, v110
	s_nop 0
	v_add_f32_e32 v110, 1.0, v110
	v_rcp_f32_e32 v110, v110
	s_nop 0
	v_mul_f32_e32 v110, v113, v110
	v_mul_f32_e32 v109, v110, v109
	v_mul_f32_e32 v110, 0xbfb8aa3b, v102
	v_exp_f32_e32 v110, v110
	s_nop 0
	v_add_f32_e32 v110, 1.0, v110
	v_rcp_f32_e32 v110, v110
	s_nop 0
	v_mul_f32_e32 v102, v102, v110
	v_mul_f32_e32 v110, v102, v98
	v_mul_f32_e32 v98, 0xbfb8aa3b, v103
	v_exp_f32_e32 v98, v98
	s_nop 0
	v_add_f32_e32 v98, 1.0, v98
	v_rcp_f32_e32 v98, v98
	s_nop 0
	v_mul_f32_e32 v98, v103, v98
	v_mul_f32_e32 v111, v98, v99
	v_mul_f32_e32 v98, 0xbfb8aa3b, v104
	v_exp_f32_e32 v98, v98
	v_lshl_add_u64 v[102:103], v[116:117], 0, v[114:115]
	v_add_f32_e32 v98, 1.0, v98
	v_rcp_f32_e32 v98, v98
	s_nop 0
	v_mul_f32_e32 v98, v104, v98
	v_mul_f32_e32 v104, v98, v100
	v_mul_f32_e32 v98, 0xbfb8aa3b, v105
	v_exp_f32_e32 v98, v98
	s_nop 0
	v_add_f32_e32 v98, 1.0, v98
	v_rcp_f32_e32 v98, v98
	s_nop 0
	v_mul_f32_e32 v98, v105, v98
	v_mul_f32_e32 v101, v98, v101
	v_cvt_pk_bf16_f32 v98, v106, v107
	v_cvt_pk_bf16_f32 v99, v108, v109
	v_cvt_pk_bf16_f32 v100, v110, v111
	v_cvt_pk_bf16_f32 v101, v104, v101
	global_store_dwordx4 v[102:103], v[98:101], off
	s_nop 1
	v_mul_f32_e32 v100, 0xbfb8aa3b, v94
	v_exp_f32_e32 v100, v100
	v_or_b32_e32 v98, 32, v139
	v_mad_i64_i32 v[98:99], s[6:7], v98, s74, v[134:135]
	v_add_f32_e32 v100, 1.0, v100
	v_rcp_f32_e32 v100, v100
	s_nop 0
	v_mul_f32_e32 v94, v94, v100
	v_mul_f32_e32 v90, v94, v90
	v_mul_f32_e32 v94, 0xbfb8aa3b, v95
	v_exp_f32_e32 v94, v94
	s_nop 0
	v_add_f32_e32 v94, 1.0, v94
	v_rcp_f32_e32 v94, v94
	s_nop 0
	v_mul_f32_e32 v94, v95, v94
	v_mul_f32_e32 v91, v94, v91
	v_mul_f32_e32 v94, 0xbfb8aa3b, v96
	v_exp_f32_e32 v94, v94
	s_nop 0
	v_add_f32_e32 v94, 1.0, v94
	v_rcp_f32_e32 v94, v94
	s_nop 0
	v_mul_f32_e32 v94, v96, v94
	v_mul_f32_e32 v92, v94, v92
	v_mul_f32_e32 v94, 0xbfb8aa3b, v97
	v_exp_f32_e32 v94, v94
	s_nop 0
	v_add_f32_e32 v94, 1.0, v94
	v_rcp_f32_e32 v94, v94
	s_nop 0
	v_mul_f32_e32 v94, v97, v94
	v_mul_f32_e32 v93, v94, v93
	v_mul_f32_e32 v94, 0xbfb8aa3b, v86
	v_exp_f32_e32 v94, v94
	s_nop 0
	v_add_f32_e32 v94, 1.0, v94
	v_rcp_f32_e32 v94, v94
	s_nop 0
	v_mul_f32_e32 v86, v86, v94
	v_mul_f32_e32 v94, v86, v82
	v_mul_f32_e32 v82, 0xbfb8aa3b, v87
	v_exp_f32_e32 v82, v82
	s_nop 0
	v_add_f32_e32 v82, 1.0, v82
	v_rcp_f32_e32 v82, v82
	s_nop 0
	v_mul_f32_e32 v82, v87, v82
	v_mul_f32_e32 v95, v82, v83
	v_mul_f32_e32 v82, 0xbfb8aa3b, v88
	v_exp_f32_e32 v82, v82
	v_lshl_add_u64 v[86:87], v[98:99], 0, v[114:115]
	v_add_f32_e32 v82, 1.0, v82
	v_rcp_f32_e32 v82, v82
	s_nop 0
	v_mul_f32_e32 v82, v88, v82
	v_mul_f32_e32 v88, v82, v84
	v_mul_f32_e32 v82, 0xbfb8aa3b, v89
	v_exp_f32_e32 v82, v82
	s_nop 0
	v_add_f32_e32 v82, 1.0, v82
	v_rcp_f32_e32 v82, v82
	s_nop 0
	v_mul_f32_e32 v82, v89, v82
	v_mul_f32_e32 v85, v82, v85
	v_cvt_pk_bf16_f32 v82, v90, v91
	v_cvt_pk_bf16_f32 v83, v92, v93
	v_cvt_pk_bf16_f32 v84, v94, v95
	v_cvt_pk_bf16_f32 v85, v88, v85
	global_store_dwordx4 v[86:87], v[82:85], off
	s_nop 1
	v_mul_f32_e32 v84, 0xbfb8aa3b, v78
	v_exp_f32_e32 v84, v84
	v_or_b32_e32 v82, 48, v139
	v_mad_i64_i32 v[82:83], s[6:7], v82, s74, v[134:135]
	v_add_f32_e32 v84, 1.0, v84
	v_rcp_f32_e32 v84, v84
	s_nop 0
	v_mul_f32_e32 v78, v78, v84
	v_mul_f32_e32 v74, v78, v74
	v_mul_f32_e32 v78, 0xbfb8aa3b, v79
	v_exp_f32_e32 v78, v78
	s_nop 0
	v_add_f32_e32 v78, 1.0, v78
	v_rcp_f32_e32 v78, v78
	s_nop 0
	v_mul_f32_e32 v78, v79, v78
	v_mul_f32_e32 v75, v78, v75
	v_mul_f32_e32 v78, 0xbfb8aa3b, v80
	v_exp_f32_e32 v78, v78
	s_nop 0
	v_add_f32_e32 v78, 1.0, v78
	v_rcp_f32_e32 v78, v78
	s_nop 0
	v_mul_f32_e32 v78, v80, v78
	v_mul_f32_e32 v76, v78, v76
	v_mul_f32_e32 v78, 0xbfb8aa3b, v81
	v_exp_f32_e32 v78, v78
	s_nop 0
	v_add_f32_e32 v78, 1.0, v78
	v_rcp_f32_e32 v78, v78
	s_nop 0
	v_mul_f32_e32 v78, v81, v78
	v_mul_f32_e32 v77, v78, v77
	v_mul_f32_e32 v78, 0xbfb8aa3b, v70
	v_exp_f32_e32 v78, v78
	s_nop 0
	v_add_f32_e32 v78, 1.0, v78
	v_rcp_f32_e32 v78, v78
	s_nop 0
	v_mul_f32_e32 v70, v70, v78
	v_mul_f32_e32 v78, v70, v66
	v_mul_f32_e32 v66, 0xbfb8aa3b, v71
	v_exp_f32_e32 v66, v66
	s_nop 0
	v_add_f32_e32 v66, 1.0, v66
	v_rcp_f32_e32 v66, v66
	s_nop 0
	v_mul_f32_e32 v66, v71, v66
	v_mul_f32_e32 v79, v66, v67
	v_mul_f32_e32 v66, 0xbfb8aa3b, v72
	v_exp_f32_e32 v66, v66
	v_lshl_add_u64 v[70:71], v[82:83], 0, v[114:115]
	v_add_f32_e32 v66, 1.0, v66
	v_rcp_f32_e32 v66, v66
	s_nop 0
	v_mul_f32_e32 v66, v72, v66
	v_mul_f32_e32 v72, v66, v68
	v_mul_f32_e32 v66, 0xbfb8aa3b, v73
	v_exp_f32_e32 v66, v66
	s_nop 0
	v_add_f32_e32 v66, 1.0, v66
	v_rcp_f32_e32 v66, v66
	s_nop 0
	v_mul_f32_e32 v66, v73, v66
	v_mul_f32_e32 v69, v66, v69
	v_cvt_pk_bf16_f32 v66, v74, v75
	v_cvt_pk_bf16_f32 v67, v76, v77
	v_cvt_pk_bf16_f32 v68, v78, v79
	v_cvt_pk_bf16_f32 v69, v72, v69
	global_store_dwordx4 v[70:71], v[66:69], off
	s_nop 1
	v_mul_f32_e32 v68, 0xbfb8aa3b, v62
	v_exp_f32_e32 v68, v68
	v_add_u32_e32 v66, 0x80, v139
	v_mad_i64_i32 v[66:67], s[6:7], v66, s74, v[134:135]
	v_add_f32_e32 v68, 1.0, v68
	v_rcp_f32_e32 v68, v68
	s_nop 0
	v_mul_f32_e32 v62, v62, v68
	v_mul_f32_e32 v58, v62, v58
	v_mul_f32_e32 v62, 0xbfb8aa3b, v63
	v_exp_f32_e32 v62, v62
	s_nop 0
	v_add_f32_e32 v62, 1.0, v62
	v_rcp_f32_e32 v62, v62
	s_nop 0
	v_mul_f32_e32 v62, v63, v62
	v_mul_f32_e32 v59, v62, v59
	v_mul_f32_e32 v62, 0xbfb8aa3b, v64
	v_exp_f32_e32 v62, v62
	s_nop 0
	v_add_f32_e32 v62, 1.0, v62
	v_rcp_f32_e32 v62, v62
	s_nop 0
	v_mul_f32_e32 v62, v64, v62
	v_mul_f32_e32 v60, v62, v60
	v_mul_f32_e32 v62, 0xbfb8aa3b, v65
	v_exp_f32_e32 v62, v62
	s_nop 0
	v_add_f32_e32 v62, 1.0, v62
	v_rcp_f32_e32 v62, v62
	s_nop 0
	v_mul_f32_e32 v62, v65, v62
	v_mul_f32_e32 v61, v62, v61
	v_mul_f32_e32 v62, 0xbfb8aa3b, v54
	v_exp_f32_e32 v62, v62
	s_nop 0
	v_add_f32_e32 v62, 1.0, v62
	v_rcp_f32_e32 v62, v62
	s_nop 0
	v_mul_f32_e32 v54, v54, v62
	v_mul_f32_e32 v62, v54, v50
	v_mul_f32_e32 v50, 0xbfb8aa3b, v55
	v_exp_f32_e32 v50, v50
	s_nop 0
	v_add_f32_e32 v50, 1.0, v50
	v_rcp_f32_e32 v50, v50
	s_nop 0
	v_mul_f32_e32 v50, v55, v50
	v_mul_f32_e32 v63, v50, v51
	v_mul_f32_e32 v50, 0xbfb8aa3b, v56
	v_exp_f32_e32 v50, v50
	v_lshl_add_u64 v[54:55], v[66:67], 0, v[114:115]
	v_add_f32_e32 v50, 1.0, v50
	v_rcp_f32_e32 v50, v50
	s_nop 0
	v_mul_f32_e32 v50, v56, v50
	v_mul_f32_e32 v56, v50, v52
	v_mul_f32_e32 v50, 0xbfb8aa3b, v57
	v_exp_f32_e32 v50, v50
	s_nop 0
	v_add_f32_e32 v50, 1.0, v50
	v_rcp_f32_e32 v50, v50
	s_nop 0
	v_mul_f32_e32 v50, v57, v50
	v_mul_f32_e32 v53, v50, v53
	v_cvt_pk_bf16_f32 v50, v58, v59
	v_cvt_pk_bf16_f32 v51, v60, v61
	v_cvt_pk_bf16_f32 v52, v62, v63
	v_cvt_pk_bf16_f32 v53, v56, v53
	global_store_dwordx4 v[54:55], v[50:53], off
	s_nop 1
	v_mul_f32_e32 v52, 0xbfb8aa3b, v46
	v_exp_f32_e32 v52, v52
	v_add_u32_e32 v50, 0x90, v139
	v_mad_i64_i32 v[50:51], s[6:7], v50, s74, v[134:135]
	v_add_f32_e32 v52, 1.0, v52
	v_rcp_f32_e32 v52, v52
	s_nop 0
	v_mul_f32_e32 v46, v46, v52
	v_mul_f32_e32 v42, v46, v42
	v_mul_f32_e32 v46, 0xbfb8aa3b, v47
	v_exp_f32_e32 v46, v46
	s_nop 0
	v_add_f32_e32 v46, 1.0, v46
	v_rcp_f32_e32 v46, v46
	s_nop 0
	v_mul_f32_e32 v46, v47, v46
	v_mul_f32_e32 v43, v46, v43
	v_mul_f32_e32 v46, 0xbfb8aa3b, v48
	v_exp_f32_e32 v46, v46
	s_nop 0
	v_add_f32_e32 v46, 1.0, v46
	v_rcp_f32_e32 v46, v46
	s_nop 0
	v_mul_f32_e32 v46, v48, v46
	v_mul_f32_e32 v44, v46, v44
	v_mul_f32_e32 v46, 0xbfb8aa3b, v49
	v_exp_f32_e32 v46, v46
	s_nop 0
	v_add_f32_e32 v46, 1.0, v46
	v_rcp_f32_e32 v46, v46
	s_nop 0
	v_mul_f32_e32 v46, v49, v46
	v_mul_f32_e32 v45, v46, v45
	v_mul_f32_e32 v46, 0xbfb8aa3b, v38
	v_exp_f32_e32 v46, v46
	s_nop 0
	v_add_f32_e32 v46, 1.0, v46
	v_rcp_f32_e32 v46, v46
	s_nop 0
	v_mul_f32_e32 v38, v38, v46
	v_mul_f32_e32 v46, v38, v34
	v_mul_f32_e32 v34, 0xbfb8aa3b, v39
	v_exp_f32_e32 v34, v34
	s_nop 0
	v_add_f32_e32 v34, 1.0, v34
	v_rcp_f32_e32 v34, v34
	s_nop 0
	v_mul_f32_e32 v34, v39, v34
	v_mul_f32_e32 v47, v34, v35
	v_mul_f32_e32 v34, 0xbfb8aa3b, v40
	v_exp_f32_e32 v34, v34
	v_lshl_add_u64 v[38:39], v[50:51], 0, v[114:115]
	v_add_f32_e32 v34, 1.0, v34
	v_rcp_f32_e32 v34, v34
	s_nop 0
	v_mul_f32_e32 v34, v40, v34
	v_mul_f32_e32 v40, v34, v36
	v_mul_f32_e32 v34, 0xbfb8aa3b, v41
	v_exp_f32_e32 v34, v34
	s_nop 0
	v_add_f32_e32 v34, 1.0, v34
	v_rcp_f32_e32 v34, v34
	s_nop 0
	v_mul_f32_e32 v34, v41, v34
	v_mul_f32_e32 v37, v34, v37
	v_cvt_pk_bf16_f32 v34, v42, v43
	v_cvt_pk_bf16_f32 v35, v44, v45
	v_cvt_pk_bf16_f32 v36, v46, v47
	v_cvt_pk_bf16_f32 v37, v40, v37
	global_store_dwordx4 v[38:39], v[34:37], off
	s_nop 1
	v_mul_f32_e32 v36, 0xbfb8aa3b, v30
	v_exp_f32_e32 v36, v36
	v_add_u32_e32 v34, 0xa0, v139
	v_mad_i64_i32 v[34:35], s[6:7], v34, s74, v[134:135]
	v_add_f32_e32 v36, 1.0, v36
	v_rcp_f32_e32 v36, v36
	s_nop 0
	v_mul_f32_e32 v30, v30, v36
	v_mul_f32_e32 v26, v30, v26
	v_mul_f32_e32 v30, 0xbfb8aa3b, v31
	v_exp_f32_e32 v30, v30
	s_nop 0
	v_add_f32_e32 v30, 1.0, v30
	v_rcp_f32_e32 v30, v30
	s_nop 0
	v_mul_f32_e32 v30, v31, v30
	v_mul_f32_e32 v27, v30, v27
	v_mul_f32_e32 v30, 0xbfb8aa3b, v32
	v_exp_f32_e32 v30, v30
	s_nop 0
	v_add_f32_e32 v30, 1.0, v30
	v_rcp_f32_e32 v30, v30
	s_nop 0
	v_mul_f32_e32 v30, v32, v30
	v_mul_f32_e32 v28, v30, v28
	v_mul_f32_e32 v30, 0xbfb8aa3b, v33
	v_exp_f32_e32 v30, v30
	s_nop 0
	v_add_f32_e32 v30, 1.0, v30
	v_rcp_f32_e32 v30, v30
	s_nop 0
	v_mul_f32_e32 v30, v33, v30
	v_mul_f32_e32 v29, v30, v29
	v_mul_f32_e32 v30, 0xbfb8aa3b, v22
	v_exp_f32_e32 v30, v30
	s_nop 0
	v_add_f32_e32 v30, 1.0, v30
	v_rcp_f32_e32 v30, v30
	s_nop 0
	v_mul_f32_e32 v22, v22, v30
	v_mul_f32_e32 v30, v22, v18
	v_mul_f32_e32 v18, 0xbfb8aa3b, v23
	v_exp_f32_e32 v18, v18
	s_nop 0
	v_add_f32_e32 v18, 1.0, v18
	v_rcp_f32_e32 v18, v18
	s_nop 0
	v_mul_f32_e32 v18, v23, v18
	v_mul_f32_e32 v31, v18, v19
	v_mul_f32_e32 v18, 0xbfb8aa3b, v24
	v_exp_f32_e32 v18, v18
	v_lshl_add_u64 v[22:23], v[34:35], 0, v[114:115]
	v_add_f32_e32 v18, 1.0, v18
	v_rcp_f32_e32 v18, v18
	s_nop 0
	v_mul_f32_e32 v18, v24, v18
	v_mul_f32_e32 v24, v18, v20
	v_mul_f32_e32 v18, 0xbfb8aa3b, v25
	v_exp_f32_e32 v18, v18
	s_nop 0
	v_add_f32_e32 v18, 1.0, v18
	v_rcp_f32_e32 v18, v18
	s_nop 0
	v_mul_f32_e32 v18, v25, v18
	v_mul_f32_e32 v21, v18, v21
	v_cvt_pk_bf16_f32 v18, v26, v27
	v_cvt_pk_bf16_f32 v19, v28, v29
	v_cvt_pk_bf16_f32 v20, v30, v31
	v_cvt_pk_bf16_f32 v21, v24, v21
	global_store_dwordx4 v[22:23], v[18:21], off
	s_nop 1
	v_mul_f32_e32 v20, 0xbfb8aa3b, v14
	v_exp_f32_e32 v20, v20
	v_add_u32_e32 v18, 0xb0, v139
	v_mad_i64_i32 v[18:19], s[6:7], v18, s74, v[134:135]
	v_add_f32_e32 v20, 1.0, v20
	v_rcp_f32_e32 v20, v20
	s_mov_b64 s[6:7], s[42:43]
	v_mul_f32_e32 v14, v14, v20
	v_mul_f32_e32 v10, v14, v10
	v_mul_f32_e32 v14, 0xbfb8aa3b, v15
	v_exp_f32_e32 v14, v14
	s_nop 0
	v_add_f32_e32 v14, 1.0, v14
	v_rcp_f32_e32 v14, v14
	s_nop 0
	v_mul_f32_e32 v14, v15, v14
	v_mul_f32_e32 v11, v14, v11
	v_mul_f32_e32 v14, 0xbfb8aa3b, v16
	v_exp_f32_e32 v14, v14
	s_nop 0
	v_add_f32_e32 v14, 1.0, v14
	v_rcp_f32_e32 v14, v14
	s_nop 0
	v_mul_f32_e32 v14, v16, v14
	v_mul_f32_e32 v12, v14, v12
	v_mul_f32_e32 v14, 0xbfb8aa3b, v17
	v_exp_f32_e32 v14, v14
	s_nop 0
	v_add_f32_e32 v14, 1.0, v14
	v_rcp_f32_e32 v14, v14
	s_nop 0
	v_mul_f32_e32 v14, v17, v14
	v_mul_f32_e32 v13, v14, v13
	v_mul_f32_e32 v14, 0xbfb8aa3b, v6
	v_exp_f32_e32 v14, v14
	s_nop 0
	v_add_f32_e32 v14, 1.0, v14
	v_rcp_f32_e32 v14, v14
	s_nop 0
	v_mul_f32_e32 v6, v6, v14
	v_mul_f32_e32 v14, v6, v2
	v_mul_f32_e32 v2, 0xbfb8aa3b, v7
	v_exp_f32_e32 v2, v2
	s_nop 0
	v_add_f32_e32 v2, 1.0, v2
	v_rcp_f32_e32 v2, v2
	s_nop 0
	v_mul_f32_e32 v2, v7, v2
	v_mul_f32_e32 v15, v2, v3
	v_mul_f32_e32 v2, 0xbfb8aa3b, v8
	v_exp_f32_e32 v2, v2
	v_lshl_add_u64 v[6:7], v[18:19], 0, v[114:115]
	v_add_f32_e32 v2, 1.0, v2
	v_rcp_f32_e32 v2, v2
	s_nop 0
	v_mul_f32_e32 v2, v8, v2
	v_mul_f32_e32 v8, v2, v4
	v_mul_f32_e32 v2, 0xbfb8aa3b, v9
	v_exp_f32_e32 v2, v2
	s_nop 0
	v_add_f32_e32 v2, 1.0, v2
	v_rcp_f32_e32 v2, v2
	s_nop 0
	v_mul_f32_e32 v2, v9, v2
	v_mul_f32_e32 v5, v2, v5
	v_cvt_pk_bf16_f32 v2, v10, v11
	v_cvt_pk_bf16_f32 v3, v12, v13
	v_cvt_pk_bf16_f32 v4, v14, v15
	v_cvt_pk_bf16_f32 v5, v8, v5
	global_store_dwordx4 v[6:7], v[2:5], off
	s_cbranch_vccz .LBB0_500
	s_waitcnt vmcnt(0)
	v_readlane_b32 s0, v255, 8
	v_readlane_b32 s62, v255, 10
	v_readlane_b32 s84, v255, 12
	s_cmpk_gt_u32 s22, 0xff
	v_readlane_b32 s1, v255, 9
	s_mov_b64 s[58:59], s[92:93]
	v_readlane_b32 s63, v255, 11
	v_readlane_b32 s85, v255, 13
	s_cbranch_scc1 .LBB0_507
	s_barrier

.Lrot_enter_2:
	s_add_u32 s7, s40, 0xfff80080
	s_addc_u32 s11, s41, -1
	s_add_i32 s49, 0, 0x10000
	v_add_u32_e32 v142, s49, v158
	ds_read_b128 v[130:133], v142
	ds_read_b128 v[134:137], v142 offset:1024
	ds_read_b128 v[138:141], v142 offset:2048
	ds_read_b128 v[142:145], v142 offset:3072
	s_cmp_eq_u32 s6, 4
	s_cselect_b32 s95, s51, s11
	s_cselect_b32 s94, s50, s7
	s_cselect_b32 s97, s53, s9
	s_cselect_b32 s96, s52, s8
	v_lshl_add_u64 v[156:157], s[40:41], 0, v[150:151]
	s_add_i32 m0, s55, 0xc000
	ds_read_b128 v[152:155], v159
	ds_read_b128 v[160:163], v159 offset:1024
	ds_read_b128 v[164:167], v159 offset:2048
	ds_read_b128 v[168:171], v159 offset:3072
	ds_read_b128 v[172:175], v159 offset:4096
	ds_read_b128 v[176:179], v159 offset:5120
	ds_read_b128 v[180:183], v159 offset:6144
	ds_read_b128 v[184:187], v159 offset:7168
	global_load_lds_dwordx4 v[156:157], off
	v_lshl_add_u64 v[156:157], v[156:157], 0, s[60:61]
	s_add_i32 m0, s55, 0xe000
	s_nop 0
	global_load_lds_dwordx4 v[156:157], off
	s_waitcnt lgkmcnt(8)
	s_barrier
	s_waitcnt lgkmcnt(0)
	v_mfma_f32_16x16x32_bf16 v[126:129], v[130:133], v[152:155], v[126:129]
	v_mfma_f32_16x16x32_bf16 v[122:125], v[138:141], v[152:155], v[122:125]
	v_mfma_f32_16x16x32_bf16 v[114:117], v[130:133], v[164:167], v[114:117]
	v_mfma_f32_16x16x32_bf16 v[110:113], v[138:141], v[164:167], v[110:113]
	v_mfma_f32_16x16x32_bf16 v[102:105], v[130:133], v[172:175], v[102:105]
	v_mfma_f32_16x16x32_bf16 v[94:97], v[138:141], v[172:175], v[94:97]
	v_mfma_f32_16x16x32_bf16 v[86:89], v[130:133], v[180:183], v[86:89]
	v_mfma_f32_16x16x32_bf16 v[78:81], v[138:141], v[180:183], v[78:81]
	v_mfma_f32_16x16x32_bf16 v[126:129], v[134:137], v[160:163], v[126:129]
	v_mfma_f32_16x16x32_bf16 v[122:125], v[142:145], v[160:163], v[122:125]
	v_mfma_f32_16x16x32_bf16 v[114:117], v[134:137], v[168:171], v[114:117]
	v_mfma_f32_16x16x32_bf16 v[110:113], v[142:145], v[168:171], v[110:113]
	v_mfma_f32_16x16x32_bf16 v[102:105], v[134:137], v[176:179], v[102:105]
	v_mfma_f32_16x16x32_bf16 v[94:97], v[142:145], v[176:179], v[94:97]
	v_mfma_f32_16x16x32_bf16 v[86:89], v[134:137], v[184:187], v[86:89]
	v_mfma_f32_16x16x32_bf16 v[78:81], v[142:145], v[184:187], v[78:81]
	s_barrier
	s_add_i32 s7, 0, 0x14000
	v_add_u32_e32 v156, s7, v158
	s_add_i32 s11, s49, s63
	ds_read_b128 v[188:191], v156
	ds_read_b128 v[192:195], v156 offset:1024
	ds_read_b128 v[196:199], v156 offset:2048
	ds_read_b128 v[200:203], v156 offset:3072
	v_lshl_add_u64 v[156:157], s[96:97], 0, v[0:1]
	s_mov_b32 m0, s11
	v_lshl_add_u64 v[204:205], v[156:157], 0, s[68:69]
	global_load_lds_dwordx4 v[156:157], off
	s_add_i32 m0, s11, 0x2000
	s_nop 0
	global_load_lds_dwordx4 v[204:205], off
	s_waitcnt lgkmcnt(0)
	s_barrier
	v_mfma_f32_16x16x32_bf16 v[118:121], v[188:191], v[152:155], v[118:121]
	v_mfma_f32_16x16x32_bf16 v[106:109], v[196:199], v[152:155], v[106:109]
	v_mfma_f32_16x16x32_bf16 v[98:101], v[188:191], v[164:167], v[98:101]
	v_mfma_f32_16x16x32_bf16 v[90:93], v[196:199], v[164:167], v[90:93]
	v_mfma_f32_16x16x32_bf16 v[82:85], v[188:191], v[172:175], v[82:85]
	v_mfma_f32_16x16x32_bf16 v[74:77], v[196:199], v[172:175], v[74:77]
	v_mfma_f32_16x16x32_bf16 v[70:73], v[188:191], v[180:183], v[70:73]
	v_mfma_f32_16x16x32_bf16 v[66:69], v[196:199], v[180:183], v[66:69]
	v_mfma_f32_16x16x32_bf16 v[118:121], v[192:195], v[160:163], v[118:121]
	v_mfma_f32_16x16x32_bf16 v[106:109], v[200:203], v[160:163], v[106:109]
	v_mfma_f32_16x16x32_bf16 v[98:101], v[192:195], v[168:171], v[98:101]
	v_mfma_f32_16x16x32_bf16 v[90:93], v[200:203], v[168:171], v[90:93]
	v_mfma_f32_16x16x32_bf16 v[82:85], v[192:195], v[176:179], v[82:85]
	v_mfma_f32_16x16x32_bf16 v[74:77], v[200:203], v[176:179], v[74:77]
	v_mfma_f32_16x16x32_bf16 v[70:73], v[192:195], v[184:187], v[70:73]
	v_mfma_f32_16x16x32_bf16 v[66:69], v[200:203], v[184:187], v[66:69]
	s_barrier
	s_mov_b32 m0, s55
	v_lshl_add_u64 v[204:205], s[94:95], 0, v[148:149]
	ds_read_b128 v[152:155], v159 offset:16384
	ds_read_b128 v[160:163], v159 offset:17408
	ds_read_b128 v[164:167], v159 offset:18432
	ds_read_b128 v[168:171], v159 offset:19456
	ds_read_b128 v[172:175], v159 offset:20480
	ds_read_b128 v[176:179], v159 offset:21504
	ds_read_b128 v[180:183], v159 offset:22528
	ds_read_b128 v[184:187], v159 offset:23552
	global_load_lds_dwordx4 v[204:205], off
	v_lshl_add_u64 v[206:207], v[204:205], 0, s[60:61]
	s_mov_b32 m0, s84
	s_nop 0
	global_load_lds_dwordx4 v[206:207], off
	s_waitcnt lgkmcnt(0)
	s_barrier
	v_mfma_f32_16x16x32_bf16 v[62:65], v[130:133], v[152:155], v[62:65]
	v_mfma_f32_16x16x32_bf16 v[58:61], v[138:141], v[152:155], v[58:61]
	v_mfma_f32_16x16x32_bf16 v[54:57], v[130:133], v[164:167], v[54:57]
	v_mfma_f32_16x16x32_bf16 v[46:49], v[138:141], v[164:167], v[46:49]
	v_mfma_f32_16x16x32_bf16 v[38:41], v[130:133], v[172:175], v[38:41]
	v_mfma_f32_16x16x32_bf16 v[30:33], v[138:141], v[172:175], v[30:33]
	v_mfma_f32_16x16x32_bf16 v[22:25], v[130:133], v[180:183], v[22:25]
	v_mfma_f32_16x16x32_bf16 v[14:17], v[138:141], v[180:183], v[14:17]
	v_mfma_f32_16x16x32_bf16 v[62:65], v[134:137], v[160:163], v[62:65]
	v_mfma_f32_16x16x32_bf16 v[58:61], v[142:145], v[160:163], v[58:61]
	v_mfma_f32_16x16x32_bf16 v[54:57], v[134:137], v[168:171], v[54:57]
	v_mfma_f32_16x16x32_bf16 v[46:49], v[142:145], v[168:171], v[46:49]
	v_mfma_f32_16x16x32_bf16 v[38:41], v[134:137], v[176:179], v[38:41]
	v_mfma_f32_16x16x32_bf16 v[30:33], v[142:145], v[176:179], v[30:33]
	v_mfma_f32_16x16x32_bf16 v[22:25], v[134:137], v[184:187], v[22:25]
	v_mfma_f32_16x16x32_bf16 v[14:17], v[142:145], v[184:187], v[14:17]
	s_barrier
	s_add_i32 s7, s7, s63
	v_lshl_add_u64 v[130:131], v[156:157], 0, vcc
	s_mov_b32 m0, s7
	s_nop 0
	global_load_lds_dwordx4 v[130:131], off
	v_lshl_add_u64 v[130:131], v[156:157], 0, s[78:79]
	s_add_i32 m0, s7, 0x2000
	s_nop 0
	global_load_lds_dwordx4 v[130:131], off
	v_lshl_add_u64 v[230:231], v[204:205], 0, s[20:21]
	s_mov_b32 m0, s85
	s_nop 0
	global_load_lds_dwordx4 v[230:231], off
	v_lshl_add_u64 v[230:231], v[204:205], 0, s[64:65]
	s_mov_b32 m0, s86
	s_nop 0
	global_load_lds_dwordx4 v[230:231], off
	s_waitcnt vmcnt(8)
	s_barrier
	v_mfma_f32_16x16x32_bf16 v[50:53], v[188:191], v[152:155], v[50:53]
	v_mfma_f32_16x16x32_bf16 v[42:45], v[196:199], v[152:155], v[42:45]
	v_mfma_f32_16x16x32_bf16 v[34:37], v[188:191], v[164:167], v[34:37]
	v_mfma_f32_16x16x32_bf16 v[26:29], v[196:199], v[164:167], v[26:29]
	v_mfma_f32_16x16x32_bf16 v[18:21], v[188:191], v[172:175], v[18:21]
	v_mfma_f32_16x16x32_bf16 v[10:13], v[196:199], v[172:175], v[10:13]
	v_mfma_f32_16x16x32_bf16 v[6:9], v[188:191], v[180:183], v[6:9]
	v_mfma_f32_16x16x32_bf16 v[2:5], v[196:199], v[180:183], v[2:5]
	v_mfma_f32_16x16x32_bf16 v[50:53], v[192:195], v[160:163], v[50:53]
	v_mfma_f32_16x16x32_bf16 v[42:45], v[200:203], v[160:163], v[42:45]
	v_mfma_f32_16x16x32_bf16 v[34:37], v[192:195], v[168:171], v[34:37]
	v_mfma_f32_16x16x32_bf16 v[26:29], v[200:203], v[168:171], v[26:29]
	v_mfma_f32_16x16x32_bf16 v[18:21], v[192:195], v[176:179], v[18:21]
	v_mfma_f32_16x16x32_bf16 v[10:13], v[200:203], v[176:179], v[10:13]
	v_mfma_f32_16x16x32_bf16 v[6:9], v[192:195], v[184:187], v[6:9]
	v_mfma_f32_16x16x32_bf16 v[2:5], v[200:203], v[184:187], v[2:5]
	s_barrier
	s_add_i32 s7, 0, 0x18000
	v_add_u32_e32 v142, s7, v158
	ds_read_b128 v[130:133], v142
	ds_read_b128 v[134:137], v142 offset:1024
	ds_read_b128 v[138:141], v142 offset:2048
	ds_read_b128 v[142:145], v142 offset:3072
	ds_read_b128 v[152:155], v159 offset:32768
	ds_read_b128 v[160:163], v159 offset:33792
	ds_read_b128 v[164:167], v159 offset:34816
	ds_read_b128 v[168:171], v159 offset:35840
	ds_read_b128 v[172:175], v159 offset:36864
	ds_read_b128 v[176:179], v159 offset:37888
	ds_read_b128 v[180:183], v159 offset:38912
	ds_read_b128 v[184:187], v159 offset:39936
	s_waitcnt lgkmcnt(8)
	s_barrier
	s_waitcnt lgkmcnt(0)
	v_mfma_f32_16x16x32_bf16 v[126:129], v[130:133], v[152:155], v[126:129]
	v_mfma_f32_16x16x32_bf16 v[122:125], v[138:141], v[152:155], v[122:125]
	v_mfma_f32_16x16x32_bf16 v[114:117], v[130:133], v[164:167], v[114:117]
	v_mfma_f32_16x16x32_bf16 v[110:113], v[138:141], v[164:167], v[110:113]
	v_mfma_f32_16x16x32_bf16 v[102:105], v[130:133], v[172:175], v[102:105]
	v_mfma_f32_16x16x32_bf16 v[94:97], v[138:141], v[172:175], v[94:97]
	v_mfma_f32_16x16x32_bf16 v[86:89], v[130:133], v[180:183], v[86:89]
	v_mfma_f32_16x16x32_bf16 v[78:81], v[138:141], v[180:183], v[78:81]
	v_mfma_f32_16x16x32_bf16 v[126:129], v[134:137], v[160:163], v[126:129]
	v_mfma_f32_16x16x32_bf16 v[122:125], v[142:145], v[160:163], v[122:125]
	v_mfma_f32_16x16x32_bf16 v[114:117], v[134:137], v[168:171], v[114:117]
	v_mfma_f32_16x16x32_bf16 v[110:113], v[142:145], v[168:171], v[110:113]
	v_mfma_f32_16x16x32_bf16 v[102:105], v[134:137], v[176:179], v[102:105]
	v_mfma_f32_16x16x32_bf16 v[94:97], v[142:145], v[176:179], v[94:97]
	v_mfma_f32_16x16x32_bf16 v[86:89], v[134:137], v[184:187], v[86:89]
	v_mfma_f32_16x16x32_bf16 v[78:81], v[142:145], v[184:187], v[78:81]
	s_barrier
	s_add_i32 s11, 0, 0x1c000
	s_add_i32 s7, s7, s63
	v_add_u32_e32 v200, s11, v158
	v_lshl_add_u64 v[206:207], v[156:157], 0, s[34:35]
	s_mov_b32 m0, s7
	ds_read_b128 v[188:191], v200
	ds_read_b128 v[192:195], v200 offset:1024
	ds_read_b128 v[196:199], v200 offset:2048
	ds_read_b128 v[200:203], v200 offset:3072
	global_load_lds_dwordx4 v[206:207], off
	v_lshl_add_u64 v[206:207], v[156:157], 0, s[38:39]
	s_add_i32 m0, s7, 0x2000
	s_nop 0
	global_load_lds_dwordx4 v[206:207], off
	s_waitcnt lgkmcnt(0)
	s_barrier
	v_mfma_f32_16x16x32_bf16 v[118:121], v[188:191], v[152:155], v[118:121]
	v_mfma_f32_16x16x32_bf16 v[106:109], v[196:199], v[152:155], v[106:109]
	v_mfma_f32_16x16x32_bf16 v[98:101], v[188:191], v[164:167], v[98:101]
	v_mfma_f32_16x16x32_bf16 v[90:93], v[196:199], v[164:167], v[90:93]
	v_mfma_f32_16x16x32_bf16 v[82:85], v[188:191], v[172:175], v[82:85]
	v_mfma_f32_16x16x32_bf16 v[74:77], v[196:199], v[172:175], v[74:77]
	v_mfma_f32_16x16x32_bf16 v[70:73], v[188:191], v[180:183], v[70:73]
	v_mfma_f32_16x16x32_bf16 v[66:69], v[196:199], v[180:183], v[66:69]
	v_mfma_f32_16x16x32_bf16 v[118:121], v[192:195], v[160:163], v[118:121]
	v_mfma_f32_16x16x32_bf16 v[106:109], v[200:203], v[160:163], v[106:109]
	v_mfma_f32_16x16x32_bf16 v[98:101], v[192:195], v[168:171], v[98:101]
	v_mfma_f32_16x16x32_bf16 v[90:93], v[200:203], v[168:171], v[90:93]
	v_mfma_f32_16x16x32_bf16 v[82:85], v[192:195], v[176:179], v[82:85]
	v_mfma_f32_16x16x32_bf16 v[74:77], v[200:203], v[176:179], v[74:77]
	v_mfma_f32_16x16x32_bf16 v[70:73], v[192:195], v[184:187], v[70:73]
	v_mfma_f32_16x16x32_bf16 v[66:69], v[200:203], v[184:187], v[66:69]
	s_barrier
	s_mov_b32 m0, s89
	v_lshl_add_u64 v[206:207], v[204:205], 0, s[34:35]
	ds_read_b128 v[152:155], v159 offset:49152
	ds_read_b128 v[160:163], v159 offset:50176
	ds_read_b128 v[164:167], v159 offset:51200
	ds_read_b128 v[168:171], v159 offset:52224
	ds_read_b128 v[172:175], v159 offset:53248
	ds_read_b128 v[176:179], v159 offset:54272
	ds_read_b128 v[180:183], v159 offset:55296
	ds_read_b128 v[184:187], v159 offset:56320
	global_load_lds_dwordx4 v[206:207], off
	v_lshl_add_u64 v[204:205], v[204:205], 0, s[66:67]
	s_mov_b32 m0, s90
	s_nop 0
	global_load_lds_dwordx4 v[204:205], off
	s_waitcnt lgkmcnt(0)
	s_barrier
	v_mfma_f32_16x16x32_bf16 v[62:65], v[130:133], v[152:155], v[62:65]
	v_mfma_f32_16x16x32_bf16 v[58:61], v[138:141], v[152:155], v[58:61]
	v_mfma_f32_16x16x32_bf16 v[54:57], v[130:133], v[164:167], v[54:57]
	v_mfma_f32_16x16x32_bf16 v[46:49], v[138:141], v[164:167], v[46:49]
	v_mfma_f32_16x16x32_bf16 v[38:41], v[130:133], v[172:175], v[38:41]
	v_mfma_f32_16x16x32_bf16 v[30:33], v[138:141], v[172:175], v[30:33]
	v_mfma_f32_16x16x32_bf16 v[22:25], v[130:133], v[180:183], v[22:25]
	v_mfma_f32_16x16x32_bf16 v[14:17], v[138:141], v[180:183], v[14:17]
	v_mfma_f32_16x16x32_bf16 v[62:65], v[134:137], v[160:163], v[62:65]
	v_mfma_f32_16x16x32_bf16 v[58:61], v[142:145], v[160:163], v[58:61]
	v_mfma_f32_16x16x32_bf16 v[54:57], v[134:137], v[168:171], v[54:57]
	v_mfma_f32_16x16x32_bf16 v[46:49], v[142:145], v[168:171], v[46:49]
	v_mfma_f32_16x16x32_bf16 v[38:41], v[134:137], v[176:179], v[38:41]
	v_mfma_f32_16x16x32_bf16 v[30:33], v[142:145], v[176:179], v[30:33]
	v_mfma_f32_16x16x32_bf16 v[22:25], v[134:137], v[184:187], v[22:25]
	v_mfma_f32_16x16x32_bf16 v[14:17], v[142:145], v[184:187], v[14:17]
	s_barrier
	s_add_i32 s7, s11, s63
	v_lshl_add_u64 v[130:131], v[156:157], 0, s[72:73]
	s_mov_b32 m0, s7
	s_nop 0
	global_load_lds_dwordx4 v[130:131], off
	v_lshl_add_u64 v[130:131], v[156:157], 0, s[56:57]
	s_add_i32 m0, s7, 0x2000
	s_nop 0
	global_load_lds_dwordx4 v[130:131], off
	s_waitcnt vmcnt(6)
	s_add_i32 s6, s6, 2
	s_add_u32 s8, s8, 0x100
	s_addc_u32 s9, s9, 0
	s_add_u32 s40, s40, 0x100
	s_addc_u32 s41, s41, 0
	s_cmp_gt_u32 s6, 5
	s_cbranch_scc0 .LBB0_578
	s_barrier
	v_mfma_f32_16x16x32_bf16 v[50:53], v[188:191], v[152:155], v[50:53]
	v_mfma_f32_16x16x32_bf16 v[42:45], v[196:199], v[152:155], v[42:45]
	v_mfma_f32_16x16x32_bf16 v[34:37], v[188:191], v[164:167], v[34:37]
	v_mfma_f32_16x16x32_bf16 v[26:29], v[196:199], v[164:167], v[26:29]
	v_mfma_f32_16x16x32_bf16 v[18:21], v[188:191], v[172:175], v[18:21]
	v_mfma_f32_16x16x32_bf16 v[10:13], v[196:199], v[172:175], v[10:13]
	v_mfma_f32_16x16x32_bf16 v[6:9], v[188:191], v[180:183], v[6:9]
	v_mfma_f32_16x16x32_bf16 v[2:5], v[196:199], v[180:183], v[2:5]
	v_mfma_f32_16x16x32_bf16 v[50:53], v[192:195], v[160:163], v[50:53]
	v_mfma_f32_16x16x32_bf16 v[42:45], v[200:203], v[160:163], v[42:45]
	v_mfma_f32_16x16x32_bf16 v[34:37], v[192:195], v[168:171], v[34:37]
	v_mfma_f32_16x16x32_bf16 v[26:29], v[200:203], v[168:171], v[26:29]
	v_mfma_f32_16x16x32_bf16 v[18:21], v[192:195], v[176:179], v[18:21]
	v_mfma_f32_16x16x32_bf16 v[10:13], v[200:203], v[176:179], v[10:13]
	v_mfma_f32_16x16x32_bf16 v[6:9], v[192:195], v[184:187], v[6:9]
	v_mfma_f32_16x16x32_bf16 v[2:5], v[200:203], v[184:187], v[2:5]
	s_barrier
	v_mov_b32_e32 v156, v146
	s_lshl_b32 s6, s92, 8
	v_ashrrev_i32_e32 v130, 2, v156
	s_or_b32 s6, s6, s88
	v_and_b32_e32 v130, -4, v130
	v_add_u32_e32 v152, s6, v130
	v_ashrrev_i32_e32 v153, 31, v152
	v_cndmask_b32_e64 v131, 0, 1, s[44:45]
	v_lshl_add_u64 v[154:155], v[152:153], 2, s[42:43]
	v_mov_b32_e32 v130, 1.0
	v_cmp_ne_u32_e64 s[40:41], 1, v131
	s_andn2_b64 vcc, exec, s[44:45]
	v_mov_b32_e32 v134, 1.0
	v_mov_b32_e32 v135, 1.0
	v_mov_b32_e32 v136, 1.0
	v_mov_b32_e32 v137, 1.0
	s_cbranch_vccnz .LBB0_581
	global_load_dwordx4 v[134:137], v[154:155], off

.Lrot_enter_1:
	s_add_u32 s7, s48, 0xffea0080
	s_addc_u32 s78, s49, -1
	s_add_i32 s79, 0, 0x10000
	v_add_u32_e32 v132, s79, v135
	ds_read_b128 v[138:141], v132
	ds_read_b128 v[142:145], v132 offset:1024
	ds_read_b128 v[148:151], v132 offset:2048
	ds_read_b128 v[152:155], v132 offset:3072
	s_cmpk_eq_i32 s6, 0x54
	s_cselect_b32 s91, s45, s78
	s_cselect_b32 s90, s44, s7
	s_cselect_b32 s93, s47, s9
	s_cselect_b32 s92, s46, s8
	v_lshl_add_u64 v[132:133], s[48:49], 0, v[130:131]
	s_add_i32 m0, s56, 0xc000
	ds_read_b128 v[156:159], v136
	ds_read_b128 v[160:163], v136 offset:1024
	ds_read_b128 v[164:167], v136 offset:2048
	ds_read_b128 v[168:171], v136 offset:3072
	ds_read_b128 v[172:175], v136 offset:4096
	ds_read_b128 v[176:179], v136 offset:5120
	ds_read_b128 v[180:183], v136 offset:6144
	ds_read_b128 v[184:187], v136 offset:7168
	global_load_lds_dwordx4 v[132:133], off
	v_lshl_add_u64 v[132:133], v[132:133], 0, s[26:27]
	s_add_i32 m0, s56, 0xe000
	s_nop 0
	global_load_lds_dwordx4 v[132:133], off
	s_waitcnt lgkmcnt(8)
	s_barrier
	s_waitcnt lgkmcnt(0)
	v_mfma_f32_16x16x32_bf16 v[126:129], v[138:141], v[156:159], v[126:129]
	v_mfma_f32_16x16x32_bf16 v[122:125], v[148:151], v[156:159], v[122:125]
	v_mfma_f32_16x16x32_bf16 v[118:121], v[138:141], v[164:167], v[118:121]
	v_mfma_f32_16x16x32_bf16 v[110:113], v[148:151], v[164:167], v[110:113]
	v_mfma_f32_16x16x32_bf16 v[102:105], v[138:141], v[172:175], v[102:105]
	v_mfma_f32_16x16x32_bf16 v[94:97], v[148:151], v[172:175], v[94:97]
	v_mfma_f32_16x16x32_bf16 v[86:89], v[138:141], v[180:183], v[86:89]
	v_mfma_f32_16x16x32_bf16 v[78:81], v[148:151], v[180:183], v[78:81]
	v_mfma_f32_16x16x32_bf16 v[126:129], v[142:145], v[160:163], v[126:129]
	v_mfma_f32_16x16x32_bf16 v[122:125], v[152:155], v[160:163], v[122:125]
	v_mfma_f32_16x16x32_bf16 v[118:121], v[142:145], v[168:171], v[118:121]
	v_mfma_f32_16x16x32_bf16 v[110:113], v[152:155], v[168:171], v[110:113]
	v_mfma_f32_16x16x32_bf16 v[102:105], v[142:145], v[176:179], v[102:105]
	v_mfma_f32_16x16x32_bf16 v[94:97], v[152:155], v[176:179], v[94:97]
	v_mfma_f32_16x16x32_bf16 v[86:89], v[142:145], v[184:187], v[86:89]
	v_mfma_f32_16x16x32_bf16 v[78:81], v[152:155], v[184:187], v[78:81]
	s_barrier
	s_add_i32 s7, 0, 0x14000
	v_add_u32_e32 v132, s7, v135
	s_add_i32 s78, s79, s55
	ds_read_b128 v[188:191], v132
	ds_read_b128 v[192:195], v132 offset:1024
	ds_read_b128 v[196:199], v132 offset:2048
	ds_read_b128 v[200:203], v132 offset:3072
	v_lshl_add_u64 v[132:133], s[92:93], 0, v[0:1]
	s_mov_b32 m0, s78
	v_lshl_add_u64 v[204:205], v[132:133], 0, s[26:27]
	global_load_lds_dwordx4 v[132:133], off
	s_add_i32 m0, s78, 0x2000
	s_nop 0
	global_load_lds_dwordx4 v[204:205], off
	s_waitcnt lgkmcnt(0)
	s_barrier
	v_mfma_f32_16x16x32_bf16 v[114:117], v[188:191], v[156:159], v[114:117]
	v_mfma_f32_16x16x32_bf16 v[106:109], v[196:199], v[156:159], v[106:109]
	v_mfma_f32_16x16x32_bf16 v[98:101], v[188:191], v[164:167], v[98:101]
	v_mfma_f32_16x16x32_bf16 v[90:93], v[196:199], v[164:167], v[90:93]
	v_mfma_f32_16x16x32_bf16 v[82:85], v[188:191], v[172:175], v[82:85]
	v_mfma_f32_16x16x32_bf16 v[74:77], v[196:199], v[172:175], v[74:77]
	v_mfma_f32_16x16x32_bf16 v[70:73], v[188:191], v[180:183], v[70:73]
	v_mfma_f32_16x16x32_bf16 v[66:69], v[196:199], v[180:183], v[66:69]
	v_mfma_f32_16x16x32_bf16 v[114:117], v[192:195], v[160:163], v[114:117]
	v_mfma_f32_16x16x32_bf16 v[106:109], v[200:203], v[160:163], v[106:109]
	v_mfma_f32_16x16x32_bf16 v[98:101], v[192:195], v[168:171], v[98:101]
	v_mfma_f32_16x16x32_bf16 v[90:93], v[200:203], v[168:171], v[90:93]
	v_mfma_f32_16x16x32_bf16 v[82:85], v[192:195], v[176:179], v[82:85]
	v_mfma_f32_16x16x32_bf16 v[74:77], v[200:203], v[176:179], v[74:77]
	v_mfma_f32_16x16x32_bf16 v[70:73], v[192:195], v[184:187], v[70:73]
	v_mfma_f32_16x16x32_bf16 v[66:69], v[200:203], v[184:187], v[66:69]
	s_barrier
	s_mov_b32 m0, s56
	v_lshl_add_u64 v[204:205], s[90:91], 0, v[0:1]
	ds_read_b128 v[156:159], v136 offset:16384
	ds_read_b128 v[160:163], v136 offset:17408
	ds_read_b128 v[164:167], v136 offset:18432
	ds_read_b128 v[168:171], v136 offset:19456
	ds_read_b128 v[172:175], v136 offset:20480
	ds_read_b128 v[176:179], v136 offset:21504
	ds_read_b128 v[180:183], v136 offset:22528
	ds_read_b128 v[184:187], v136 offset:23552
	global_load_lds_dwordx4 v[204:205], off
	v_lshl_add_u64 v[206:207], v[204:205], 0, s[26:27]
	s_mov_b32 m0, s57
	s_nop 0
	global_load_lds_dwordx4 v[206:207], off
	s_waitcnt lgkmcnt(0)
	s_barrier
	v_mfma_f32_16x16x32_bf16 v[62:65], v[138:141], v[156:159], v[62:65]
	v_mfma_f32_16x16x32_bf16 v[58:61], v[148:151], v[156:159], v[58:61]
	v_mfma_f32_16x16x32_bf16 v[54:57], v[138:141], v[164:167], v[54:57]
	v_mfma_f32_16x16x32_bf16 v[46:49], v[148:151], v[164:167], v[46:49]
	v_mfma_f32_16x16x32_bf16 v[38:41], v[138:141], v[172:175], v[38:41]
	v_mfma_f32_16x16x32_bf16 v[30:33], v[148:151], v[172:175], v[30:33]
	v_mfma_f32_16x16x32_bf16 v[22:25], v[138:141], v[180:183], v[22:25]
	v_mfma_f32_16x16x32_bf16 v[14:17], v[148:151], v[180:183], v[14:17]
	v_mfma_f32_16x16x32_bf16 v[62:65], v[142:145], v[160:163], v[62:65]
	v_mfma_f32_16x16x32_bf16 v[58:61], v[152:155], v[160:163], v[58:61]
	v_mfma_f32_16x16x32_bf16 v[54:57], v[142:145], v[168:171], v[54:57]
	v_mfma_f32_16x16x32_bf16 v[46:49], v[152:155], v[168:171], v[46:49]
	v_mfma_f32_16x16x32_bf16 v[38:41], v[142:145], v[176:179], v[38:41]
	v_mfma_f32_16x16x32_bf16 v[30:33], v[152:155], v[176:179], v[30:33]
	v_mfma_f32_16x16x32_bf16 v[22:25], v[142:145], v[184:187], v[22:25]
	v_mfma_f32_16x16x32_bf16 v[14:17], v[152:155], v[184:187], v[14:17]
	s_barrier
	s_add_i32 s7, s7, s55
	v_lshl_add_u64 v[138:139], v[132:133], 0, s[28:29]
	s_mov_b32 m0, s7
	s_nop 0
	global_load_lds_dwordx4 v[138:139], off
	v_lshl_add_u64 v[138:139], v[132:133], 0, s[30:31]
	s_add_i32 m0, s7, 0x2000
	s_nop 0
	global_load_lds_dwordx4 v[138:139], off
	v_lshl_add_u64 v[230:231], v[204:205], 0, s[28:29]
	s_mov_b32 m0, s58
	s_nop 0
	global_load_lds_dwordx4 v[230:231], off
	v_lshl_add_u64 v[230:231], v[204:205], 0, s[30:31]
	s_mov_b32 m0, s59
	s_nop 0
	global_load_lds_dwordx4 v[230:231], off
	s_waitcnt vmcnt(8)
	s_barrier
	v_mfma_f32_16x16x32_bf16 v[50:53], v[188:191], v[156:159], v[50:53]
	v_mfma_f32_16x16x32_bf16 v[42:45], v[196:199], v[156:159], v[42:45]
	v_mfma_f32_16x16x32_bf16 v[34:37], v[188:191], v[164:167], v[34:37]
	v_mfma_f32_16x16x32_bf16 v[26:29], v[196:199], v[164:167], v[26:29]
	v_mfma_f32_16x16x32_bf16 v[18:21], v[188:191], v[172:175], v[18:21]
	v_mfma_f32_16x16x32_bf16 v[10:13], v[196:199], v[172:175], v[10:13]
	v_mfma_f32_16x16x32_bf16 v[6:9], v[188:191], v[180:183], v[6:9]
	v_mfma_f32_16x16x32_bf16 v[2:5], v[196:199], v[180:183], v[2:5]
	v_mfma_f32_16x16x32_bf16 v[50:53], v[192:195], v[160:163], v[50:53]
	v_mfma_f32_16x16x32_bf16 v[42:45], v[200:203], v[160:163], v[42:45]
	v_mfma_f32_16x16x32_bf16 v[34:37], v[192:195], v[168:171], v[34:37]
	v_mfma_f32_16x16x32_bf16 v[26:29], v[200:203], v[168:171], v[26:29]
	v_mfma_f32_16x16x32_bf16 v[18:21], v[192:195], v[176:179], v[18:21]
	v_mfma_f32_16x16x32_bf16 v[10:13], v[200:203], v[176:179], v[10:13]
	v_mfma_f32_16x16x32_bf16 v[6:9], v[192:195], v[184:187], v[6:9]
	v_mfma_f32_16x16x32_bf16 v[2:5], v[200:203], v[184:187], v[2:5]
	s_barrier
	s_add_i32 s7, 0, 0x18000
	v_add_u32_e32 v137, s7, v135
	ds_read_b128 v[138:141], v137
	ds_read_b128 v[142:145], v137 offset:1024
	ds_read_b128 v[148:151], v137 offset:2048
	ds_read_b128 v[152:155], v137 offset:3072
	ds_read_b128 v[156:159], v136 offset:32768
	ds_read_b128 v[160:163], v136 offset:33792
	ds_read_b128 v[164:167], v136 offset:34816
	ds_read_b128 v[168:171], v136 offset:35840
	ds_read_b128 v[172:175], v136 offset:36864
	ds_read_b128 v[176:179], v136 offset:37888
	ds_read_b128 v[180:183], v136 offset:38912
	ds_read_b128 v[184:187], v136 offset:39936
	s_waitcnt lgkmcnt(8)
	s_barrier
	s_waitcnt lgkmcnt(0)
	v_mfma_f32_16x16x32_bf16 v[126:129], v[138:141], v[156:159], v[126:129]
	v_mfma_f32_16x16x32_bf16 v[122:125], v[148:151], v[156:159], v[122:125]
	v_mfma_f32_16x16x32_bf16 v[118:121], v[138:141], v[164:167], v[118:121]
	v_mfma_f32_16x16x32_bf16 v[110:113], v[148:151], v[164:167], v[110:113]
	v_mfma_f32_16x16x32_bf16 v[102:105], v[138:141], v[172:175], v[102:105]
	v_mfma_f32_16x16x32_bf16 v[94:97], v[148:151], v[172:175], v[94:97]
	v_mfma_f32_16x16x32_bf16 v[86:89], v[138:141], v[180:183], v[86:89]
	v_mfma_f32_16x16x32_bf16 v[78:81], v[148:151], v[180:183], v[78:81]
	v_mfma_f32_16x16x32_bf16 v[126:129], v[142:145], v[160:163], v[126:129]
	v_mfma_f32_16x16x32_bf16 v[122:125], v[152:155], v[160:163], v[122:125]
	v_mfma_f32_16x16x32_bf16 v[118:121], v[142:145], v[168:171], v[118:121]
	v_mfma_f32_16x16x32_bf16 v[110:113], v[152:155], v[168:171], v[110:113]
	v_mfma_f32_16x16x32_bf16 v[102:105], v[142:145], v[176:179], v[102:105]
	v_mfma_f32_16x16x32_bf16 v[94:97], v[152:155], v[176:179], v[94:97]
	v_mfma_f32_16x16x32_bf16 v[86:89], v[142:145], v[184:187], v[86:89]
	v_mfma_f32_16x16x32_bf16 v[78:81], v[152:155], v[184:187], v[78:81]
	s_barrier
	s_add_i32 s78, 0, 0x1c000
	s_add_i32 s7, s7, s55
	v_add_u32_e32 v137, s78, v135
	v_lshl_add_u64 v[206:207], v[132:133], 0, s[34:35]
	s_mov_b32 m0, s7
	ds_read_b128 v[188:191], v137
	ds_read_b128 v[192:195], v137 offset:1024
	ds_read_b128 v[196:199], v137 offset:2048
	ds_read_b128 v[200:203], v137 offset:3072
	global_load_lds_dwordx4 v[206:207], off
	v_lshl_add_u64 v[206:207], v[132:133], 0, s[36:37]
	s_add_i32 m0, s7, 0x2000
	s_nop 0
	global_load_lds_dwordx4 v[206:207], off
	s_waitcnt lgkmcnt(0)
	s_barrier
	v_mfma_f32_16x16x32_bf16 v[114:117], v[188:191], v[156:159], v[114:117]
	v_mfma_f32_16x16x32_bf16 v[106:109], v[196:199], v[156:159], v[106:109]
	v_mfma_f32_16x16x32_bf16 v[98:101], v[188:191], v[164:167], v[98:101]
	v_mfma_f32_16x16x32_bf16 v[90:93], v[196:199], v[164:167], v[90:93]
	v_mfma_f32_16x16x32_bf16 v[82:85], v[188:191], v[172:175], v[82:85]
	v_mfma_f32_16x16x32_bf16 v[74:77], v[196:199], v[172:175], v[74:77]
	v_mfma_f32_16x16x32_bf16 v[70:73], v[188:191], v[180:183], v[70:73]
	v_mfma_f32_16x16x32_bf16 v[66:69], v[196:199], v[180:183], v[66:69]
	v_mfma_f32_16x16x32_bf16 v[114:117], v[192:195], v[160:163], v[114:117]
	v_mfma_f32_16x16x32_bf16 v[106:109], v[200:203], v[160:163], v[106:109]
	v_mfma_f32_16x16x32_bf16 v[98:101], v[192:195], v[168:171], v[98:101]
	v_mfma_f32_16x16x32_bf16 v[90:93], v[200:203], v[168:171], v[90:93]
	v_mfma_f32_16x16x32_bf16 v[82:85], v[192:195], v[176:179], v[82:85]
	v_mfma_f32_16x16x32_bf16 v[74:77], v[200:203], v[176:179], v[74:77]
	v_mfma_f32_16x16x32_bf16 v[70:73], v[192:195], v[184:187], v[70:73]
	v_mfma_f32_16x16x32_bf16 v[66:69], v[200:203], v[184:187], v[66:69]
	s_barrier
	s_mov_b32 m0, s84
	v_lshl_add_u64 v[206:207], v[204:205], 0, s[34:35]
	ds_read_b128 v[156:159], v136 offset:49152
	ds_read_b128 v[160:163], v136 offset:50176
	ds_read_b128 v[164:167], v136 offset:51200
	ds_read_b128 v[168:171], v136 offset:52224
	ds_read_b128 v[172:175], v136 offset:53248
	ds_read_b128 v[176:179], v136 offset:54272
	ds_read_b128 v[180:183], v136 offset:55296
	ds_read_b128 v[184:187], v136 offset:56320
	global_load_lds_dwordx4 v[206:207], off
	v_lshl_add_u64 v[204:205], v[204:205], 0, s[36:37]
	s_mov_b32 m0, s85
	s_nop 0
	global_load_lds_dwordx4 v[204:205], off
	s_waitcnt lgkmcnt(0)
	s_barrier
	v_mfma_f32_16x16x32_bf16 v[62:65], v[138:141], v[156:159], v[62:65]
	v_mfma_f32_16x16x32_bf16 v[58:61], v[148:151], v[156:159], v[58:61]
	v_mfma_f32_16x16x32_bf16 v[54:57], v[138:141], v[164:167], v[54:57]
	v_mfma_f32_16x16x32_bf16 v[46:49], v[148:151], v[164:167], v[46:49]
	v_mfma_f32_16x16x32_bf16 v[38:41], v[138:141], v[172:175], v[38:41]
	v_mfma_f32_16x16x32_bf16 v[30:33], v[148:151], v[172:175], v[30:33]
	v_mfma_f32_16x16x32_bf16 v[22:25], v[138:141], v[180:183], v[22:25]
	v_mfma_f32_16x16x32_bf16 v[14:17], v[148:151], v[180:183], v[14:17]
	v_mfma_f32_16x16x32_bf16 v[62:65], v[142:145], v[160:163], v[62:65]
	v_mfma_f32_16x16x32_bf16 v[58:61], v[152:155], v[160:163], v[58:61]
	v_mfma_f32_16x16x32_bf16 v[54:57], v[142:145], v[168:171], v[54:57]
	v_mfma_f32_16x16x32_bf16 v[46:49], v[152:155], v[168:171], v[46:49]
	v_mfma_f32_16x16x32_bf16 v[38:41], v[142:145], v[176:179], v[38:41]
	v_mfma_f32_16x16x32_bf16 v[30:33], v[152:155], v[176:179], v[30:33]
	v_mfma_f32_16x16x32_bf16 v[22:25], v[142:145], v[184:187], v[22:25]
	v_mfma_f32_16x16x32_bf16 v[14:17], v[152:155], v[184:187], v[14:17]
	s_barrier
	s_add_i32 s7, s78, s55
	v_lshl_add_u64 v[138:139], v[132:133], 0, s[18:19]
	s_mov_b32 m0, s7
	v_lshl_add_u64 v[132:133], v[132:133], 0, s[14:15]
	global_load_lds_dwordx4 v[138:139], off
	s_add_i32 m0, s7, 0x2000
	s_nop 0
	global_load_lds_dwordx4 v[132:133], off
	s_waitcnt vmcnt(6)
	s_add_i32 s6, s6, 2
	s_add_u32 s8, s8, 0x100
	s_addc_u32 s9, s9, 0
	s_add_u32 s48, s48, 0x100
	s_addc_u32 s49, s49, 0
	s_cmpk_gt_u32 s6, 0x55
	s_cbranch_scc0 .LBB0_679
	s_barrier
	v_mfma_f32_16x16x32_bf16 v[50:53], v[188:191], v[156:159], v[50:53]
	v_mfma_f32_16x16x32_bf16 v[42:45], v[196:199], v[156:159], v[42:45]
	v_mfma_f32_16x16x32_bf16 v[34:37], v[188:191], v[164:167], v[34:37]
	v_mfma_f32_16x16x32_bf16 v[26:29], v[196:199], v[164:167], v[26:29]
	v_mfma_f32_16x16x32_bf16 v[18:21], v[188:191], v[172:175], v[18:21]
	v_mfma_f32_16x16x32_bf16 v[10:13], v[196:199], v[172:175], v[10:13]
	v_mfma_f32_16x16x32_bf16 v[6:9], v[188:191], v[180:183], v[6:9]
	v_mfma_f32_16x16x32_bf16 v[2:5], v[196:199], v[180:183], v[2:5]
	v_mfma_f32_16x16x32_bf16 v[50:53], v[192:195], v[160:163], v[50:53]
	v_mfma_f32_16x16x32_bf16 v[42:45], v[200:203], v[160:163], v[42:45]
	v_mfma_f32_16x16x32_bf16 v[34:37], v[192:195], v[168:171], v[34:37]
	v_mfma_f32_16x16x32_bf16 v[26:29], v[200:203], v[168:171], v[26:29]
	v_mfma_f32_16x16x32_bf16 v[18:21], v[192:195], v[176:179], v[18:21]
	v_mfma_f32_16x16x32_bf16 v[10:13], v[200:203], v[176:179], v[10:13]
	v_mfma_f32_16x16x32_bf16 v[6:9], v[192:195], v[184:187], v[6:9]
	v_mfma_f32_16x16x32_bf16 v[2:5], v[200:203], v[184:187], v[2:5]
	s_barrier
	v_mov_b32_e32 v137, v134
	s_lshl_b32 s6, s88, 8
	v_ashrrev_i32_e32 v132, 2, v137
	s_or_b32 s6, s6, s63
	v_and_b32_e32 v132, -4, v132
	v_add_u32_e32 v132, s6, v132
	s_lshl_b32 s6, s87, 8
	s_add_i32 s6, s6, s62
	v_and_or_b32 v188, v137, 15, s6
	v_ashrrev_i32_e32 v189, 31, v188
	v_ashrrev_i32_e32 v133, 31, v132
	v_lshlrev_b64 v[206:207], 13, v[188:189]
	v_or_b32_e32 v156, 16, v188
	v_or_b32_e32 v172, 32, v188
	v_or_b32_e32 v188, 48, v188
	v_lshlrev_b64 v[132:133], 2, v[132:133]
	v_ashrrev_i32_e32 v157, 31, v156
	v_ashrrev_i32_e32 v173, 31, v172
	v_ashrrev_i32_e32 v189, 31, v188
	v_lshl_add_u64 v[204:205], s[40:41], 0, v[132:133]
	v_lshlrev_b64 v[208:209], 13, v[156:157]
	v_lshlrev_b64 v[210:211], 13, v[172:173]
	v_lshlrev_b64 v[212:213], 13, v[188:189]
	v_lshl_add_u64 v[152:153], v[204:205], 0, v[206:207]
	v_lshl_add_u64 v[168:169], v[204:205], 0, v[208:209]
	v_lshl_add_u64 v[184:185], v[204:205], 0, v[210:211]
	v_lshl_add_u64 v[200:201], v[204:205], 0, v[212:213]
	global_load_dwordx4 v[138:141], v[152:153], off
	global_load_dwordx4 v[142:145], v[152:153], off offset:64
	global_load_dwordx4 v[148:151], v[152:153], off offset:512
	s_nop 0
	global_load_dwordx4 v[152:155], v[152:153], off offset:576
	s_nop 0
	global_load_dwordx4 v[156:159], v[168:169], off
	global_load_dwordx4 v[160:163], v[168:169], off offset:64
	global_load_dwordx4 v[164:167], v[168:169], off offset:512
	s_nop 0
	global_load_dwordx4 v[168:171], v[168:169], off offset:576
	s_nop 0
	global_load_dwordx4 v[172:175], v[184:185], off
	global_load_dwordx4 v[176:179], v[184:185], off offset:64
	global_load_dwordx4 v[180:183], v[184:185], off offset:512
	s_nop 0
	global_load_dwordx4 v[184:187], v[184:185], off offset:576
	s_nop 0
	global_load_dwordx4 v[188:191], v[200:201], off
	global_load_dwordx4 v[192:195], v[200:201], off offset:64
	global_load_dwordx4 v[196:199], v[200:201], off offset:512
	s_nop 0
	global_load_dwordx4 v[200:203], v[200:201], off offset:576
	s_waitcnt vmcnt(0)
	v_pk_fma_f32 v[126:127], v[126:127], 0.5, v[138:139] op_sel_hi:[1,0,1]
	v_lshl_add_u64 v[138:139], s[4:5], 0, v[206:207]
	v_lshl_add_u64 v[138:139], v[138:139], 0, v[132:133]
	v_pk_fma_f32 v[116:117], v[116:117], 0.5, v[150:151] op_sel_hi:[1,0,1]
	v_pk_fma_f32 v[114:115], v[114:115], 0.5, v[148:149] op_sel_hi:[1,0,1]
	global_store_dwordx4 v[138:139], v[114:117], off offset:512
	v_pk_fma_f32 v[100:101], v[100:101], 0.5, v[166:167] op_sel_hi:[1,0,1]
	v_pk_fma_f32 v[98:99], v[98:99], 0.5, v[164:165] op_sel_hi:[1,0,1]
	v_lshl_add_u64 v[114:115], s[4:5], 0, v[208:209]
	v_lshl_add_u64 v[114:115], v[114:115], 0, v[132:133]
	global_store_dwordx4 v[114:115], v[98:101], off offset:512
	v_pk_fma_f32 v[84:85], v[84:85], 0.5, v[182:183] op_sel_hi:[1,0,1]
	v_pk_fma_f32 v[82:83], v[82:83], 0.5, v[180:181] op_sel_hi:[1,0,1]
	v_lshl_add_u64 v[98:99], s[4:5], 0, v[210:211]
	v_lshl_add_u64 v[98:99], v[98:99], 0, v[132:133]
	v_pk_fma_f32 v[108:109], v[108:109], 0.5, v[154:155] op_sel_hi:[1,0,1]
	v_pk_fma_f32 v[106:107], v[106:107], 0.5, v[152:153] op_sel_hi:[1,0,1]
	v_pk_fma_f32 v[92:93], v[92:93], 0.5, v[170:171] op_sel_hi:[1,0,1]
	v_pk_fma_f32 v[90:91], v[90:91], 0.5, v[168:169] op_sel_hi:[1,0,1]
	global_store_dwordx4 v[98:99], v[82:85], off offset:512
	v_pk_fma_f32 v[76:77], v[76:77], 0.5, v[186:187] op_sel_hi:[1,0,1]
	v_pk_fma_f32 v[74:75], v[74:75], 0.5, v[184:185] op_sel_hi:[1,0,1]
	v_lshl_add_u64 v[82:83], s[4:5], 0, v[212:213]
	global_store_dwordx4 v[138:139], v[106:109], off offset:576
	global_store_dwordx4 v[114:115], v[90:93], off offset:576
	global_store_dwordx4 v[98:99], v[74:77], off offset:576
	v_pk_fma_f32 v[108:109], v[120:121], 0.5, v[158:159] op_sel_hi:[1,0,1]
	v_pk_fma_f32 v[106:107], v[118:119], 0.5, v[156:157] op_sel_hi:[1,0,1]
	v_pk_fma_f32 v[92:93], v[104:105], 0.5, v[174:175] op_sel_hi:[1,0,1]
	v_pk_fma_f32 v[90:91], v[102:103], 0.5, v[172:173] op_sel_hi:[1,0,1]
	v_pk_fma_f32 v[76:77], v[88:89], 0.5, v[190:191] op_sel_hi:[1,0,1]
	v_pk_fma_f32 v[74:75], v[86:87], 0.5, v[188:189] op_sel_hi:[1,0,1]
	v_lshl_add_u64 v[82:83], v[82:83], 0, v[132:133]
	v_pk_fma_f32 v[128:129], v[128:129], 0.5, v[140:141] op_sel_hi:[1,0,1]
	v_pk_fma_f32 v[124:125], v[124:125], 0.5, v[144:145] op_sel_hi:[1,0,1]
	v_pk_fma_f32 v[122:123], v[122:123], 0.5, v[142:143] op_sel_hi:[1,0,1]
	global_store_dwordx4 v[114:115], v[106:109], off
	global_store_dwordx4 v[98:99], v[90:93], off
	global_store_dwordx4 v[82:83], v[74:77], off
	v_pk_fma_f32 v[108:109], v[112:113], 0.5, v[162:163] op_sel_hi:[1,0,1]
	v_pk_fma_f32 v[106:107], v[110:111], 0.5, v[160:161] op_sel_hi:[1,0,1]
	v_pk_fma_f32 v[92:93], v[96:97], 0.5, v[178:179] op_sel_hi:[1,0,1]
	v_pk_fma_f32 v[90:91], v[94:95], 0.5, v[176:177] op_sel_hi:[1,0,1]
	v_pk_fma_f32 v[76:77], v[80:81], 0.5, v[194:195] op_sel_hi:[1,0,1]
	v_pk_fma_f32 v[74:75], v[78:79], 0.5, v[192:193] op_sel_hi:[1,0,1]
	v_pk_fma_f32 v[72:73], v[72:73], 0.5, v[198:199] op_sel_hi:[1,0,1]
	v_pk_fma_f32 v[70:71], v[70:71], 0.5, v[196:197] op_sel_hi:[1,0,1]
	v_pk_fma_f32 v[68:69], v[68:69], 0.5, v[202:203] op_sel_hi:[1,0,1]
	v_pk_fma_f32 v[66:67], v[66:67], 0.5, v[200:201] op_sel_hi:[1,0,1]
	global_store_dwordx4 v[138:139], v[126:129], off
	global_store_dwordx4 v[138:139], v[122:125], off offset:64
	global_store_dwordx4 v[114:115], v[106:109], off offset:64
	global_store_dwordx4 v[98:99], v[90:93], off offset:64
	global_store_dwordx4 v[82:83], v[74:77], off offset:64
	global_store_dwordx4 v[82:83], v[70:73], off offset:512
	global_store_dwordx4 v[82:83], v[66:69], off offset:576
	s_mov_b64 s[6:7], 0x120000
	v_lshl_add_u64 v[140:141], v[206:207], 0, s[6:7]
	s_mov_b64 s[6:7], 0x140000
	v_lshl_add_u64 v[138:139], v[206:207], 0, s[0:1]
	v_lshl_add_u64 v[142:143], v[206:207], 0, s[6:7]
	v_lshl_add_u64 v[144:145], v[206:207], 0, s[28:29]
	v_lshl_add_u64 v[78:79], v[204:205], 0, v[138:139]
	v_lshl_add_u64 v[94:95], v[204:205], 0, v[140:141]
	v_lshl_add_u64 v[110:111], v[204:205], 0, v[142:143]
	v_lshl_add_u64 v[126:127], v[204:205], 0, v[144:145]
	global_load_dwordx4 v[66:69], v[78:79], off
	global_load_dwordx4 v[70:73], v[78:79], off offset:64
	global_load_dwordx4 v[74:77], v[78:79], off offset:512
	s_nop 0
	global_load_dwordx4 v[78:81], v[78:79], off offset:576
	s_nop 0
	global_load_dwordx4 v[82:85], v[94:95], off
	global_load_dwordx4 v[86:89], v[94:95], off offset:64
	global_load_dwordx4 v[90:93], v[94:95], off offset:512
	s_nop 0
	global_load_dwordx4 v[94:97], v[94:95], off offset:576
	s_nop 0
	global_load_dwordx4 v[98:101], v[110:111], off
	global_load_dwordx4 v[102:105], v[110:111], off offset:64
	global_load_dwordx4 v[106:109], v[110:111], off offset:512
	s_nop 0
	global_load_dwordx4 v[110:113], v[110:111], off offset:576
	s_nop 0
	global_load_dwordx4 v[114:117], v[126:127], off
	global_load_dwordx4 v[118:121], v[126:127], off offset:64
	global_load_dwordx4 v[122:125], v[126:127], off offset:512
	s_nop 0
	global_load_dwordx4 v[126:129], v[126:127], off offset:576
	s_waitcnt vmcnt(0)
	v_pk_fma_f32 v[62:63], v[62:63], 0.5, v[66:67] op_sel_hi:[1,0,1]
	v_lshl_add_u64 v[66:67], s[4:5], 0, v[138:139]
	v_lshl_add_u64 v[66:67], v[66:67], 0, v[132:133]
	v_pk_fma_f32 v[52:53], v[52:53], 0.5, v[76:77] op_sel_hi:[1,0,1]
	v_pk_fma_f32 v[50:51], v[50:51], 0.5, v[74:75] op_sel_hi:[1,0,1]
	global_store_dwordx4 v[66:67], v[50:53], off offset:512
	v_pk_fma_f32 v[36:37], v[36:37], 0.5, v[92:93] op_sel_hi:[1,0,1]
	v_pk_fma_f32 v[34:35], v[34:35], 0.5, v[90:91] op_sel_hi:[1,0,1]
	v_lshl_add_u64 v[50:51], s[4:5], 0, v[140:141]
	v_lshl_add_u64 v[50:51], v[50:51], 0, v[132:133]
	global_store_dwordx4 v[50:51], v[34:37], off offset:512
	v_pk_fma_f32 v[20:21], v[20:21], 0.5, v[108:109] op_sel_hi:[1,0,1]
	v_pk_fma_f32 v[18:19], v[18:19], 0.5, v[106:107] op_sel_hi:[1,0,1]
	v_lshl_add_u64 v[34:35], s[4:5], 0, v[142:143]
	v_lshl_add_u64 v[34:35], v[34:35], 0, v[132:133]
	v_pk_fma_f32 v[44:45], v[44:45], 0.5, v[80:81] op_sel_hi:[1,0,1]
	v_pk_fma_f32 v[42:43], v[42:43], 0.5, v[78:79] op_sel_hi:[1,0,1]
	v_pk_fma_f32 v[28:29], v[28:29], 0.5, v[96:97] op_sel_hi:[1,0,1]
	v_pk_fma_f32 v[26:27], v[26:27], 0.5, v[94:95] op_sel_hi:[1,0,1]
	global_store_dwordx4 v[34:35], v[18:21], off offset:512
	v_pk_fma_f32 v[12:13], v[12:13], 0.5, v[112:113] op_sel_hi:[1,0,1]
	v_pk_fma_f32 v[10:11], v[10:11], 0.5, v[110:111] op_sel_hi:[1,0,1]
	v_lshl_add_u64 v[18:19], s[4:5], 0, v[144:145]
	global_store_dwordx4 v[66:67], v[42:45], off offset:576
	global_store_dwordx4 v[50:51], v[26:29], off offset:576
	global_store_dwordx4 v[34:35], v[10:13], off offset:576
	v_pk_fma_f32 v[44:45], v[56:57], 0.5, v[84:85] op_sel_hi:[1,0,1]
	v_pk_fma_f32 v[42:43], v[54:55], 0.5, v[82:83] op_sel_hi:[1,0,1]
	v_pk_fma_f32 v[28:29], v[40:41], 0.5, v[100:101] op_sel_hi:[1,0,1]
	v_pk_fma_f32 v[26:27], v[38:39], 0.5, v[98:99] op_sel_hi:[1,0,1]
	v_pk_fma_f32 v[12:13], v[24:25], 0.5, v[116:117] op_sel_hi:[1,0,1]
	v_pk_fma_f32 v[10:11], v[22:23], 0.5, v[114:115] op_sel_hi:[1,0,1]
	v_lshl_add_u64 v[18:19], v[18:19], 0, v[132:133]
	v_pk_fma_f32 v[64:65], v[64:65], 0.5, v[68:69] op_sel_hi:[1,0,1]
	v_pk_fma_f32 v[60:61], v[60:61], 0.5, v[72:73] op_sel_hi:[1,0,1]
	v_pk_fma_f32 v[58:59], v[58:59], 0.5, v[70:71] op_sel_hi:[1,0,1]
	global_store_dwordx4 v[50:51], v[42:45], off
	global_store_dwordx4 v[34:35], v[26:29], off
	global_store_dwordx4 v[18:19], v[10:13], off
	v_pk_fma_f32 v[44:45], v[48:49], 0.5, v[88:89] op_sel_hi:[1,0,1]
	v_pk_fma_f32 v[42:43], v[46:47], 0.5, v[86:87] op_sel_hi:[1,0,1]
	v_pk_fma_f32 v[28:29], v[32:33], 0.5, v[104:105] op_sel_hi:[1,0,1]
	v_pk_fma_f32 v[26:27], v[30:31], 0.5, v[102:103] op_sel_hi:[1,0,1]
	v_pk_fma_f32 v[12:13], v[16:17], 0.5, v[120:121] op_sel_hi:[1,0,1]
	v_pk_fma_f32 v[10:11], v[14:15], 0.5, v[118:119] op_sel_hi:[1,0,1]
	v_pk_fma_f32 v[8:9], v[8:9], 0.5, v[124:125] op_sel_hi:[1,0,1]
	v_pk_fma_f32 v[6:7], v[6:7], 0.5, v[122:123] op_sel_hi:[1,0,1]
	v_pk_fma_f32 v[4:5], v[4:5], 0.5, v[128:129] op_sel_hi:[1,0,1]
	v_pk_fma_f32 v[2:3], v[2:3], 0.5, v[126:127] op_sel_hi:[1,0,1]
	global_store_dwordx4 v[66:67], v[62:65], off
	global_store_dwordx4 v[66:67], v[58:61], off offset:64
	global_store_dwordx4 v[50:51], v[42:45], off offset:64
	global_store_dwordx4 v[34:35], v[26:29], off offset:64
	global_store_dwordx4 v[18:19], v[10:13], off offset:64
	global_store_dwordx4 v[18:19], v[6:9], off offset:512
	global_store_dwordx4 v[18:19], v[2:5], off offset:576
	s_and_b64 vcc, exec, s[42:43]
	s_mov_b32 s87, s10
	s_mov_b32 s88, s11
	s_mov_b64 s[8:9], s[46:47]
	s_mov_b64 s[6:7], s[44:45]
	s_movk_i32 s92, 0x4000
	s_movk_i32 s93, 0xf800
	s_movk_i32 s91, 0x60
	s_mov_b32 s78, 0x2a000000
	s_mov_b32 s79, 0x3fffe
	s_mov_b32 s90, 0xc0000
	s_cbranch_vccz .LBB0_672
	s_waitcnt vmcnt(0)
	s_cmpk_gt_u32 s50, 0xff
	s_cbranch_scc1 .LBB0_683
	s_barrier

.Lrot_enter_0:
	s_add_u32 s8, s6, 0x100
	s_addc_u32 s9, s7, 0
	s_add_i32 s78, 0, 0x10000
	v_add_u32_e32 v134, s78, v137
	ds_read_b128 v[140:143], v134
	ds_read_b128 v[148:151], v134 offset:1024
	ds_read_b128 v[152:155], v134 offset:2048
	ds_read_b128 v[156:159], v134 offset:3072
	s_cmp_eq_u32 s87, 28
	s_cselect_b32 s89, s45, s9
	s_cselect_b32 s88, s44, s8
	s_cselect_b32 s91, s47, s86
	s_cselect_b32 s90, s46, s41
	v_lshl_add_u64 v[134:135], s[6:7], 0, v[132:133]
	v_lshl_add_u64 v[144:145], v[134:135], 0, s[16:17]
	s_add_i32 m0, s49, 0xc000
	ds_read_b128 v[160:163], v138
	ds_read_b128 v[164:167], v138 offset:1024
	ds_read_b128 v[168:171], v138 offset:2048
	ds_read_b128 v[172:175], v138 offset:3072
	ds_read_b128 v[176:179], v138 offset:4096
	ds_read_b128 v[180:183], v138 offset:5120
	ds_read_b128 v[184:187], v138 offset:6144
	ds_read_b128 v[188:191], v138 offset:7168
	global_load_lds_dwordx4 v[144:145], off
	v_lshl_add_u64 v[134:135], v[134:135], 0, s[80:81]
	s_add_i32 m0, s49, 0xe000
	s_nop 0
	global_load_lds_dwordx4 v[134:135], off
	s_waitcnt lgkmcnt(8)
	s_barrier
	s_waitcnt lgkmcnt(0)
	v_mfma_f32_16x16x32_bf16 v[126:129], v[140:143], v[160:163], v[126:129]
	v_mfma_f32_16x16x32_bf16 v[122:125], v[152:155], v[160:163], v[122:125]
	v_mfma_f32_16x16x32_bf16 v[110:113], v[140:143], v[168:171], v[110:113]
	v_mfma_f32_16x16x32_bf16 v[106:109], v[152:155], v[168:171], v[106:109]
	v_mfma_f32_16x16x32_bf16 v[94:97], v[140:143], v[176:179], v[94:97]
	v_mfma_f32_16x16x32_bf16 v[90:93], v[152:155], v[176:179], v[90:93]
	v_mfma_f32_16x16x32_bf16 v[78:81], v[140:143], v[184:187], v[78:81]
	v_mfma_f32_16x16x32_bf16 v[74:77], v[152:155], v[184:187], v[74:77]
	v_mfma_f32_16x16x32_bf16 v[126:129], v[148:151], v[164:167], v[126:129]
	v_mfma_f32_16x16x32_bf16 v[122:125], v[156:159], v[164:167], v[122:125]
	v_mfma_f32_16x16x32_bf16 v[110:113], v[148:151], v[172:175], v[110:113]
	v_mfma_f32_16x16x32_bf16 v[106:109], v[156:159], v[172:175], v[106:109]
	v_mfma_f32_16x16x32_bf16 v[94:97], v[148:151], v[180:183], v[94:97]
	v_mfma_f32_16x16x32_bf16 v[90:93], v[156:159], v[180:183], v[90:93]
	v_mfma_f32_16x16x32_bf16 v[78:81], v[148:151], v[188:191], v[78:81]
	v_mfma_f32_16x16x32_bf16 v[74:77], v[156:159], v[188:191], v[74:77]
	s_barrier
	s_add_i32 s6, 0, 0x14000
	v_add_u32_e32 v134, s6, v137
	s_add_i32 s7, s78, s54
	ds_read_b128 v[192:195], v134
	ds_read_b128 v[196:199], v134 offset:1024
	ds_read_b128 v[200:203], v134 offset:2048
	ds_read_b128 v[204:207], v134 offset:3072
	v_lshl_add_u64 v[134:135], s[90:91], 0, v[0:1]
	s_mov_b32 m0, s7
	v_lshl_add_u64 v[144:145], v[134:135], 0, s[60:61]
	global_load_lds_dwordx4 v[134:135], off
	s_add_i32 m0, s7, 0x2000
	s_nop 0
	global_load_lds_dwordx4 v[144:145], off
	s_waitcnt lgkmcnt(0)
	s_barrier
	v_mfma_f32_16x16x32_bf16 v[118:121], v[192:195], v[160:163], v[118:121]
	v_mfma_f32_16x16x32_bf16 v[114:117], v[200:203], v[160:163], v[114:117]
	v_mfma_f32_16x16x32_bf16 v[102:105], v[192:195], v[168:171], v[102:105]
	v_mfma_f32_16x16x32_bf16 v[98:101], v[200:203], v[168:171], v[98:101]
	v_mfma_f32_16x16x32_bf16 v[86:89], v[192:195], v[176:179], v[86:89]
	v_mfma_f32_16x16x32_bf16 v[82:85], v[200:203], v[176:179], v[82:85]
	v_mfma_f32_16x16x32_bf16 v[70:73], v[192:195], v[184:187], v[70:73]
	v_mfma_f32_16x16x32_bf16 v[66:69], v[200:203], v[184:187], v[66:69]
	v_mfma_f32_16x16x32_bf16 v[118:121], v[196:199], v[164:167], v[118:121]
	v_mfma_f32_16x16x32_bf16 v[114:117], v[204:207], v[164:167], v[114:117]
	v_mfma_f32_16x16x32_bf16 v[102:105], v[196:199], v[172:175], v[102:105]
	v_mfma_f32_16x16x32_bf16 v[98:101], v[204:207], v[172:175], v[98:101]
	v_mfma_f32_16x16x32_bf16 v[86:89], v[196:199], v[180:183], v[86:89]
	v_mfma_f32_16x16x32_bf16 v[82:85], v[204:207], v[180:183], v[82:85]
	v_mfma_f32_16x16x32_bf16 v[70:73], v[196:199], v[188:191], v[70:73]
	v_mfma_f32_16x16x32_bf16 v[66:69], v[204:207], v[188:191], v[66:69]
	s_barrier
	s_mov_b32 m0, s49
	v_lshl_add_u64 v[144:145], s[88:89], 0, v[130:131]
	ds_read_b128 v[160:163], v138 offset:16384
	ds_read_b128 v[164:167], v138 offset:17408
	ds_read_b128 v[168:171], v138 offset:18432
	ds_read_b128 v[172:175], v138 offset:19456
	ds_read_b128 v[176:179], v138 offset:20480
	ds_read_b128 v[180:183], v138 offset:21504
	ds_read_b128 v[184:187], v138 offset:22528
	ds_read_b128 v[188:191], v138 offset:23552
	global_load_lds_dwordx4 v[144:145], off
	v_lshl_add_u64 v[208:209], v[144:145], 0, s[60:61]
	s_mov_b32 m0, s55
	s_nop 0
	global_load_lds_dwordx4 v[208:209], off
	s_waitcnt lgkmcnt(0)
	s_barrier
	v_mfma_f32_16x16x32_bf16 v[62:65], v[140:143], v[160:163], v[62:65]
	v_mfma_f32_16x16x32_bf16 v[58:61], v[152:155], v[160:163], v[58:61]
	v_mfma_f32_16x16x32_bf16 v[46:49], v[140:143], v[168:171], v[46:49]
	v_mfma_f32_16x16x32_bf16 v[42:45], v[152:155], v[168:171], v[42:45]
	v_mfma_f32_16x16x32_bf16 v[30:33], v[140:143], v[176:179], v[30:33]
	v_mfma_f32_16x16x32_bf16 v[26:29], v[152:155], v[176:179], v[26:29]
	v_mfma_f32_16x16x32_bf16 v[14:17], v[140:143], v[184:187], v[14:17]
	v_mfma_f32_16x16x32_bf16 v[10:13], v[152:155], v[184:187], v[10:13]
	v_mfma_f32_16x16x32_bf16 v[62:65], v[148:151], v[164:167], v[62:65]
	v_mfma_f32_16x16x32_bf16 v[58:61], v[156:159], v[164:167], v[58:61]
	v_mfma_f32_16x16x32_bf16 v[46:49], v[148:151], v[172:175], v[46:49]
	v_mfma_f32_16x16x32_bf16 v[42:45], v[156:159], v[172:175], v[42:45]
	v_mfma_f32_16x16x32_bf16 v[30:33], v[148:151], v[180:183], v[30:33]
	v_mfma_f32_16x16x32_bf16 v[26:29], v[156:159], v[180:183], v[26:29]
	v_mfma_f32_16x16x32_bf16 v[14:17], v[148:151], v[188:191], v[14:17]
	v_mfma_f32_16x16x32_bf16 v[10:13], v[156:159], v[188:191], v[10:13]
	s_barrier
	s_add_i32 s6, s6, s54
	v_lshl_add_u64 v[140:141], v[134:135], 0, s[20:21]
	s_mov_b32 m0, s6
	s_nop 0
	global_load_lds_dwordx4 v[140:141], off
	v_lshl_add_u64 v[140:141], v[134:135], 0, s[64:65]
	s_add_i32 m0, s6, 0x2000
	s_nop 0
	global_load_lds_dwordx4 v[140:141], off
	v_lshl_add_u64 v[230:231], v[144:145], 0, s[20:21]
	s_mov_b32 m0, s56
	s_nop 0
	global_load_lds_dwordx4 v[230:231], off
	v_lshl_add_u64 v[230:231], v[144:145], 0, s[64:65]
	s_mov_b32 m0, s57
	s_nop 0
	global_load_lds_dwordx4 v[230:231], off
	s_waitcnt vmcnt(8)
	s_barrier
	v_mfma_f32_16x16x32_bf16 v[54:57], v[192:195], v[160:163], v[54:57]
	v_mfma_f32_16x16x32_bf16 v[50:53], v[200:203], v[160:163], v[50:53]
	v_mfma_f32_16x16x32_bf16 v[38:41], v[192:195], v[168:171], v[38:41]
	v_mfma_f32_16x16x32_bf16 v[34:37], v[200:203], v[168:171], v[34:37]
	v_mfma_f32_16x16x32_bf16 v[22:25], v[192:195], v[176:179], v[22:25]
	v_mfma_f32_16x16x32_bf16 v[18:21], v[200:203], v[176:179], v[18:21]
	v_mfma_f32_16x16x32_bf16 v[6:9], v[192:195], v[184:187], v[6:9]
	v_mfma_f32_16x16x32_bf16 v[2:5], v[200:203], v[184:187], v[2:5]
	v_mfma_f32_16x16x32_bf16 v[54:57], v[196:199], v[164:167], v[54:57]
	v_mfma_f32_16x16x32_bf16 v[50:53], v[204:207], v[164:167], v[50:53]
	v_mfma_f32_16x16x32_bf16 v[38:41], v[196:199], v[172:175], v[38:41]
	v_mfma_f32_16x16x32_bf16 v[34:37], v[204:207], v[172:175], v[34:37]
	v_mfma_f32_16x16x32_bf16 v[22:25], v[196:199], v[180:183], v[22:25]
	v_mfma_f32_16x16x32_bf16 v[18:21], v[204:207], v[180:183], v[18:21]
	v_mfma_f32_16x16x32_bf16 v[6:9], v[196:199], v[188:191], v[6:9]
	v_mfma_f32_16x16x32_bf16 v[2:5], v[204:207], v[188:191], v[2:5]
	s_barrier
	s_add_i32 s6, 0, 0x18000
	v_add_u32_e32 v139, s6, v137
	ds_read_b128 v[140:143], v139
	ds_read_b128 v[148:151], v139 offset:1024
	ds_read_b128 v[152:155], v139 offset:2048
	ds_read_b128 v[156:159], v139 offset:3072
	ds_read_b128 v[160:163], v138 offset:32768
	ds_read_b128 v[164:167], v138 offset:33792
	ds_read_b128 v[168:171], v138 offset:34816
	ds_read_b128 v[172:175], v138 offset:35840
	ds_read_b128 v[176:179], v138 offset:36864
	ds_read_b128 v[180:183], v138 offset:37888
	ds_read_b128 v[184:187], v138 offset:38912
	ds_read_b128 v[188:191], v138 offset:39936
	s_waitcnt lgkmcnt(8)
	s_barrier
	s_waitcnt lgkmcnt(0)
	v_mfma_f32_16x16x32_bf16 v[126:129], v[140:143], v[160:163], v[126:129]
	v_mfma_f32_16x16x32_bf16 v[122:125], v[152:155], v[160:163], v[122:125]
	v_mfma_f32_16x16x32_bf16 v[110:113], v[140:143], v[168:171], v[110:113]
	v_mfma_f32_16x16x32_bf16 v[106:109], v[152:155], v[168:171], v[106:109]
	v_mfma_f32_16x16x32_bf16 v[94:97], v[140:143], v[176:179], v[94:97]
	v_mfma_f32_16x16x32_bf16 v[90:93], v[152:155], v[176:179], v[90:93]
	v_mfma_f32_16x16x32_bf16 v[78:81], v[140:143], v[184:187], v[78:81]
	v_mfma_f32_16x16x32_bf16 v[74:77], v[152:155], v[184:187], v[74:77]
	v_mfma_f32_16x16x32_bf16 v[126:129], v[148:151], v[164:167], v[126:129]
	v_mfma_f32_16x16x32_bf16 v[122:125], v[156:159], v[164:167], v[122:125]
	v_mfma_f32_16x16x32_bf16 v[110:113], v[148:151], v[172:175], v[110:113]
	v_mfma_f32_16x16x32_bf16 v[106:109], v[156:159], v[172:175], v[106:109]
	v_mfma_f32_16x16x32_bf16 v[94:97], v[148:151], v[180:183], v[94:97]
	v_mfma_f32_16x16x32_bf16 v[90:93], v[156:159], v[180:183], v[90:93]
	v_mfma_f32_16x16x32_bf16 v[78:81], v[148:151], v[188:191], v[78:81]
	v_mfma_f32_16x16x32_bf16 v[74:77], v[156:159], v[188:191], v[74:77]
	s_barrier
	s_add_i32 s7, 0, 0x1c000
	s_add_i32 s6, s6, s54
	v_add_u32_e32 v139, s7, v137
	v_lshl_add_u64 v[208:209], v[134:135], 0, s[34:35]
	s_mov_b32 m0, s6
	ds_read_b128 v[192:195], v139
	ds_read_b128 v[196:199], v139 offset:1024
	ds_read_b128 v[200:203], v139 offset:2048
	ds_read_b128 v[204:207], v139 offset:3072
	global_load_lds_dwordx4 v[208:209], off
	v_lshl_add_u64 v[208:209], v[134:135], 0, s[66:67]
	s_add_i32 m0, s6, 0x2000
	s_nop 0
	global_load_lds_dwordx4 v[208:209], off
	s_waitcnt lgkmcnt(0)
	s_barrier
	v_mfma_f32_16x16x32_bf16 v[118:121], v[192:195], v[160:163], v[118:121]
	v_mfma_f32_16x16x32_bf16 v[114:117], v[200:203], v[160:163], v[114:117]
	v_mfma_f32_16x16x32_bf16 v[102:105], v[192:195], v[168:171], v[102:105]
	v_mfma_f32_16x16x32_bf16 v[98:101], v[200:203], v[168:171], v[98:101]
	v_mfma_f32_16x16x32_bf16 v[86:89], v[192:195], v[176:179], v[86:89]
	v_mfma_f32_16x16x32_bf16 v[82:85], v[200:203], v[176:179], v[82:85]
	v_mfma_f32_16x16x32_bf16 v[70:73], v[192:195], v[184:187], v[70:73]
	v_mfma_f32_16x16x32_bf16 v[66:69], v[200:203], v[184:187], v[66:69]
	v_mfma_f32_16x16x32_bf16 v[118:121], v[196:199], v[164:167], v[118:121]
	v_mfma_f32_16x16x32_bf16 v[114:117], v[204:207], v[164:167], v[114:117]
	v_mfma_f32_16x16x32_bf16 v[102:105], v[196:199], v[172:175], v[102:105]
	v_mfma_f32_16x16x32_bf16 v[98:101], v[204:207], v[172:175], v[98:101]
	v_mfma_f32_16x16x32_bf16 v[86:89], v[196:199], v[180:183], v[86:89]
	v_mfma_f32_16x16x32_bf16 v[82:85], v[204:207], v[180:183], v[82:85]
	v_mfma_f32_16x16x32_bf16 v[70:73], v[196:199], v[188:191], v[70:73]
	v_mfma_f32_16x16x32_bf16 v[66:69], v[204:207], v[188:191], v[66:69]
	s_barrier
	s_mov_b32 m0, s58
	v_lshl_add_u64 v[208:209], v[144:145], 0, s[34:35]
	ds_read_b128 v[160:163], v138 offset:49152
	ds_read_b128 v[164:167], v138 offset:50176
	ds_read_b128 v[168:171], v138 offset:51200
	ds_read_b128 v[172:175], v138 offset:52224
	ds_read_b128 v[176:179], v138 offset:53248
	ds_read_b128 v[180:183], v138 offset:54272
	ds_read_b128 v[184:187], v138 offset:55296
	ds_read_b128 v[188:191], v138 offset:56320
	global_load_lds_dwordx4 v[208:209], off
	v_lshl_add_u64 v[144:145], v[144:145], 0, s[66:67]
	s_mov_b32 m0, s59
	s_nop 0
	global_load_lds_dwordx4 v[144:145], off
	s_waitcnt lgkmcnt(0)
	s_barrier
	v_mfma_f32_16x16x32_bf16 v[62:65], v[140:143], v[160:163], v[62:65]
	v_mfma_f32_16x16x32_bf16 v[58:61], v[152:155], v[160:163], v[58:61]
	v_mfma_f32_16x16x32_bf16 v[46:49], v[140:143], v[168:171], v[46:49]
	v_mfma_f32_16x16x32_bf16 v[42:45], v[152:155], v[168:171], v[42:45]
	v_mfma_f32_16x16x32_bf16 v[30:33], v[140:143], v[176:179], v[30:33]
	v_mfma_f32_16x16x32_bf16 v[26:29], v[152:155], v[176:179], v[26:29]
	v_mfma_f32_16x16x32_bf16 v[14:17], v[140:143], v[184:187], v[14:17]
	v_mfma_f32_16x16x32_bf16 v[10:13], v[152:155], v[184:187], v[10:13]
	v_mfma_f32_16x16x32_bf16 v[62:65], v[148:151], v[164:167], v[62:65]
	v_mfma_f32_16x16x32_bf16 v[58:61], v[156:159], v[164:167], v[58:61]
	v_mfma_f32_16x16x32_bf16 v[46:49], v[148:151], v[172:175], v[46:49]
	v_mfma_f32_16x16x32_bf16 v[42:45], v[156:159], v[172:175], v[42:45]
	v_mfma_f32_16x16x32_bf16 v[30:33], v[148:151], v[180:183], v[30:33]
	v_mfma_f32_16x16x32_bf16 v[26:29], v[156:159], v[180:183], v[26:29]
	v_mfma_f32_16x16x32_bf16 v[14:17], v[148:151], v[188:191], v[14:17]
	v_mfma_f32_16x16x32_bf16 v[10:13], v[156:159], v[188:191], v[10:13]
	s_barrier
	s_add_i32 s6, s7, s54
	v_lshl_add_u64 v[140:141], v[134:135], 0, s[16:17]
	s_mov_b32 m0, s6
	v_lshl_add_u64 v[134:135], v[134:135], 0, s[80:81]
	global_load_lds_dwordx4 v[140:141], off
	s_add_i32 m0, s6, 0x2000
	s_nop 0
	global_load_lds_dwordx4 v[134:135], off
	s_waitcnt vmcnt(6)
	s_add_i32 s87, s87, 2
	s_add_u32 s41, s41, 0x100
	s_addc_u32 s86, s86, 0
	s_cmp_gt_u32 s87, 29
	s_mov_b64 s[6:7], s[8:9]
	s_cbranch_scc0 .LBB0_694
	s_barrier
	v_mfma_f32_16x16x32_bf16 v[54:57], v[192:195], v[160:163], v[54:57]
	v_mfma_f32_16x16x32_bf16 v[50:53], v[200:203], v[160:163], v[50:53]
	v_mfma_f32_16x16x32_bf16 v[38:41], v[192:195], v[168:171], v[38:41]
	v_mfma_f32_16x16x32_bf16 v[34:37], v[200:203], v[168:171], v[34:37]
	v_mfma_f32_16x16x32_bf16 v[22:25], v[192:195], v[176:179], v[22:25]
	v_mfma_f32_16x16x32_bf16 v[18:21], v[200:203], v[176:179], v[18:21]
	v_mfma_f32_16x16x32_bf16 v[6:9], v[192:195], v[184:187], v[6:9]
	v_mfma_f32_16x16x32_bf16 v[2:5], v[200:203], v[184:187], v[2:5]
	v_mfma_f32_16x16x32_bf16 v[54:57], v[196:199], v[164:167], v[54:57]
	v_mfma_f32_16x16x32_bf16 v[50:53], v[204:207], v[164:167], v[50:53]
	v_mfma_f32_16x16x32_bf16 v[38:41], v[196:199], v[172:175], v[38:41]
	v_mfma_f32_16x16x32_bf16 v[34:37], v[204:207], v[172:175], v[34:37]
	v_mfma_f32_16x16x32_bf16 v[22:25], v[196:199], v[180:183], v[22:25]
	v_mfma_f32_16x16x32_bf16 v[18:21], v[204:207], v[180:183], v[18:21]
	v_mfma_f32_16x16x32_bf16 v[6:9], v[196:199], v[188:191], v[6:9]
	v_mfma_f32_16x16x32_bf16 v[2:5], v[204:207], v[188:191], v[2:5]
	s_barrier
	v_mov_b32_e32 v134, v136
	s_lshl_b32 s6, s48, 8
	s_add_i32 s6, s6, s10
	v_and_or_b32 v139, v134, 15, s6
	s_lshl_b32 s6, s85, 7
	v_ashrrev_i32_e32 v134, 1, v134
	s_or_b32 s6, s6, s62
	v_and_b32_e32 v134, -8, v134
	v_add_u32_e32 v140, s6, v134
	v_mul_f32_e32 v134, 0xbfb8aa3b, v126
	v_exp_f32_e32 v142, v134
	v_mul_f32_e32 v134, 0xbfb8aa3b, v127
	v_exp_f32_e32 v143, v134
	v_ashrrev_i32_e32 v141, 31, v140
	v_add_f32_e32 v142, 1.0, v142
	v_rcp_f32_e32 v144, v142
	v_add_f32_e32 v142, 1.0, v143
	v_rcp_f32_e32 v145, v142
	v_mov_b64_e32 v[134:135], s[4:5]
	v_mul_f32_e32 v126, v126, v144
	v_mul_f32_e32 v118, v126, v118
	v_mul_f32_e32 v126, v127, v145
	v_mul_f32_e32 v127, 0xbfb8aa3b, v128
	v_exp_f32_e32 v127, v127
	v_mul_f32_e32 v144, 0xbfb8aa3b, v129
	v_exp_f32_e32 v144, v144
	v_mul_f32_e32 v119, v126, v119
	v_add_f32_e32 v126, 1.0, v127
	v_rcp_f32_e32 v126, v126
	v_add_f32_e32 v127, 1.0, v144
	v_mul_f32_e32 v144, 0xbfb8aa3b, v122
	v_rcp_f32_e32 v127, v127
	v_exp_f32_e32 v144, v144
	v_mul_f32_e32 v126, v128, v126
	v_mul_f32_e32 v126, v126, v120
	v_mul_f32_e32 v120, v129, v127
	v_add_f32_e32 v127, 1.0, v144
	v_rcp_f32_e32 v127, v127
	v_mul_f32_e32 v128, 0xbfb8aa3b, v123
	v_mul_f32_e32 v129, v120, v121
	v_exp_f32_e32 v128, v128
	v_mul_f32_e32 v120, v122, v127
	v_mul_f32_e32 v122, v120, v114
	v_mul_f32_e32 v120, 0xbfb8aa3b, v124
	v_exp_f32_e32 v120, v120
	v_mul_f32_e32 v121, 0xbfb8aa3b, v125
	v_exp_f32_e32 v121, v121
	v_add_f32_e32 v114, 1.0, v128
	v_rcp_f32_e32 v114, v114
	v_add_f32_e32 v120, 1.0, v120
	v_rcp_f32_e32 v120, v120
	v_add_f32_e32 v121, 1.0, v121
	v_rcp_f32_e32 v121, v121
	v_mul_f32_e32 v114, v123, v114
	v_mul_f32_e32 v123, v114, v115
	v_mul_f32_e32 v114, v124, v120
	v_mul_f32_e32 v124, v114, v116
	v_mul_f32_e32 v114, v125, v121
	v_mad_i64_i32 v[142:143], s[6:7], v139, s74, v[134:135]
	v_mul_f32_e32 v125, v114, v117
	v_lshlrev_b64 v[114:115], 1, v[140:141]
	v_lshl_add_u64 v[120:121], v[142:143], 0, v[114:115]
	v_cvt_pk_bf16_f32 v116, v118, v119
	v_cvt_pk_bf16_f32 v117, v126, v129
	v_cvt_pk_bf16_f32 v118, v122, v123
	v_cvt_pk_bf16_f32 v119, v124, v125
	global_store_dwordx4 v[120:121], v[116:119], off
	s_and_b64 vcc, exec, s[42:43]
	s_mov_b32 s48, s40
	v_mul_f32_e32 v116, 0xbfb8aa3b, v110
	v_exp_f32_e32 v116, v116
	v_mul_f32_e32 v117, 0xbfb8aa3b, v111
	v_exp_f32_e32 v117, v117
	v_or_b32_e32 v118, 16, v139
	v_add_f32_e32 v116, 1.0, v116
	v_rcp_f32_e32 v119, v116
	v_add_f32_e32 v116, 1.0, v117
	v_rcp_f32_e32 v120, v116
	v_mad_i64_i32 v[116:117], s[6:7], v118, s74, v[134:135]
	v_mul_f32_e32 v110, v110, v119
	v_mul_f32_e32 v110, v110, v102
	v_mul_f32_e32 v102, v111, v120
	v_mul_f32_e32 v111, 0xbfb8aa3b, v112
	v_exp_f32_e32 v111, v111
	v_mul_f32_e32 v118, 0xbfb8aa3b, v113
	v_exp_f32_e32 v118, v118
	v_mul_f32_e32 v119, v102, v103
	v_add_f32_e32 v102, 1.0, v111
	v_rcp_f32_e32 v102, v102
	v_add_f32_e32 v103, 1.0, v118
	v_mul_f32_e32 v111, 0xbfb8aa3b, v106
	v_rcp_f32_e32 v103, v103
	v_exp_f32_e32 v111, v111
	v_mul_f32_e32 v102, v112, v102
	v_mul_f32_e32 v104, v102, v104
	v_mul_f32_e32 v102, v113, v103
	v_add_f32_e32 v103, 1.0, v111
	v_rcp_f32_e32 v103, v103
	v_mul_f32_e32 v111, 0xbfb8aa3b, v107
	v_mul_f32_e32 v105, v102, v105
	v_exp_f32_e32 v111, v111
	v_mul_f32_e32 v102, v106, v103
	v_mul_f32_e32 v106, v102, v98
	v_mul_f32_e32 v102, 0xbfb8aa3b, v108
	v_exp_f32_e32 v102, v102
	v_mul_f32_e32 v103, 0xbfb8aa3b, v109
	v_exp_f32_e32 v103, v103
	v_add_f32_e32 v98, 1.0, v111
	v_rcp_f32_e32 v98, v98
	v_add_f32_e32 v102, 1.0, v102
	v_rcp_f32_e32 v102, v102
	v_add_f32_e32 v103, 1.0, v103
	v_rcp_f32_e32 v103, v103
	v_mul_f32_e32 v98, v107, v98
	v_mul_f32_e32 v107, v98, v99
	v_mul_f32_e32 v98, v108, v102
	v_mul_f32_e32 v108, v98, v100
	v_mul_f32_e32 v98, v109, v103
	v_mul_f32_e32 v101, v98, v101
	v_lshl_add_u64 v[102:103], v[116:117], 0, v[114:115]
	v_cvt_pk_bf16_f32 v98, v110, v119
	v_cvt_pk_bf16_f32 v99, v104, v105
	v_cvt_pk_bf16_f32 v100, v106, v107
	v_cvt_pk_bf16_f32 v101, v108, v101
	global_store_dwordx4 v[102:103], v[98:101], off
	s_mov_b32 s85, s84
	s_mov_b64 s[8:9], s[46:47]
	v_mul_f32_e32 v98, 0xbfb8aa3b, v94
	v_exp_f32_e32 v98, v98
	v_mul_f32_e32 v99, 0xbfb8aa3b, v95
	v_exp_f32_e32 v99, v99
	v_or_b32_e32 v100, 32, v139
	v_add_f32_e32 v98, 1.0, v98
	v_rcp_f32_e32 v101, v98
	v_add_f32_e32 v98, 1.0, v99
	v_rcp_f32_e32 v102, v98
	v_mad_i64_i32 v[98:99], s[6:7], v100, s74, v[134:135]
	v_mul_f32_e32 v94, v94, v101
	v_mul_f32_e32 v94, v94, v86
	v_mul_f32_e32 v86, v95, v102
	v_mul_f32_e32 v95, 0xbfb8aa3b, v96
	v_exp_f32_e32 v95, v95
	v_mul_f32_e32 v100, 0xbfb8aa3b, v97
	v_exp_f32_e32 v100, v100
	v_mul_f32_e32 v101, v86, v87
	v_add_f32_e32 v86, 1.0, v95
	v_rcp_f32_e32 v86, v86
	v_add_f32_e32 v87, 1.0, v100
	v_mul_f32_e32 v95, 0xbfb8aa3b, v90
	v_rcp_f32_e32 v87, v87
	v_exp_f32_e32 v95, v95
	v_mul_f32_e32 v86, v96, v86
	v_mul_f32_e32 v88, v86, v88
	v_mul_f32_e32 v86, v97, v87
	v_add_f32_e32 v87, 1.0, v95
	v_rcp_f32_e32 v87, v87
	v_mul_f32_e32 v95, 0xbfb8aa3b, v91
	v_mul_f32_e32 v89, v86, v89
	v_exp_f32_e32 v95, v95
	v_mul_f32_e32 v86, v90, v87
	v_mul_f32_e32 v90, v86, v82
	v_mul_f32_e32 v86, 0xbfb8aa3b, v92
	v_exp_f32_e32 v86, v86
	v_mul_f32_e32 v87, 0xbfb8aa3b, v93
	v_exp_f32_e32 v87, v87
	v_add_f32_e32 v82, 1.0, v95
	v_rcp_f32_e32 v82, v82
	v_add_f32_e32 v86, 1.0, v86
	v_rcp_f32_e32 v86, v86
	v_add_f32_e32 v87, 1.0, v87
	v_rcp_f32_e32 v87, v87
	v_mul_f32_e32 v82, v91, v82
	v_mul_f32_e32 v91, v82, v83
	v_mul_f32_e32 v82, v92, v86
	v_mul_f32_e32 v92, v82, v84
	v_mul_f32_e32 v82, v93, v87
	v_mul_f32_e32 v85, v82, v85
	v_lshl_add_u64 v[86:87], v[98:99], 0, v[114:115]
	v_cvt_pk_bf16_f32 v82, v94, v101
	v_cvt_pk_bf16_f32 v83, v88, v89
	v_cvt_pk_bf16_f32 v84, v90, v91
	v_cvt_pk_bf16_f32 v85, v92, v85
	global_store_dwordx4 v[86:87], v[82:85], off
	s_nop 1
	v_mul_f32_e32 v82, 0xbfb8aa3b, v78
	v_exp_f32_e32 v82, v82
	v_mul_f32_e32 v83, 0xbfb8aa3b, v79
	v_exp_f32_e32 v83, v83
	v_or_b32_e32 v84, 48, v139
	v_add_f32_e32 v82, 1.0, v82
	v_rcp_f32_e32 v85, v82
	v_add_f32_e32 v82, 1.0, v83
	v_rcp_f32_e32 v86, v82
	v_mad_i64_i32 v[82:83], s[6:7], v84, s74, v[134:135]
	v_mul_f32_e32 v78, v78, v85
	v_mul_f32_e32 v78, v78, v70
	v_mul_f32_e32 v70, v79, v86
	v_mul_f32_e32 v79, 0xbfb8aa3b, v80
	v_exp_f32_e32 v79, v79
	v_mul_f32_e32 v84, 0xbfb8aa3b, v81
	v_exp_f32_e32 v84, v84
	v_mul_f32_e32 v85, v70, v71
	v_add_f32_e32 v70, 1.0, v79
	v_rcp_f32_e32 v70, v70
	v_add_f32_e32 v71, 1.0, v84
	v_mul_f32_e32 v79, 0xbfb8aa3b, v74
	v_rcp_f32_e32 v71, v71
	v_exp_f32_e32 v79, v79
	v_mul_f32_e32 v70, v80, v70
	v_mul_f32_e32 v72, v70, v72
	v_mul_f32_e32 v70, v81, v71
	v_add_f32_e32 v71, 1.0, v79
	v_rcp_f32_e32 v71, v71
	v_mul_f32_e32 v79, 0xbfb8aa3b, v75
	v_mul_f32_e32 v73, v70, v73
	v_exp_f32_e32 v79, v79
	v_mul_f32_e32 v70, v74, v71
	v_mul_f32_e32 v74, v70, v66
	v_mul_f32_e32 v70, 0xbfb8aa3b, v76
	v_exp_f32_e32 v70, v70
	v_mul_f32_e32 v71, 0xbfb8aa3b, v77
	v_exp_f32_e32 v71, v71
	v_add_f32_e32 v66, 1.0, v79
	v_rcp_f32_e32 v66, v66
	v_add_f32_e32 v70, 1.0, v70
	v_rcp_f32_e32 v70, v70
	v_add_f32_e32 v71, 1.0, v71
	v_rcp_f32_e32 v71, v71
	v_mul_f32_e32 v66, v75, v66
	v_mul_f32_e32 v75, v66, v67
	v_mul_f32_e32 v66, v76, v70
	v_mul_f32_e32 v76, v66, v68
	v_mul_f32_e32 v66, v77, v71
	v_mul_f32_e32 v69, v66, v69
	v_lshl_add_u64 v[70:71], v[82:83], 0, v[114:115]
	v_cvt_pk_bf16_f32 v66, v78, v85
	v_cvt_pk_bf16_f32 v67, v72, v73
	v_cvt_pk_bf16_f32 v68, v74, v75
	v_cvt_pk_bf16_f32 v69, v76, v69
	global_store_dwordx4 v[70:71], v[66:69], off
	s_nop 1
	v_mul_f32_e32 v66, 0xbfb8aa3b, v62
	v_exp_f32_e32 v66, v66
	v_mul_f32_e32 v67, 0xbfb8aa3b, v63
	v_exp_f32_e32 v67, v67
	v_add_u32_e32 v68, 0x80, v139
	v_add_f32_e32 v66, 1.0, v66
	v_rcp_f32_e32 v69, v66
	v_add_f32_e32 v66, 1.0, v67
	v_rcp_f32_e32 v70, v66
	v_mad_i64_i32 v[66:67], s[6:7], v68, s74, v[134:135]
	v_mul_f32_e32 v62, v62, v69
	v_mul_f32_e32 v62, v62, v54
	v_mul_f32_e32 v54, v63, v70
	v_mul_f32_e32 v63, 0xbfb8aa3b, v64
	v_exp_f32_e32 v63, v63
	v_mul_f32_e32 v68, 0xbfb8aa3b, v65
	v_exp_f32_e32 v68, v68
	v_mul_f32_e32 v69, v54, v55
	v_add_f32_e32 v54, 1.0, v63
	v_rcp_f32_e32 v54, v54
	v_add_f32_e32 v55, 1.0, v68
	v_mul_f32_e32 v63, 0xbfb8aa3b, v58
	v_rcp_f32_e32 v55, v55
	v_exp_f32_e32 v63, v63
	v_mul_f32_e32 v54, v64, v54
	v_mul_f32_e32 v56, v54, v56
	v_mul_f32_e32 v54, v65, v55
	v_add_f32_e32 v55, 1.0, v63
	v_rcp_f32_e32 v55, v55
	v_mul_f32_e32 v63, 0xbfb8aa3b, v59
	v_mul_f32_e32 v57, v54, v57
	v_exp_f32_e32 v63, v63
	v_mul_f32_e32 v54, v58, v55
	v_mul_f32_e32 v58, v54, v50
	v_mul_f32_e32 v54, 0xbfb8aa3b, v60
	v_exp_f32_e32 v54, v54
	v_mul_f32_e32 v55, 0xbfb8aa3b, v61
	v_exp_f32_e32 v55, v55
	v_add_f32_e32 v50, 1.0, v63
	v_rcp_f32_e32 v50, v50
	v_add_f32_e32 v54, 1.0, v54
	v_rcp_f32_e32 v54, v54
	v_add_f32_e32 v55, 1.0, v55
	v_rcp_f32_e32 v55, v55
	v_mul_f32_e32 v50, v59, v50
	v_mul_f32_e32 v59, v50, v51
	v_mul_f32_e32 v50, v60, v54
	v_mul_f32_e32 v60, v50, v52
	v_mul_f32_e32 v50, v61, v55
	v_mul_f32_e32 v53, v50, v53
	v_lshl_add_u64 v[54:55], v[66:67], 0, v[114:115]
	v_cvt_pk_bf16_f32 v50, v62, v69
	v_cvt_pk_bf16_f32 v51, v56, v57
	v_cvt_pk_bf16_f32 v52, v58, v59
	v_cvt_pk_bf16_f32 v53, v60, v53
	global_store_dwordx4 v[54:55], v[50:53], off
	s_nop 1
	v_mul_f32_e32 v50, 0xbfb8aa3b, v46
	v_exp_f32_e32 v50, v50
	v_mul_f32_e32 v51, 0xbfb8aa3b, v47
	v_exp_f32_e32 v51, v51
	v_add_u32_e32 v52, 0x90, v139
	v_add_f32_e32 v50, 1.0, v50
	v_rcp_f32_e32 v53, v50
	v_add_f32_e32 v50, 1.0, v51
	v_rcp_f32_e32 v54, v50
	v_mad_i64_i32 v[50:51], s[6:7], v52, s74, v[134:135]
	v_mul_f32_e32 v46, v46, v53
	v_mul_f32_e32 v46, v46, v38
	v_mul_f32_e32 v38, v47, v54
	v_mul_f32_e32 v47, 0xbfb8aa3b, v48
	v_exp_f32_e32 v47, v47
	v_mul_f32_e32 v52, 0xbfb8aa3b, v49
	v_exp_f32_e32 v52, v52
	v_mul_f32_e32 v53, v38, v39
	v_add_f32_e32 v38, 1.0, v47
	v_rcp_f32_e32 v38, v38
	v_add_f32_e32 v39, 1.0, v52
	v_mul_f32_e32 v47, 0xbfb8aa3b, v42
	v_rcp_f32_e32 v39, v39
	v_exp_f32_e32 v47, v47
	v_mul_f32_e32 v38, v48, v38
	v_mul_f32_e32 v40, v38, v40
	v_mul_f32_e32 v38, v49, v39
	v_add_f32_e32 v39, 1.0, v47
	v_rcp_f32_e32 v39, v39
	v_mul_f32_e32 v47, 0xbfb8aa3b, v43
	v_mul_f32_e32 v41, v38, v41
	v_exp_f32_e32 v47, v47
	v_mul_f32_e32 v38, v42, v39
	v_mul_f32_e32 v42, v38, v34
	v_mul_f32_e32 v38, 0xbfb8aa3b, v44
	v_exp_f32_e32 v38, v38
	v_mul_f32_e32 v39, 0xbfb8aa3b, v45
	v_exp_f32_e32 v39, v39
	v_add_f32_e32 v34, 1.0, v47
	v_rcp_f32_e32 v34, v34
	v_add_f32_e32 v38, 1.0, v38
	v_rcp_f32_e32 v38, v38
	v_add_f32_e32 v39, 1.0, v39
	v_rcp_f32_e32 v39, v39
	v_mul_f32_e32 v34, v43, v34
	v_mul_f32_e32 v43, v34, v35
	v_mul_f32_e32 v34, v44, v38
	v_mul_f32_e32 v44, v34, v36
	v_mul_f32_e32 v34, v45, v39
	v_mul_f32_e32 v37, v34, v37
	v_lshl_add_u64 v[38:39], v[50:51], 0, v[114:115]
	v_cvt_pk_bf16_f32 v34, v46, v53
	v_cvt_pk_bf16_f32 v35, v40, v41
	v_cvt_pk_bf16_f32 v36, v42, v43
	v_cvt_pk_bf16_f32 v37, v44, v37
	global_store_dwordx4 v[38:39], v[34:37], off
	s_nop 1
	v_mul_f32_e32 v34, 0xbfb8aa3b, v30
	v_exp_f32_e32 v34, v34
	v_mul_f32_e32 v35, 0xbfb8aa3b, v31
	v_exp_f32_e32 v35, v35
	v_add_u32_e32 v36, 0xa0, v139
	v_add_f32_e32 v34, 1.0, v34
	v_rcp_f32_e32 v37, v34
	v_add_f32_e32 v34, 1.0, v35
	v_rcp_f32_e32 v38, v34
	v_mad_i64_i32 v[34:35], s[6:7], v36, s74, v[134:135]
	v_mul_f32_e32 v30, v30, v37
	v_mul_f32_e32 v30, v30, v22
	v_mul_f32_e32 v22, v31, v38
	v_mul_f32_e32 v31, 0xbfb8aa3b, v32
	v_exp_f32_e32 v31, v31
	v_mul_f32_e32 v36, 0xbfb8aa3b, v33
	v_exp_f32_e32 v36, v36
	v_mul_f32_e32 v37, v22, v23
	v_add_f32_e32 v22, 1.0, v31
	v_rcp_f32_e32 v22, v22
	v_add_f32_e32 v23, 1.0, v36
	v_mul_f32_e32 v31, 0xbfb8aa3b, v26
	v_rcp_f32_e32 v23, v23
	v_exp_f32_e32 v31, v31
	v_mul_f32_e32 v22, v32, v22
	v_mul_f32_e32 v24, v22, v24
	v_mul_f32_e32 v22, v33, v23
	v_add_f32_e32 v23, 1.0, v31
	v_rcp_f32_e32 v23, v23
	v_mul_f32_e32 v31, 0xbfb8aa3b, v27
	v_mul_f32_e32 v25, v22, v25
	v_exp_f32_e32 v31, v31
	v_mul_f32_e32 v22, v26, v23
	v_mul_f32_e32 v26, v22, v18
	v_mul_f32_e32 v22, 0xbfb8aa3b, v28
	v_exp_f32_e32 v22, v22
	v_mul_f32_e32 v23, 0xbfb8aa3b, v29
	v_exp_f32_e32 v23, v23
	v_add_f32_e32 v18, 1.0, v31
	v_rcp_f32_e32 v18, v18
	v_add_f32_e32 v22, 1.0, v22
	v_rcp_f32_e32 v22, v22
	v_add_f32_e32 v23, 1.0, v23
	v_rcp_f32_e32 v23, v23
	v_mul_f32_e32 v18, v27, v18
	v_mul_f32_e32 v27, v18, v19
	v_mul_f32_e32 v18, v28, v22
	v_mul_f32_e32 v28, v18, v20
	v_mul_f32_e32 v18, v29, v23
	v_mul_f32_e32 v21, v18, v21
	v_lshl_add_u64 v[22:23], v[34:35], 0, v[114:115]
	v_cvt_pk_bf16_f32 v18, v30, v37
	v_cvt_pk_bf16_f32 v19, v24, v25
	v_cvt_pk_bf16_f32 v20, v26, v27
	v_cvt_pk_bf16_f32 v21, v28, v21
	global_store_dwordx4 v[22:23], v[18:21], off
	s_nop 1
	v_mul_f32_e32 v18, 0xbfb8aa3b, v14
	v_exp_f32_e32 v18, v18
	v_mul_f32_e32 v19, 0xbfb8aa3b, v15
	v_exp_f32_e32 v19, v19
	v_add_u32_e32 v20, 0xb0, v139
	v_add_f32_e32 v18, 1.0, v18
	v_rcp_f32_e32 v21, v18
	v_add_f32_e32 v18, 1.0, v19
	v_rcp_f32_e32 v22, v18
	v_mad_i64_i32 v[18:19], s[6:7], v20, s74, v[134:135]
	v_mul_f32_e32 v14, v14, v21
	v_mul_f32_e32 v14, v14, v6
	v_mul_f32_e32 v6, v15, v22
	v_mul_f32_e32 v15, 0xbfb8aa3b, v16
	v_exp_f32_e32 v15, v15
	v_mul_f32_e32 v20, 0xbfb8aa3b, v17
	v_exp_f32_e32 v20, v20
	v_mul_f32_e32 v21, v6, v7
	v_add_f32_e32 v6, 1.0, v15
	v_rcp_f32_e32 v6, v6
	v_add_f32_e32 v7, 1.0, v20
	v_mul_f32_e32 v15, 0xbfb8aa3b, v10
	v_rcp_f32_e32 v7, v7
	v_exp_f32_e32 v15, v15
	v_mul_f32_e32 v6, v16, v6
	v_mul_f32_e32 v8, v6, v8
	v_mul_f32_e32 v6, v17, v7
	v_add_f32_e32 v7, 1.0, v15
	v_rcp_f32_e32 v7, v7
	v_mul_f32_e32 v15, 0xbfb8aa3b, v11
	v_mul_f32_e32 v9, v6, v9
	v_exp_f32_e32 v15, v15
	v_mul_f32_e32 v6, v10, v7
	v_mul_f32_e32 v10, v6, v2
	v_mul_f32_e32 v6, 0xbfb8aa3b, v12
	v_exp_f32_e32 v6, v6
	v_mul_f32_e32 v7, 0xbfb8aa3b, v13
	v_exp_f32_e32 v7, v7
	v_add_f32_e32 v2, 1.0, v15
	v_rcp_f32_e32 v2, v2
	v_add_f32_e32 v6, 1.0, v6
	v_rcp_f32_e32 v6, v6
	v_add_f32_e32 v7, 1.0, v7
	v_rcp_f32_e32 v7, v7
	v_mul_f32_e32 v2, v11, v2
	v_mul_f32_e32 v11, v2, v3
	v_mul_f32_e32 v2, v12, v6
	v_mul_f32_e32 v12, v2, v4
	v_mul_f32_e32 v2, v13, v7
	v_mul_f32_e32 v5, v2, v5
	v_lshl_add_u64 v[6:7], v[18:19], 0, v[114:115]
	s_mov_b64 s[6:7], s[44:45]
	v_cvt_pk_bf16_f32 v2, v14, v21
	v_cvt_pk_bf16_f32 v3, v8, v9
	v_cvt_pk_bf16_f32 v4, v10, v11
	v_cvt_pk_bf16_f32 v5, v12, v5
	global_store_dwordx4 v[6:7], v[2:5], off
	s_cbranch_vccz .LBB0_691
	s_waitcnt vmcnt(0)
	v_readlane_b32 s0, v255, 8
	v_readlane_b32 s62, v255, 10
	v_readlane_b32 s84, v255, 12
	v_readlane_b32 s44, v255, 26
	s_cmpk_gt_u32 s22, 0xff
	v_readlane_b32 s1, v255, 9
	s_mov_b64 s[58:59], s[92:93]
	v_readlane_b32 s63, v255, 11
	v_readlane_b32 s85, v255, 13
	v_readlane_b32 s45, v255, 27
	s_cbranch_scc1 .LBB0_698
	s_barrier
